# prep row phase: wave all-reduces via DPP adds + v_permlane16/32_swap instead of ds_bpermute round trips
# speedup vs baseline: 1.0060x; 1.0060x over previous
.LBB0_54:
	s_or_b64 exec, exec, s[0:1]
	s_movk_i32 s2, 0x4000
	v_cmp_gt_i32_e32 vcc, s2, v66
	v_mbcnt_lo_u32_b32 v1, -1, 0
	s_waitcnt lgkmcnt(0)
	s_barrier
	s_and_saveexec_b64 s[8:9], vcc
	s_cbranch_execz .LBB0_61
	v_mov_b32_e32 v250, v66
	v_mov_b32_e32 v251, v69
	v_lshlrev_b32_e32 v206, 4, v251
	v_add_u32_e32 v207, 0x1000, v206
	global_load_dwordx4 v[2:5], v206, s[14:15]
	global_load_dwordx4 v[6:9], v206, s[14:15] offset:1024
	global_load_dwordx4 v[10:13], v206, s[14:15] offset:2048
	global_load_dwordx4 v[14:17], v206, s[14:15] offset:3072
	global_load_dwordx4 v[18:21], v207, s[14:15]
	global_load_dwordx4 v[22:25], v207, s[14:15] offset:1024
	global_load_dwordx4 v[26:29], v207, s[14:15] offset:2048
	global_load_dwordx4 v[30:33], v207, s[14:15] offset:3072
	v_and_b32_e32 v222, 7, v251
	v_lshlrev_b32_e32 v222, 2, v222
	global_load_dword v196, v222, s[18:19]
	v_lshlrev_b32_e32 v193, 13, v250
	v_add_u32_e32 v193, v193, v206
	v_add_u32_e32 v193, 0x1000, v193
	v_lshlrev_b32_e32 v194, 12, v250
	v_lshl_add_u32 v194, v251, 3, v194
	v_lshlrev_b32_e32 v195, 2, v250
	v_lshl_add_u32 v195, v251, 15, v195
	v_add_u32_e32 v192, 16, v206
	v_xor_b32_e32 v186, 32, v251
	v_lshlrev_b32_e32 v186, 2, v186
	v_xor_b32_e32 v187, 16, v251
	v_lshlrev_b32_e32 v187, 2, v187
	v_xor_b32_e32 v188, 8, v251
	v_lshlrev_b32_e32 v188, 2, v188
	v_xor_b32_e32 v189, 4, v251
	v_lshlrev_b32_e32 v189, 2, v189
	v_xor_b32_e32 v190, 2, v251
	v_lshlrev_b32_e32 v190, 2, v190
	v_xor_b32_e32 v191, 1, v251
	v_lshlrev_b32_e32 v191, 2, v191
	v_mov_b32_e32 v241, 0x358637bd
	v_mov_b32_e32 v242, 0x3ecc95a3
	v_mov_b32_e32 v243, 0x7f800000
	v_mov_b32_e32 v244, 0x7fc00000
	v_mov_b32_e32 v245, 0xff800000
	s_mov_b32 s17, 0x800000
	s_mov_b32 s24, 0xbfb8aa3b
	s_mov_b32 s25, 0x3f2aaaab
	s_mov_b32 s28, 0x3f317218
	s_mov_b32 s29, 0x7f800000
	s_mov_b32 s30, 0x33800000
	s_mov_b32 s0, 0x1000000
	global_load_dwordx4 v[34:37], v193, s[12:13] offset:-4096 nt
	global_load_dwordx4 v[38:41], v193, s[12:13] offset:-3072 nt
	global_load_dwordx4 v[42:45], v193, s[12:13] offset:-2048 nt
	global_load_dwordx4 v[46:49], v193, s[12:13] offset:-1024 nt
	global_load_dwordx4 v[50:53], v193, s[12:13] offset:0 nt
	global_load_dwordx4 v[54:57], v193, s[12:13] offset:1024 nt
	global_load_dwordx4 v[58:61], v193, s[12:13] offset:2048 nt
	global_load_dwordx4 v[62:65], v193, s[12:13] offset:3072 nt
	v_add_u32_e32 v193, s0, v193
	global_load_dwordx4 v[66:69], v193, s[12:13] offset:-4096 nt
	global_load_dwordx4 v[70:73], v193, s[12:13] offset:-3072 nt
	global_load_dwordx4 v[74:77], v193, s[12:13] offset:-2048 nt
	global_load_dwordx4 v[78:81], v193, s[12:13] offset:-1024 nt
	global_load_dwordx4 v[82:85], v193, s[12:13] offset:0 nt
	global_load_dwordx4 v[86:89], v193, s[12:13] offset:1024 nt
	global_load_dwordx4 v[90:93], v193, s[12:13] offset:2048 nt
	global_load_dwordx4 v[94:97], v193, s[12:13] offset:3072 nt
	v_add_u32_e32 v193, s0, v193
	s_waitcnt vmcnt(8)
	v_pk_mul_f32 v[198:199], v[34:35], v[34:35]
	v_pk_mul_f32 v[200:201], v[36:37], v[36:37]
	v_pk_fma_f32 v[198:199], v[38:39], v[38:39], v[198:199]
	v_pk_fma_f32 v[200:201], v[40:41], v[40:41], v[200:201]
	v_pk_fma_f32 v[198:199], v[42:43], v[42:43], v[198:199]
	v_pk_fma_f32 v[200:201], v[44:45], v[44:45], v[200:201]
	v_pk_fma_f32 v[198:199], v[46:47], v[46:47], v[198:199]
	v_pk_fma_f32 v[200:201], v[48:49], v[48:49], v[200:201]
	v_pk_fma_f32 v[198:199], v[50:51], v[50:51], v[198:199]
	v_pk_fma_f32 v[200:201], v[52:53], v[52:53], v[200:201]
	v_pk_fma_f32 v[198:199], v[54:55], v[54:55], v[198:199]
	v_pk_fma_f32 v[200:201], v[56:57], v[56:57], v[200:201]
	v_pk_fma_f32 v[198:199], v[58:59], v[58:59], v[198:199]
	v_pk_fma_f32 v[200:201], v[60:61], v[60:61], v[200:201]
	v_pk_fma_f32 v[198:199], v[62:63], v[62:63], v[198:199]
	v_pk_fma_f32 v[200:201], v[64:65], v[64:65], v[200:201]
	v_pk_add_f32 v[198:199], v[198:199], v[200:201]
	v_add_f32_e32 v198, v198, v199
	s_nop 1
	v_add_f32_dpp v198, v198, v198 quad_perm:[1,0,3,2] row_mask:0xf bank_mask:0xf
	s_nop 1
	v_add_f32_dpp v198, v198, v198 quad_perm:[2,3,0,1] row_mask:0xf bank_mask:0xf
	s_nop 1
	v_add_f32_dpp v198, v198, v198 row_half_mirror row_mask:0xf bank_mask:0xf
	s_nop 1
	v_add_f32_dpp v198, v198, v198 row_mirror row_mask:0xf bank_mask:0xf
	v_mov_b32_e32 v199, v198
	s_nop 1
	v_permlane16_swap_b32 v199, v198
	v_add_f32_e32 v198, v198, v199
	v_mov_b32_e32 v199, v198
	s_nop 1
	v_permlane32_swap_b32 v199, v198
	v_add_f32_e32 v198, v198, v199
	ds_read_b128 v[130:133], v192
	ds_read_b128 v[134:137], v192 offset:1024
	ds_read_b128 v[138:141], v192 offset:2048
	ds_read_b128 v[142:145], v192 offset:3072
	ds_read_b128 v[146:149], v192 offset:4096
	ds_read_b128 v[150:153], v192 offset:5120
	ds_read_b128 v[154:157], v192 offset:6144
	ds_read_b128 v[158:161], v192 offset:7168
	v_fmamk_f32 v198, v198, 0x3a000000, v241
	v_mul_f32_e32 v199, 0x4b800000, v198
	v_cmp_gt_f32_e32 vcc, s17, v198
	s_nop 1
	v_cndmask_b32_e32 v198, v198, v199, vcc
	v_rsq_f32_e32 v198, v198
	s_nop 0
	v_mul_f32_e32 v199, 0x45800000, v198
	v_cndmask_b32_e32 v202, v198, v199, vcc
	v_pk_mul_f32 v[98:99], v[34:35], v[202:203] op_sel_hi:[1,0]
	v_pk_mul_f32 v[98:99], v[2:3], v[98:99]
	v_pk_mul_f32 v[100:101], v[36:37], v[202:203] op_sel_hi:[1,0]
	v_pk_mul_f32 v[100:101], v[4:5], v[100:101]
	v_cvt_pk_bf16_f32 v206, v98, v99
	v_cvt_pk_bf16_f32 v207, v100, v101
	global_store_dwordx2 v194, v[206:207], s[52:53]
	v_pk_mul_f32 v[102:103], v[38:39], v[202:203] op_sel_hi:[1,0]
	v_pk_mul_f32 v[102:103], v[6:7], v[102:103]
	v_pk_mul_f32 v[104:105], v[40:41], v[202:203] op_sel_hi:[1,0]
	v_pk_mul_f32 v[104:105], v[8:9], v[104:105]
	v_cvt_pk_bf16_f32 v206, v102, v103
	v_cvt_pk_bf16_f32 v207, v104, v105
	global_store_dwordx2 v194, v[206:207], s[52:53] offset:512
	v_pk_mul_f32 v[106:107], v[42:43], v[202:203] op_sel_hi:[1,0]
	v_pk_mul_f32 v[106:107], v[10:11], v[106:107]
	v_pk_mul_f32 v[108:109], v[44:45], v[202:203] op_sel_hi:[1,0]
	v_pk_mul_f32 v[108:109], v[12:13], v[108:109]
	v_cvt_pk_bf16_f32 v206, v106, v107
	v_cvt_pk_bf16_f32 v207, v108, v109
	global_store_dwordx2 v194, v[206:207], s[52:53] offset:1024
	v_pk_mul_f32 v[110:111], v[46:47], v[202:203] op_sel_hi:[1,0]
	v_pk_mul_f32 v[110:111], v[14:15], v[110:111]
	v_pk_mul_f32 v[112:113], v[48:49], v[202:203] op_sel_hi:[1,0]
	v_pk_mul_f32 v[112:113], v[16:17], v[112:113]
	v_cvt_pk_bf16_f32 v206, v110, v111
	v_cvt_pk_bf16_f32 v207, v112, v113
	global_store_dwordx2 v194, v[206:207], s[52:53] offset:1536
	v_pk_mul_f32 v[114:115], v[50:51], v[202:203] op_sel_hi:[1,0]
	v_pk_mul_f32 v[114:115], v[18:19], v[114:115]
	v_pk_mul_f32 v[116:117], v[52:53], v[202:203] op_sel_hi:[1,0]
	v_pk_mul_f32 v[116:117], v[20:21], v[116:117]
	v_cvt_pk_bf16_f32 v206, v114, v115
	v_cvt_pk_bf16_f32 v207, v116, v117
	global_store_dwordx2 v194, v[206:207], s[52:53] offset:2048
	v_pk_mul_f32 v[118:119], v[54:55], v[202:203] op_sel_hi:[1,0]
	v_pk_mul_f32 v[118:119], v[22:23], v[118:119]
	v_pk_mul_f32 v[120:121], v[56:57], v[202:203] op_sel_hi:[1,0]
	v_pk_mul_f32 v[120:121], v[24:25], v[120:121]
	v_cvt_pk_bf16_f32 v206, v118, v119
	v_cvt_pk_bf16_f32 v207, v120, v121
	global_store_dwordx2 v194, v[206:207], s[52:53] offset:2560
	v_pk_mul_f32 v[122:123], v[58:59], v[202:203] op_sel_hi:[1,0]
	v_pk_mul_f32 v[122:123], v[26:27], v[122:123]
	v_pk_mul_f32 v[124:125], v[60:61], v[202:203] op_sel_hi:[1,0]
	v_pk_mul_f32 v[124:125], v[28:29], v[124:125]
	v_cvt_pk_bf16_f32 v206, v122, v123
	v_cvt_pk_bf16_f32 v207, v124, v125
	global_store_dwordx2 v194, v[206:207], s[52:53] offset:3072
	v_pk_mul_f32 v[126:127], v[62:63], v[202:203] op_sel_hi:[1,0]
	v_pk_mul_f32 v[126:127], v[30:31], v[126:127]
	v_pk_mul_f32 v[128:129], v[64:65], v[202:203] op_sel_hi:[1,0]
	v_pk_mul_f32 v[128:129], v[32:33], v[128:129]
	v_cvt_pk_bf16_f32 v206, v126, v127
	v_cvt_pk_bf16_f32 v207, v128, v129
	global_store_dwordx2 v194, v[206:207], s[52:53] offset:3584
	v_add_u32_e32 v194, 0x800000, v194
	global_load_dwordx4 v[34:37], v193, s[12:13] offset:-4096 nt
	global_load_dwordx4 v[38:41], v193, s[12:13] offset:-3072 nt
	global_load_dwordx4 v[42:45], v193, s[12:13] offset:-2048 nt
	global_load_dwordx4 v[46:49], v193, s[12:13] offset:-1024 nt
	global_load_dwordx4 v[50:53], v193, s[12:13] offset:0 nt
	global_load_dwordx4 v[54:57], v193, s[12:13] offset:1024 nt
	global_load_dwordx4 v[58:61], v193, s[12:13] offset:2048 nt
	global_load_dwordx4 v[62:65], v193, s[12:13] offset:3072 nt
	v_add_u32_e32 v193, s0, v193
	s_waitcnt lgkmcnt(6)
	v_pk_mul_f32 v[162:163], v[130:131], v[98:99] op_sel_hi:[1,0]
	v_pk_mul_f32 v[164:165], v[132:133], v[98:99] op_sel_hi:[1,0]
	v_pk_mul_f32 v[166:167], v[134:135], v[98:99] op_sel_hi:[1,0]
	v_pk_mul_f32 v[168:169], v[136:137], v[98:99] op_sel_hi:[1,0]
	ds_read_b128 v[130:133], v192 offset:8192
	ds_read_b128 v[134:137], v192 offset:9216
	s_waitcnt lgkmcnt(6)
	v_pk_fma_f32 v[162:163], v[138:139], v[98:99], v[162:163] op_sel:[0,1,0] op_sel_hi:[1,1,1]
	v_pk_fma_f32 v[164:165], v[140:141], v[98:99], v[164:165] op_sel:[0,1,0] op_sel_hi:[1,1,1]
	v_pk_fma_f32 v[166:167], v[142:143], v[98:99], v[166:167] op_sel:[0,1,0] op_sel_hi:[1,1,1]
	v_pk_fma_f32 v[168:169], v[144:145], v[98:99], v[168:169] op_sel:[0,1,0] op_sel_hi:[1,1,1]
	ds_read_b128 v[138:141], v192 offset:10240
	ds_read_b128 v[142:145], v192 offset:11264
	s_waitcnt lgkmcnt(6)
	v_pk_fma_f32 v[162:163], v[146:147], v[100:101], v[162:163] op_sel_hi:[1,0,1]
	v_pk_fma_f32 v[164:165], v[148:149], v[100:101], v[164:165] op_sel_hi:[1,0,1]
	v_pk_fma_f32 v[166:167], v[150:151], v[100:101], v[166:167] op_sel_hi:[1,0,1]
	v_pk_fma_f32 v[168:169], v[152:153], v[100:101], v[168:169] op_sel_hi:[1,0,1]
	ds_read_b128 v[146:149], v192 offset:12288
	ds_read_b128 v[150:153], v192 offset:13312
	s_waitcnt lgkmcnt(6)
	v_pk_fma_f32 v[162:163], v[154:155], v[100:101], v[162:163] op_sel:[0,1,0] op_sel_hi:[1,1,1]
	v_pk_fma_f32 v[164:165], v[156:157], v[100:101], v[164:165] op_sel:[0,1,0] op_sel_hi:[1,1,1]
	v_pk_fma_f32 v[166:167], v[158:159], v[100:101], v[166:167] op_sel:[0,1,0] op_sel_hi:[1,1,1]
	v_pk_fma_f32 v[168:169], v[160:161], v[100:101], v[168:169] op_sel:[0,1,0] op_sel_hi:[1,1,1]
	ds_read_b128 v[154:157], v192 offset:14336
	ds_read_b128 v[158:161], v192 offset:15360
	s_waitcnt lgkmcnt(6)
	v_pk_fma_f32 v[162:163], v[130:131], v[102:103], v[162:163] op_sel_hi:[1,0,1]
	v_pk_fma_f32 v[164:165], v[132:133], v[102:103], v[164:165] op_sel_hi:[1,0,1]
	v_pk_fma_f32 v[166:167], v[134:135], v[102:103], v[166:167] op_sel_hi:[1,0,1]
	v_pk_fma_f32 v[168:169], v[136:137], v[102:103], v[168:169] op_sel_hi:[1,0,1]
	ds_read_b128 v[130:133], v192 offset:16384
	ds_read_b128 v[134:137], v192 offset:17408
	s_waitcnt lgkmcnt(6)
	v_pk_fma_f32 v[162:163], v[138:139], v[102:103], v[162:163] op_sel:[0,1,0] op_sel_hi:[1,1,1]
	v_pk_fma_f32 v[164:165], v[140:141], v[102:103], v[164:165] op_sel:[0,1,0] op_sel_hi:[1,1,1]
	v_pk_fma_f32 v[166:167], v[142:143], v[102:103], v[166:167] op_sel:[0,1,0] op_sel_hi:[1,1,1]
	v_pk_fma_f32 v[168:169], v[144:145], v[102:103], v[168:169] op_sel:[0,1,0] op_sel_hi:[1,1,1]
	ds_read_b128 v[138:141], v192 offset:18432
	ds_read_b128 v[142:145], v192 offset:19456
	s_waitcnt lgkmcnt(6)
	v_pk_fma_f32 v[162:163], v[146:147], v[104:105], v[162:163] op_sel_hi:[1,0,1]
	v_pk_fma_f32 v[164:165], v[148:149], v[104:105], v[164:165] op_sel_hi:[1,0,1]
	v_pk_fma_f32 v[166:167], v[150:151], v[104:105], v[166:167] op_sel_hi:[1,0,1]
	v_pk_fma_f32 v[168:169], v[152:153], v[104:105], v[168:169] op_sel_hi:[1,0,1]
	ds_read_b128 v[146:149], v192 offset:20480
	ds_read_b128 v[150:153], v192 offset:21504
	s_waitcnt lgkmcnt(6)
	v_pk_fma_f32 v[162:163], v[154:155], v[104:105], v[162:163] op_sel:[0,1,0] op_sel_hi:[1,1,1]
	v_pk_fma_f32 v[164:165], v[156:157], v[104:105], v[164:165] op_sel:[0,1,0] op_sel_hi:[1,1,1]
	v_pk_fma_f32 v[166:167], v[158:159], v[104:105], v[166:167] op_sel:[0,1,0] op_sel_hi:[1,1,1]
	v_pk_fma_f32 v[168:169], v[160:161], v[104:105], v[168:169] op_sel:[0,1,0] op_sel_hi:[1,1,1]
	ds_read_b128 v[154:157], v192 offset:22528
	ds_read_b128 v[158:161], v192 offset:23552
	s_waitcnt lgkmcnt(6)
	v_pk_fma_f32 v[162:163], v[130:131], v[106:107], v[162:163] op_sel_hi:[1,0,1]
	v_pk_fma_f32 v[164:165], v[132:133], v[106:107], v[164:165] op_sel_hi:[1,0,1]
	v_pk_fma_f32 v[166:167], v[134:135], v[106:107], v[166:167] op_sel_hi:[1,0,1]
	v_pk_fma_f32 v[168:169], v[136:137], v[106:107], v[168:169] op_sel_hi:[1,0,1]
	ds_read_b128 v[130:133], v192 offset:24576
	ds_read_b128 v[134:137], v192 offset:25600
	s_waitcnt lgkmcnt(6)
	v_pk_fma_f32 v[162:163], v[138:139], v[106:107], v[162:163] op_sel:[0,1,0] op_sel_hi:[1,1,1]
	v_pk_fma_f32 v[164:165], v[140:141], v[106:107], v[164:165] op_sel:[0,1,0] op_sel_hi:[1,1,1]
	v_pk_fma_f32 v[166:167], v[142:143], v[106:107], v[166:167] op_sel:[0,1,0] op_sel_hi:[1,1,1]
	v_pk_fma_f32 v[168:169], v[144:145], v[106:107], v[168:169] op_sel:[0,1,0] op_sel_hi:[1,1,1]
	ds_read_b128 v[138:141], v192 offset:26624
	ds_read_b128 v[142:145], v192 offset:27648
	s_waitcnt lgkmcnt(6)
	v_pk_fma_f32 v[162:163], v[146:147], v[108:109], v[162:163] op_sel_hi:[1,0,1]
	v_pk_fma_f32 v[164:165], v[148:149], v[108:109], v[164:165] op_sel_hi:[1,0,1]
	v_pk_fma_f32 v[166:167], v[150:151], v[108:109], v[166:167] op_sel_hi:[1,0,1]
	v_pk_fma_f32 v[168:169], v[152:153], v[108:109], v[168:169] op_sel_hi:[1,0,1]
	ds_read_b128 v[146:149], v192 offset:28672
	ds_read_b128 v[150:153], v192 offset:29696
	s_waitcnt lgkmcnt(6)
	v_pk_fma_f32 v[162:163], v[154:155], v[108:109], v[162:163] op_sel:[0,1,0] op_sel_hi:[1,1,1]
	v_pk_fma_f32 v[164:165], v[156:157], v[108:109], v[164:165] op_sel:[0,1,0] op_sel_hi:[1,1,1]
	v_pk_fma_f32 v[166:167], v[158:159], v[108:109], v[166:167] op_sel:[0,1,0] op_sel_hi:[1,1,1]
	v_pk_fma_f32 v[168:169], v[160:161], v[108:109], v[168:169] op_sel:[0,1,0] op_sel_hi:[1,1,1]
	ds_read_b128 v[154:157], v192 offset:30720
	ds_read_b128 v[158:161], v192 offset:31744
	s_waitcnt lgkmcnt(6)
	v_pk_fma_f32 v[162:163], v[130:131], v[110:111], v[162:163] op_sel_hi:[1,0,1]
	v_pk_fma_f32 v[164:165], v[132:133], v[110:111], v[164:165] op_sel_hi:[1,0,1]
	v_pk_fma_f32 v[166:167], v[134:135], v[110:111], v[166:167] op_sel_hi:[1,0,1]
	v_pk_fma_f32 v[168:169], v[136:137], v[110:111], v[168:169] op_sel_hi:[1,0,1]
	ds_read_b128 v[130:133], v192 offset:32768
	ds_read_b128 v[134:137], v192 offset:33792
	s_waitcnt lgkmcnt(6)
	v_pk_fma_f32 v[162:163], v[138:139], v[110:111], v[162:163] op_sel:[0,1,0] op_sel_hi:[1,1,1]
	v_pk_fma_f32 v[164:165], v[140:141], v[110:111], v[164:165] op_sel:[0,1,0] op_sel_hi:[1,1,1]
	v_pk_fma_f32 v[166:167], v[142:143], v[110:111], v[166:167] op_sel:[0,1,0] op_sel_hi:[1,1,1]
	v_pk_fma_f32 v[168:169], v[144:145], v[110:111], v[168:169] op_sel:[0,1,0] op_sel_hi:[1,1,1]
	ds_read_b128 v[138:141], v192 offset:34816
	ds_read_b128 v[142:145], v192 offset:35840
	s_waitcnt lgkmcnt(6)
	v_pk_fma_f32 v[162:163], v[146:147], v[112:113], v[162:163] op_sel_hi:[1,0,1]
	v_pk_fma_f32 v[164:165], v[148:149], v[112:113], v[164:165] op_sel_hi:[1,0,1]
	v_pk_fma_f32 v[166:167], v[150:151], v[112:113], v[166:167] op_sel_hi:[1,0,1]
	v_pk_fma_f32 v[168:169], v[152:153], v[112:113], v[168:169] op_sel_hi:[1,0,1]
	ds_read_b128 v[146:149], v192 offset:36864
	ds_read_b128 v[150:153], v192 offset:37888
	s_waitcnt lgkmcnt(6)
	v_pk_fma_f32 v[162:163], v[154:155], v[112:113], v[162:163] op_sel:[0,1,0] op_sel_hi:[1,1,1]
	v_pk_fma_f32 v[164:165], v[156:157], v[112:113], v[164:165] op_sel:[0,1,0] op_sel_hi:[1,1,1]
	v_pk_fma_f32 v[166:167], v[158:159], v[112:113], v[166:167] op_sel:[0,1,0] op_sel_hi:[1,1,1]
	v_pk_fma_f32 v[168:169], v[160:161], v[112:113], v[168:169] op_sel:[0,1,0] op_sel_hi:[1,1,1]
	ds_read_b128 v[154:157], v192 offset:38912
	ds_read_b128 v[158:161], v192 offset:39936
	s_waitcnt lgkmcnt(6)
	v_pk_fma_f32 v[162:163], v[130:131], v[114:115], v[162:163] op_sel_hi:[1,0,1]
	v_pk_fma_f32 v[164:165], v[132:133], v[114:115], v[164:165] op_sel_hi:[1,0,1]
	v_pk_fma_f32 v[166:167], v[134:135], v[114:115], v[166:167] op_sel_hi:[1,0,1]
	v_pk_fma_f32 v[168:169], v[136:137], v[114:115], v[168:169] op_sel_hi:[1,0,1]
	ds_read_b128 v[130:133], v192 offset:40960
	ds_read_b128 v[134:137], v192 offset:41984
	s_waitcnt lgkmcnt(6)
	v_pk_fma_f32 v[162:163], v[138:139], v[114:115], v[162:163] op_sel:[0,1,0] op_sel_hi:[1,1,1]
	v_pk_fma_f32 v[164:165], v[140:141], v[114:115], v[164:165] op_sel:[0,1,0] op_sel_hi:[1,1,1]
	v_pk_fma_f32 v[166:167], v[142:143], v[114:115], v[166:167] op_sel:[0,1,0] op_sel_hi:[1,1,1]
	v_pk_fma_f32 v[168:169], v[144:145], v[114:115], v[168:169] op_sel:[0,1,0] op_sel_hi:[1,1,1]
	ds_read_b128 v[138:141], v192 offset:43008
	ds_read_b128 v[142:145], v192 offset:44032
	s_waitcnt lgkmcnt(6)
	v_pk_fma_f32 v[162:163], v[146:147], v[116:117], v[162:163] op_sel_hi:[1,0,1]
	v_pk_fma_f32 v[164:165], v[148:149], v[116:117], v[164:165] op_sel_hi:[1,0,1]
	v_pk_fma_f32 v[166:167], v[150:151], v[116:117], v[166:167] op_sel_hi:[1,0,1]
	v_pk_fma_f32 v[168:169], v[152:153], v[116:117], v[168:169] op_sel_hi:[1,0,1]
	ds_read_b128 v[146:149], v192 offset:45056
	ds_read_b128 v[150:153], v192 offset:46080
	s_waitcnt lgkmcnt(6)
	v_pk_fma_f32 v[162:163], v[154:155], v[116:117], v[162:163] op_sel:[0,1,0] op_sel_hi:[1,1,1]
	v_pk_fma_f32 v[164:165], v[156:157], v[116:117], v[164:165] op_sel:[0,1,0] op_sel_hi:[1,1,1]
	v_pk_fma_f32 v[166:167], v[158:159], v[116:117], v[166:167] op_sel:[0,1,0] op_sel_hi:[1,1,1]
	v_pk_fma_f32 v[168:169], v[160:161], v[116:117], v[168:169] op_sel:[0,1,0] op_sel_hi:[1,1,1]
	ds_read_b128 v[154:157], v192 offset:47104
	ds_read_b128 v[158:161], v192 offset:48128
	s_waitcnt lgkmcnt(6)
	v_pk_fma_f32 v[162:163], v[130:131], v[118:119], v[162:163] op_sel_hi:[1,0,1]
	v_pk_fma_f32 v[164:165], v[132:133], v[118:119], v[164:165] op_sel_hi:[1,0,1]
	v_pk_fma_f32 v[166:167], v[134:135], v[118:119], v[166:167] op_sel_hi:[1,0,1]
	v_pk_fma_f32 v[168:169], v[136:137], v[118:119], v[168:169] op_sel_hi:[1,0,1]
	ds_read_b128 v[130:133], v192 offset:49152
	ds_read_b128 v[134:137], v192 offset:50176
	s_waitcnt lgkmcnt(6)
	v_pk_fma_f32 v[162:163], v[138:139], v[118:119], v[162:163] op_sel:[0,1,0] op_sel_hi:[1,1,1]
	v_pk_fma_f32 v[164:165], v[140:141], v[118:119], v[164:165] op_sel:[0,1,0] op_sel_hi:[1,1,1]
	v_pk_fma_f32 v[166:167], v[142:143], v[118:119], v[166:167] op_sel:[0,1,0] op_sel_hi:[1,1,1]
	v_pk_fma_f32 v[168:169], v[144:145], v[118:119], v[168:169] op_sel:[0,1,0] op_sel_hi:[1,1,1]
	ds_read_b128 v[138:141], v192 offset:51200
	ds_read_b128 v[142:145], v192 offset:52224
	s_waitcnt lgkmcnt(6)
	v_pk_fma_f32 v[162:163], v[146:147], v[120:121], v[162:163] op_sel_hi:[1,0,1]
	v_pk_fma_f32 v[164:165], v[148:149], v[120:121], v[164:165] op_sel_hi:[1,0,1]
	v_pk_fma_f32 v[166:167], v[150:151], v[120:121], v[166:167] op_sel_hi:[1,0,1]
	v_pk_fma_f32 v[168:169], v[152:153], v[120:121], v[168:169] op_sel_hi:[1,0,1]
	ds_read_b128 v[146:149], v192 offset:53248
	ds_read_b128 v[150:153], v192 offset:54272
	s_waitcnt lgkmcnt(6)
	v_pk_fma_f32 v[162:163], v[154:155], v[120:121], v[162:163] op_sel:[0,1,0] op_sel_hi:[1,1,1]
	v_pk_fma_f32 v[164:165], v[156:157], v[120:121], v[164:165] op_sel:[0,1,0] op_sel_hi:[1,1,1]
	v_pk_fma_f32 v[166:167], v[158:159], v[120:121], v[166:167] op_sel:[0,1,0] op_sel_hi:[1,1,1]
	v_pk_fma_f32 v[168:169], v[160:161], v[120:121], v[168:169] op_sel:[0,1,0] op_sel_hi:[1,1,1]
	ds_read_b128 v[154:157], v192 offset:55296
	ds_read_b128 v[158:161], v192 offset:56320
	s_waitcnt lgkmcnt(6)
	v_pk_fma_f32 v[162:163], v[130:131], v[122:123], v[162:163] op_sel_hi:[1,0,1]
	v_pk_fma_f32 v[164:165], v[132:133], v[122:123], v[164:165] op_sel_hi:[1,0,1]
	v_pk_fma_f32 v[166:167], v[134:135], v[122:123], v[166:167] op_sel_hi:[1,0,1]
	v_pk_fma_f32 v[168:169], v[136:137], v[122:123], v[168:169] op_sel_hi:[1,0,1]
	ds_read_b128 v[130:133], v192 offset:57344
	ds_read_b128 v[134:137], v192 offset:58368
	s_waitcnt lgkmcnt(6)
	v_pk_fma_f32 v[162:163], v[138:139], v[122:123], v[162:163] op_sel:[0,1,0] op_sel_hi:[1,1,1]
	v_pk_fma_f32 v[164:165], v[140:141], v[122:123], v[164:165] op_sel:[0,1,0] op_sel_hi:[1,1,1]
	v_pk_fma_f32 v[166:167], v[142:143], v[122:123], v[166:167] op_sel:[0,1,0] op_sel_hi:[1,1,1]
	v_pk_fma_f32 v[168:169], v[144:145], v[122:123], v[168:169] op_sel:[0,1,0] op_sel_hi:[1,1,1]
	ds_read_b128 v[138:141], v192 offset:59392
	ds_read_b128 v[142:145], v192 offset:60416
	s_waitcnt lgkmcnt(6)
	v_pk_fma_f32 v[162:163], v[146:147], v[124:125], v[162:163] op_sel_hi:[1,0,1]
	v_pk_fma_f32 v[164:165], v[148:149], v[124:125], v[164:165] op_sel_hi:[1,0,1]
	v_pk_fma_f32 v[166:167], v[150:151], v[124:125], v[166:167] op_sel_hi:[1,0,1]
	v_pk_fma_f32 v[168:169], v[152:153], v[124:125], v[168:169] op_sel_hi:[1,0,1]
	ds_read_b128 v[146:149], v192 offset:61440
	ds_read_b128 v[150:153], v192 offset:62464
	s_waitcnt lgkmcnt(6)
	v_pk_fma_f32 v[162:163], v[154:155], v[124:125], v[162:163] op_sel:[0,1,0] op_sel_hi:[1,1,1]
	v_pk_fma_f32 v[164:165], v[156:157], v[124:125], v[164:165] op_sel:[0,1,0] op_sel_hi:[1,1,1]
	v_pk_fma_f32 v[166:167], v[158:159], v[124:125], v[166:167] op_sel:[0,1,0] op_sel_hi:[1,1,1]
	v_pk_fma_f32 v[168:169], v[160:161], v[124:125], v[168:169] op_sel:[0,1,0] op_sel_hi:[1,1,1]
	ds_read_b128 v[154:157], v192 offset:63488
	ds_read_b128 v[158:161], v192 offset:64512
	s_waitcnt lgkmcnt(6)
	v_pk_fma_f32 v[162:163], v[130:131], v[126:127], v[162:163] op_sel_hi:[1,0,1]
	v_pk_fma_f32 v[164:165], v[132:133], v[126:127], v[164:165] op_sel_hi:[1,0,1]
	v_pk_fma_f32 v[166:167], v[134:135], v[126:127], v[166:167] op_sel_hi:[1,0,1]
	v_pk_fma_f32 v[168:169], v[136:137], v[126:127], v[168:169] op_sel_hi:[1,0,1]
	s_waitcnt lgkmcnt(4)
	v_pk_fma_f32 v[162:163], v[138:139], v[126:127], v[162:163] op_sel:[0,1,0] op_sel_hi:[1,1,1]
	v_pk_fma_f32 v[164:165], v[140:141], v[126:127], v[164:165] op_sel:[0,1,0] op_sel_hi:[1,1,1]
	v_pk_fma_f32 v[166:167], v[142:143], v[126:127], v[166:167] op_sel:[0,1,0] op_sel_hi:[1,1,1]
	v_pk_fma_f32 v[168:169], v[144:145], v[126:127], v[168:169] op_sel:[0,1,0] op_sel_hi:[1,1,1]
	s_waitcnt lgkmcnt(2)
	v_pk_fma_f32 v[162:163], v[146:147], v[128:129], v[162:163] op_sel_hi:[1,0,1]
	v_pk_fma_f32 v[164:165], v[148:149], v[128:129], v[164:165] op_sel_hi:[1,0,1]
	v_pk_fma_f32 v[166:167], v[150:151], v[128:129], v[166:167] op_sel_hi:[1,0,1]
	v_pk_fma_f32 v[168:169], v[152:153], v[128:129], v[168:169] op_sel_hi:[1,0,1]
	s_waitcnt lgkmcnt(0)
	v_pk_fma_f32 v[162:163], v[154:155], v[128:129], v[162:163] op_sel:[0,1,0] op_sel_hi:[1,1,1]
	v_pk_fma_f32 v[164:165], v[156:157], v[128:129], v[164:165] op_sel:[0,1,0] op_sel_hi:[1,1,1]
	v_pk_fma_f32 v[166:167], v[158:159], v[128:129], v[166:167] op_sel:[0,1,0] op_sel_hi:[1,1,1]
	v_pk_fma_f32 v[168:169], v[160:161], v[128:129], v[168:169] op_sel:[0,1,0] op_sel_hi:[1,1,1]
	s_nop 1
	v_add_f32_dpp v162, v162, v162 quad_perm:[1,0,3,2] row_mask:0xf bank_mask:0xf
	v_add_f32_dpp v163, v163, v163 quad_perm:[1,0,3,2] row_mask:0xf bank_mask:0xf
	v_add_f32_dpp v164, v164, v164 quad_perm:[1,0,3,2] row_mask:0xf bank_mask:0xf
	v_add_f32_dpp v165, v165, v165 quad_perm:[1,0,3,2] row_mask:0xf bank_mask:0xf
	v_add_f32_dpp v166, v166, v166 quad_perm:[1,0,3,2] row_mask:0xf bank_mask:0xf
	v_add_f32_dpp v167, v167, v167 quad_perm:[1,0,3,2] row_mask:0xf bank_mask:0xf
	v_add_f32_dpp v168, v168, v168 quad_perm:[1,0,3,2] row_mask:0xf bank_mask:0xf
	v_add_f32_dpp v169, v169, v169 quad_perm:[1,0,3,2] row_mask:0xf bank_mask:0xf
	v_add_f32_dpp v162, v162, v162 quad_perm:[2,3,0,1] row_mask:0xf bank_mask:0xf
	v_add_f32_dpp v163, v163, v163 quad_perm:[2,3,0,1] row_mask:0xf bank_mask:0xf
	v_add_f32_dpp v164, v164, v164 quad_perm:[2,3,0,1] row_mask:0xf bank_mask:0xf
	v_add_f32_dpp v165, v165, v165 quad_perm:[2,3,0,1] row_mask:0xf bank_mask:0xf
	v_add_f32_dpp v166, v166, v166 quad_perm:[2,3,0,1] row_mask:0xf bank_mask:0xf
	v_add_f32_dpp v167, v167, v167 quad_perm:[2,3,0,1] row_mask:0xf bank_mask:0xf
	v_add_f32_dpp v168, v168, v168 quad_perm:[2,3,0,1] row_mask:0xf bank_mask:0xf
	v_add_f32_dpp v169, v169, v169 quad_perm:[2,3,0,1] row_mask:0xf bank_mask:0xf
	v_add_f32_dpp v162, v162, v162 row_half_mirror row_mask:0xf bank_mask:0xf
	v_add_f32_dpp v163, v163, v163 row_half_mirror row_mask:0xf bank_mask:0xf
	v_add_f32_dpp v164, v164, v164 row_half_mirror row_mask:0xf bank_mask:0xf
	v_add_f32_dpp v165, v165, v165 row_half_mirror row_mask:0xf bank_mask:0xf
	v_add_f32_dpp v166, v166, v166 row_half_mirror row_mask:0xf bank_mask:0xf
	v_add_f32_dpp v167, v167, v167 row_half_mirror row_mask:0xf bank_mask:0xf
	v_add_f32_dpp v168, v168, v168 row_half_mirror row_mask:0xf bank_mask:0xf
	v_add_f32_dpp v169, v169, v169 row_half_mirror row_mask:0xf bank_mask:0xf
	v_add_f32_dpp v162, v162, v162 row_mirror row_mask:0xf bank_mask:0xf
	v_add_f32_dpp v163, v163, v163 row_mirror row_mask:0xf bank_mask:0xf
	v_add_f32_dpp v164, v164, v164 row_mirror row_mask:0xf bank_mask:0xf
	v_add_f32_dpp v165, v165, v165 row_mirror row_mask:0xf bank_mask:0xf
	v_add_f32_dpp v166, v166, v166 row_mirror row_mask:0xf bank_mask:0xf
	v_add_f32_dpp v167, v167, v167 row_mirror row_mask:0xf bank_mask:0xf
	v_add_f32_dpp v168, v168, v168 row_mirror row_mask:0xf bank_mask:0xf
	v_add_f32_dpp v169, v169, v169 row_mirror row_mask:0xf bank_mask:0xf
	v_mov_b32_e32 v170, v162
	v_mov_b32_e32 v171, v163
	v_mov_b32_e32 v172, v164
	v_mov_b32_e32 v173, v165
	v_mov_b32_e32 v174, v166
	v_mov_b32_e32 v175, v167
	v_mov_b32_e32 v176, v168
	v_mov_b32_e32 v177, v169
	v_permlane16_swap_b32 v170, v162
	v_permlane16_swap_b32 v171, v163
	v_permlane16_swap_b32 v172, v164
	v_permlane16_swap_b32 v173, v165
	v_permlane16_swap_b32 v174, v166
	v_permlane16_swap_b32 v175, v167
	v_permlane16_swap_b32 v176, v168
	v_permlane16_swap_b32 v177, v169
	v_add_f32_e32 v162, v162, v170
	v_add_f32_e32 v163, v163, v171
	v_add_f32_e32 v164, v164, v172
	v_add_f32_e32 v165, v165, v173
	v_add_f32_e32 v166, v166, v174
	v_add_f32_e32 v167, v167, v175
	v_add_f32_e32 v168, v168, v176
	v_add_f32_e32 v169, v169, v177
	v_mov_b32_e32 v170, v162
	v_mov_b32_e32 v171, v163
	v_mov_b32_e32 v172, v164
	v_mov_b32_e32 v173, v165
	v_mov_b32_e32 v174, v166
	v_mov_b32_e32 v175, v167
	v_mov_b32_e32 v176, v168
	v_mov_b32_e32 v177, v169
	v_permlane32_swap_b32 v170, v162
	v_permlane32_swap_b32 v171, v163
	v_permlane32_swap_b32 v172, v164
	v_permlane32_swap_b32 v173, v165
	v_permlane32_swap_b32 v174, v166
	v_permlane32_swap_b32 v175, v167
	v_permlane32_swap_b32 v176, v168
	v_permlane32_swap_b32 v177, v169
	v_add_f32_e32 v162, v162, v170
	v_add_f32_e32 v163, v163, v171
	v_add_f32_e32 v164, v164, v172
	v_add_f32_e32 v165, v165, v173
	v_add_f32_e32 v166, v166, v174
	v_add_f32_e32 v167, v167, v175
	v_add_f32_e32 v168, v168, v176
	v_add_f32_e32 v169, v169, v177
	s_mov_b64 exec, 1
	v_mov_b32_e32 v222, v162
	s_mov_b64 exec, 2
	v_mov_b32_e32 v222, v163
	s_mov_b64 exec, 4
	v_mov_b32_e32 v222, v164
	s_mov_b64 exec, 8
	v_mov_b32_e32 v222, v165
	s_mov_b64 exec, 16
	v_mov_b32_e32 v222, v166
	s_mov_b64 exec, 32
	v_mov_b32_e32 v222, v167
	s_mov_b64 exec, 64
	v_mov_b32_e32 v222, v168
	s_mov_b64 exec, 0x80
	v_mov_b32_e32 v222, v169
	s_mov_b64 exec, 0xff
	v_add_f32_e32 v223, v222, v196
	v_mul_f32_e64 v225, |v223|, s24
	v_exp_f32_e32 v210, v225
	v_min_f32_e32 v225, 0, v223
	s_nop 0
	v_add_f32_e32 v211, 1.0, v210
	v_add_f32_e32 v212, -1.0, v211
	v_frexp_mant_f32_e32 v213, v211
	v_cvt_f64_f32_e32 v[208:209], v211
	v_sub_f32_e32 v214, v212, v211
	v_frexp_exp_i32_f64_e32 v208, v[208:209]
	v_cmp_gt_f32_e32 vcc, s25, v213
	v_sub_f32_e32 v212, v210, v212
	v_add_f32_e32 v209, 1.0, v214
	v_subbrev_co_u32_e32 v208, vcc, 0, v208, vcc
	v_add_f32_e32 v209, v212, v209
	v_sub_u32_e32 v212, 0, v208
	v_cvt_f32_i32_e32 v208, v208
	v_ldexp_f32 v211, v211, v212
	v_ldexp_f32 v209, v209, v212
	v_add_f32_e32 v212, -1.0, v211
	v_add_f32_e32 v213, 1.0, v211
	v_add_f32_e32 v214, 1.0, v212
	v_add_f32_e32 v215, -1.0, v213
	v_sub_f32_e32 v214, v211, v214
	v_sub_f32_e32 v211, v211, v215
	v_mul_f32_e32 v215, 0x3f317218, v208
	v_add_f32_e32 v214, v209, v214
	v_add_f32_e32 v209, v209, v211
	v_fma_f32 v211, v208, s28, -v215
	v_add_f32_e32 v216, v212, v214
	v_add_f32_e32 v217, v213, v209
	v_fmac_f32_e32 v211, 0xb102e308, v208
	v_sub_f32_e32 v208, v216, v212
	v_sub_f32_e32 v212, v217, v213
	v_rcp_f32_e32 v213, v217
	v_add_f32_e32 v218, v215, v211
	v_sub_f32_e32 v209, v209, v212
	v_sub_f32_e32 v212, v218, v215
	v_sub_f32_e32 v211, v211, v212
	v_mul_f32_e32 v212, v216, v213
	v_sub_f32_e32 v208, v214, v208
	v_mul_f32_e32 v214, v217, v212
	v_fma_f32 v215, v212, v217, -v214
	v_fmac_f32_e32 v215, v212, v209
	v_add_f32_e32 v219, v214, v215
	v_sub_f32_e32 v220, v216, v219
	v_sub_f32_e32 v214, v219, v214
	v_sub_f32_e32 v216, v216, v220
	v_sub_f32_e32 v214, v214, v215
	v_sub_f32_e32 v215, v216, v219
	v_add_f32_e32 v208, v208, v215
	v_add_f32_e32 v208, v214, v208
	v_add_f32_e32 v214, v220, v208
	v_mul_f32_e32 v215, v213, v214
	v_sub_f32_e32 v216, v220, v214
	v_mul_f32_e32 v219, v217, v215
	v_add_f32_e32 v208, v208, v216
	v_add_f32_e32 v216, v212, v215
	v_fma_f32 v217, v215, v217, -v219
	v_sub_f32_e32 v212, v216, v212
	v_fmac_f32_e32 v217, v215, v209
	v_sub_f32_e32 v209, v215, v212
	v_add_f32_e32 v212, v219, v217
	v_sub_f32_e32 v215, v212, v219
	v_sub_f32_e32 v219, v214, v212
	v_sub_f32_e32 v214, v214, v219
	v_sub_f32_e32 v212, v214, v212
	v_sub_f32_e32 v215, v215, v217
	v_add_f32_e32 v208, v208, v212
	v_add_f32_e32 v208, v215, v208
	v_add_f32_e32 v208, v219, v208
	v_mul_f32_e32 v208, v213, v208
	v_add_f32_e32 v208, v209, v208
	v_add_f32_e32 v209, v216, v208
	v_mul_f32_e32 v212, v209, v209
	v_fmamk_f32 v215, v212, 0x3e9b6dac, v242
	v_sub_f32_e32 v213, v209, v216
	v_ldexp_f32 v214, v209, 1
	v_mul_f32_e32 v209, v209, v212
	v_fmaak_f32 v212, v212, v215, 0x3f2aaada
	v_mul_f32_e32 v209, v209, v212
	v_add_f32_e32 v212, v214, v209
	v_sub_f32_e32 v208, v208, v213
	v_sub_f32_e32 v213, v212, v214
	v_ldexp_f32 v208, v208, 1
	v_sub_f32_e32 v209, v209, v213
	v_add_f32_e32 v208, v208, v209
	v_add_f32_e32 v209, v212, v208
	v_sub_f32_e32 v212, v209, v212
	v_add_f32_e32 v213, v218, v209
	v_sub_f32_e32 v208, v208, v212
	v_sub_f32_e32 v212, v213, v218
	v_sub_f32_e32 v214, v213, v212
	v_sub_f32_e32 v209, v209, v212
	v_add_f32_e32 v212, v211, v208
	v_sub_f32_e32 v214, v218, v214
	v_sub_f32_e32 v215, v212, v211
	v_add_f32_e32 v209, v209, v214
	v_sub_f32_e32 v214, v212, v215
	v_sub_f32_e32 v208, v208, v215
	v_sub_f32_e32 v211, v211, v214
	v_add_f32_e32 v209, v212, v209
	v_add_f32_e32 v208, v208, v211
	v_add_f32_e32 v211, v213, v209
	v_sub_f32_e32 v212, v211, v213
	v_sub_f32_e32 v209, v209, v212
	v_add_f32_e32 v208, v208, v209
	v_add_f32_e32 v208, v211, v208
	v_cmp_neq_f32_e32 vcc, s29, v210
	s_nop 0
	s_nop 0
	v_cndmask_b32_e32 v208, v243, v208, vcc
	v_cmp_ngt_f32_e32 vcc, -1.0, v210
	s_nop 1
	v_cndmask_b32_e32 v208, v244, v208, vcc
	v_cmp_neq_f32_e32 vcc, -1.0, v210
	s_nop 1
	v_cndmask_b32_e32 v208, v245, v208, vcc
	v_cmp_lt_f32_e64 vcc, |v210|, s30
	s_nop 1
	v_cndmask_b32_e32 v208, v208, v210, vcc
	v_sub_f32_e32 v225, v225, v208
	global_store_dword v195, v225, s[74:75]
	s_mov_b64 exec, -1
	v_add_u32_e32 v195, 0x2000, v195
	s_waitcnt vmcnt(17)
	v_pk_mul_f32 v[198:199], v[66:67], v[66:67]
	v_pk_mul_f32 v[200:201], v[68:69], v[68:69]
	v_pk_fma_f32 v[198:199], v[70:71], v[70:71], v[198:199]
	v_pk_fma_f32 v[200:201], v[72:73], v[72:73], v[200:201]
	v_pk_fma_f32 v[198:199], v[74:75], v[74:75], v[198:199]
	v_pk_fma_f32 v[200:201], v[76:77], v[76:77], v[200:201]
	v_pk_fma_f32 v[198:199], v[78:79], v[78:79], v[198:199]
	v_pk_fma_f32 v[200:201], v[80:81], v[80:81], v[200:201]
	v_pk_fma_f32 v[198:199], v[82:83], v[82:83], v[198:199]
	v_pk_fma_f32 v[200:201], v[84:85], v[84:85], v[200:201]
	v_pk_fma_f32 v[198:199], v[86:87], v[86:87], v[198:199]
	v_pk_fma_f32 v[200:201], v[88:89], v[88:89], v[200:201]
	v_pk_fma_f32 v[198:199], v[90:91], v[90:91], v[198:199]
	v_pk_fma_f32 v[200:201], v[92:93], v[92:93], v[200:201]
	v_pk_fma_f32 v[198:199], v[94:95], v[94:95], v[198:199]
	v_pk_fma_f32 v[200:201], v[96:97], v[96:97], v[200:201]
	v_pk_add_f32 v[198:199], v[198:199], v[200:201]
	v_add_f32_e32 v198, v198, v199
	s_nop 1
	v_add_f32_dpp v198, v198, v198 quad_perm:[1,0,3,2] row_mask:0xf bank_mask:0xf
	s_nop 1
	v_add_f32_dpp v198, v198, v198 quad_perm:[2,3,0,1] row_mask:0xf bank_mask:0xf
	s_nop 1
	v_add_f32_dpp v198, v198, v198 row_half_mirror row_mask:0xf bank_mask:0xf
	s_nop 1
	v_add_f32_dpp v198, v198, v198 row_mirror row_mask:0xf bank_mask:0xf
	v_mov_b32_e32 v199, v198
	s_nop 1
	v_permlane16_swap_b32 v199, v198
	v_add_f32_e32 v198, v198, v199
	v_mov_b32_e32 v199, v198
	s_nop 1
	v_permlane32_swap_b32 v199, v198
	v_add_f32_e32 v198, v198, v199
	ds_read_b128 v[130:133], v192
	ds_read_b128 v[134:137], v192 offset:1024
	ds_read_b128 v[138:141], v192 offset:2048
	ds_read_b128 v[142:145], v192 offset:3072
	ds_read_b128 v[146:149], v192 offset:4096
	ds_read_b128 v[150:153], v192 offset:5120
	ds_read_b128 v[154:157], v192 offset:6144
	ds_read_b128 v[158:161], v192 offset:7168
	v_fmamk_f32 v198, v198, 0x3a000000, v241
	v_mul_f32_e32 v199, 0x4b800000, v198
	v_cmp_gt_f32_e32 vcc, s17, v198
	s_nop 1
	v_cndmask_b32_e32 v198, v198, v199, vcc
	v_rsq_f32_e32 v198, v198
	s_nop 0
	v_mul_f32_e32 v199, 0x45800000, v198
	v_cndmask_b32_e32 v202, v198, v199, vcc
	v_pk_mul_f32 v[98:99], v[66:67], v[202:203] op_sel_hi:[1,0]
	v_pk_mul_f32 v[98:99], v[2:3], v[98:99]
	v_pk_mul_f32 v[100:101], v[68:69], v[202:203] op_sel_hi:[1,0]
	v_pk_mul_f32 v[100:101], v[4:5], v[100:101]
	v_cvt_pk_bf16_f32 v206, v98, v99
	v_cvt_pk_bf16_f32 v207, v100, v101
	global_store_dwordx2 v194, v[206:207], s[52:53]
	v_pk_mul_f32 v[102:103], v[70:71], v[202:203] op_sel_hi:[1,0]
	v_pk_mul_f32 v[102:103], v[6:7], v[102:103]
	v_pk_mul_f32 v[104:105], v[72:73], v[202:203] op_sel_hi:[1,0]
	v_pk_mul_f32 v[104:105], v[8:9], v[104:105]
	v_cvt_pk_bf16_f32 v206, v102, v103
	v_cvt_pk_bf16_f32 v207, v104, v105
	global_store_dwordx2 v194, v[206:207], s[52:53] offset:512
	v_pk_mul_f32 v[106:107], v[74:75], v[202:203] op_sel_hi:[1,0]
	v_pk_mul_f32 v[106:107], v[10:11], v[106:107]
	v_pk_mul_f32 v[108:109], v[76:77], v[202:203] op_sel_hi:[1,0]
	v_pk_mul_f32 v[108:109], v[12:13], v[108:109]
	v_cvt_pk_bf16_f32 v206, v106, v107
	v_cvt_pk_bf16_f32 v207, v108, v109
	global_store_dwordx2 v194, v[206:207], s[52:53] offset:1024
	v_pk_mul_f32 v[110:111], v[78:79], v[202:203] op_sel_hi:[1,0]
	v_pk_mul_f32 v[110:111], v[14:15], v[110:111]
	v_pk_mul_f32 v[112:113], v[80:81], v[202:203] op_sel_hi:[1,0]
	v_pk_mul_f32 v[112:113], v[16:17], v[112:113]
	v_cvt_pk_bf16_f32 v206, v110, v111
	v_cvt_pk_bf16_f32 v207, v112, v113
	global_store_dwordx2 v194, v[206:207], s[52:53] offset:1536
	v_pk_mul_f32 v[114:115], v[82:83], v[202:203] op_sel_hi:[1,0]
	v_pk_mul_f32 v[114:115], v[18:19], v[114:115]
	v_pk_mul_f32 v[116:117], v[84:85], v[202:203] op_sel_hi:[1,0]
	v_pk_mul_f32 v[116:117], v[20:21], v[116:117]
	v_cvt_pk_bf16_f32 v206, v114, v115
	v_cvt_pk_bf16_f32 v207, v116, v117
	global_store_dwordx2 v194, v[206:207], s[52:53] offset:2048
	v_pk_mul_f32 v[118:119], v[86:87], v[202:203] op_sel_hi:[1,0]
	v_pk_mul_f32 v[118:119], v[22:23], v[118:119]
	v_pk_mul_f32 v[120:121], v[88:89], v[202:203] op_sel_hi:[1,0]
	v_pk_mul_f32 v[120:121], v[24:25], v[120:121]
	v_cvt_pk_bf16_f32 v206, v118, v119
	v_cvt_pk_bf16_f32 v207, v120, v121
	global_store_dwordx2 v194, v[206:207], s[52:53] offset:2560
	v_pk_mul_f32 v[122:123], v[90:91], v[202:203] op_sel_hi:[1,0]
	v_pk_mul_f32 v[122:123], v[26:27], v[122:123]
	v_pk_mul_f32 v[124:125], v[92:93], v[202:203] op_sel_hi:[1,0]
	v_pk_mul_f32 v[124:125], v[28:29], v[124:125]
	v_cvt_pk_bf16_f32 v206, v122, v123
	v_cvt_pk_bf16_f32 v207, v124, v125
	global_store_dwordx2 v194, v[206:207], s[52:53] offset:3072
	v_pk_mul_f32 v[126:127], v[94:95], v[202:203] op_sel_hi:[1,0]
	v_pk_mul_f32 v[126:127], v[30:31], v[126:127]
	v_pk_mul_f32 v[128:129], v[96:97], v[202:203] op_sel_hi:[1,0]
	v_pk_mul_f32 v[128:129], v[32:33], v[128:129]
	v_cvt_pk_bf16_f32 v206, v126, v127
	v_cvt_pk_bf16_f32 v207, v128, v129
	global_store_dwordx2 v194, v[206:207], s[52:53] offset:3584
	v_add_u32_e32 v194, 0x800000, v194
	global_load_dwordx4 v[66:69], v193, s[12:13] offset:-4096 nt
	global_load_dwordx4 v[70:73], v193, s[12:13] offset:-3072 nt
	global_load_dwordx4 v[74:77], v193, s[12:13] offset:-2048 nt
	global_load_dwordx4 v[78:81], v193, s[12:13] offset:-1024 nt
	global_load_dwordx4 v[82:85], v193, s[12:13] offset:0 nt
	global_load_dwordx4 v[86:89], v193, s[12:13] offset:1024 nt
	global_load_dwordx4 v[90:93], v193, s[12:13] offset:2048 nt
	global_load_dwordx4 v[94:97], v193, s[12:13] offset:3072 nt
	v_add_u32_e32 v193, s0, v193
	s_waitcnt lgkmcnt(6)
	v_pk_mul_f32 v[162:163], v[130:131], v[98:99] op_sel_hi:[1,0]
	v_pk_mul_f32 v[164:165], v[132:133], v[98:99] op_sel_hi:[1,0]
	v_pk_mul_f32 v[166:167], v[134:135], v[98:99] op_sel_hi:[1,0]
	v_pk_mul_f32 v[168:169], v[136:137], v[98:99] op_sel_hi:[1,0]
	ds_read_b128 v[130:133], v192 offset:8192
	ds_read_b128 v[134:137], v192 offset:9216
	s_waitcnt lgkmcnt(6)
	v_pk_fma_f32 v[162:163], v[138:139], v[98:99], v[162:163] op_sel:[0,1,0] op_sel_hi:[1,1,1]
	v_pk_fma_f32 v[164:165], v[140:141], v[98:99], v[164:165] op_sel:[0,1,0] op_sel_hi:[1,1,1]
	v_pk_fma_f32 v[166:167], v[142:143], v[98:99], v[166:167] op_sel:[0,1,0] op_sel_hi:[1,1,1]
	v_pk_fma_f32 v[168:169], v[144:145], v[98:99], v[168:169] op_sel:[0,1,0] op_sel_hi:[1,1,1]
	ds_read_b128 v[138:141], v192 offset:10240
	ds_read_b128 v[142:145], v192 offset:11264
	s_waitcnt lgkmcnt(6)
	v_pk_fma_f32 v[162:163], v[146:147], v[100:101], v[162:163] op_sel_hi:[1,0,1]
	v_pk_fma_f32 v[164:165], v[148:149], v[100:101], v[164:165] op_sel_hi:[1,0,1]
	v_pk_fma_f32 v[166:167], v[150:151], v[100:101], v[166:167] op_sel_hi:[1,0,1]
	v_pk_fma_f32 v[168:169], v[152:153], v[100:101], v[168:169] op_sel_hi:[1,0,1]
	ds_read_b128 v[146:149], v192 offset:12288
	ds_read_b128 v[150:153], v192 offset:13312
	s_waitcnt lgkmcnt(6)
	v_pk_fma_f32 v[162:163], v[154:155], v[100:101], v[162:163] op_sel:[0,1,0] op_sel_hi:[1,1,1]
	v_pk_fma_f32 v[164:165], v[156:157], v[100:101], v[164:165] op_sel:[0,1,0] op_sel_hi:[1,1,1]
	v_pk_fma_f32 v[166:167], v[158:159], v[100:101], v[166:167] op_sel:[0,1,0] op_sel_hi:[1,1,1]
	v_pk_fma_f32 v[168:169], v[160:161], v[100:101], v[168:169] op_sel:[0,1,0] op_sel_hi:[1,1,1]
	ds_read_b128 v[154:157], v192 offset:14336
	ds_read_b128 v[158:161], v192 offset:15360
	s_waitcnt lgkmcnt(6)
	v_pk_fma_f32 v[162:163], v[130:131], v[102:103], v[162:163] op_sel_hi:[1,0,1]
	v_pk_fma_f32 v[164:165], v[132:133], v[102:103], v[164:165] op_sel_hi:[1,0,1]
	v_pk_fma_f32 v[166:167], v[134:135], v[102:103], v[166:167] op_sel_hi:[1,0,1]
	v_pk_fma_f32 v[168:169], v[136:137], v[102:103], v[168:169] op_sel_hi:[1,0,1]
	ds_read_b128 v[130:133], v192 offset:16384
	ds_read_b128 v[134:137], v192 offset:17408
	s_waitcnt lgkmcnt(6)
	v_pk_fma_f32 v[162:163], v[138:139], v[102:103], v[162:163] op_sel:[0,1,0] op_sel_hi:[1,1,1]
	v_pk_fma_f32 v[164:165], v[140:141], v[102:103], v[164:165] op_sel:[0,1,0] op_sel_hi:[1,1,1]
	v_pk_fma_f32 v[166:167], v[142:143], v[102:103], v[166:167] op_sel:[0,1,0] op_sel_hi:[1,1,1]
	v_pk_fma_f32 v[168:169], v[144:145], v[102:103], v[168:169] op_sel:[0,1,0] op_sel_hi:[1,1,1]
	ds_read_b128 v[138:141], v192 offset:18432
	ds_read_b128 v[142:145], v192 offset:19456
	s_waitcnt lgkmcnt(6)
	v_pk_fma_f32 v[162:163], v[146:147], v[104:105], v[162:163] op_sel_hi:[1,0,1]
	v_pk_fma_f32 v[164:165], v[148:149], v[104:105], v[164:165] op_sel_hi:[1,0,1]
	v_pk_fma_f32 v[166:167], v[150:151], v[104:105], v[166:167] op_sel_hi:[1,0,1]
	v_pk_fma_f32 v[168:169], v[152:153], v[104:105], v[168:169] op_sel_hi:[1,0,1]
	ds_read_b128 v[146:149], v192 offset:20480
	ds_read_b128 v[150:153], v192 offset:21504
	s_waitcnt lgkmcnt(6)
	v_pk_fma_f32 v[162:163], v[154:155], v[104:105], v[162:163] op_sel:[0,1,0] op_sel_hi:[1,1,1]
	v_pk_fma_f32 v[164:165], v[156:157], v[104:105], v[164:165] op_sel:[0,1,0] op_sel_hi:[1,1,1]
	v_pk_fma_f32 v[166:167], v[158:159], v[104:105], v[166:167] op_sel:[0,1,0] op_sel_hi:[1,1,1]
	v_pk_fma_f32 v[168:169], v[160:161], v[104:105], v[168:169] op_sel:[0,1,0] op_sel_hi:[1,1,1]
	ds_read_b128 v[154:157], v192 offset:22528
	ds_read_b128 v[158:161], v192 offset:23552
	s_waitcnt lgkmcnt(6)
	v_pk_fma_f32 v[162:163], v[130:131], v[106:107], v[162:163] op_sel_hi:[1,0,1]
	v_pk_fma_f32 v[164:165], v[132:133], v[106:107], v[164:165] op_sel_hi:[1,0,1]
	v_pk_fma_f32 v[166:167], v[134:135], v[106:107], v[166:167] op_sel_hi:[1,0,1]
	v_pk_fma_f32 v[168:169], v[136:137], v[106:107], v[168:169] op_sel_hi:[1,0,1]
	ds_read_b128 v[130:133], v192 offset:24576
	ds_read_b128 v[134:137], v192 offset:25600
	s_waitcnt lgkmcnt(6)
	v_pk_fma_f32 v[162:163], v[138:139], v[106:107], v[162:163] op_sel:[0,1,0] op_sel_hi:[1,1,1]
	v_pk_fma_f32 v[164:165], v[140:141], v[106:107], v[164:165] op_sel:[0,1,0] op_sel_hi:[1,1,1]
	v_pk_fma_f32 v[166:167], v[142:143], v[106:107], v[166:167] op_sel:[0,1,0] op_sel_hi:[1,1,1]
	v_pk_fma_f32 v[168:169], v[144:145], v[106:107], v[168:169] op_sel:[0,1,0] op_sel_hi:[1,1,1]
	ds_read_b128 v[138:141], v192 offset:26624
	ds_read_b128 v[142:145], v192 offset:27648
	s_waitcnt lgkmcnt(6)
	v_pk_fma_f32 v[162:163], v[146:147], v[108:109], v[162:163] op_sel_hi:[1,0,1]
	v_pk_fma_f32 v[164:165], v[148:149], v[108:109], v[164:165] op_sel_hi:[1,0,1]
	v_pk_fma_f32 v[166:167], v[150:151], v[108:109], v[166:167] op_sel_hi:[1,0,1]
	v_pk_fma_f32 v[168:169], v[152:153], v[108:109], v[168:169] op_sel_hi:[1,0,1]
	ds_read_b128 v[146:149], v192 offset:28672
	ds_read_b128 v[150:153], v192 offset:29696
	s_waitcnt lgkmcnt(6)
	v_pk_fma_f32 v[162:163], v[154:155], v[108:109], v[162:163] op_sel:[0,1,0] op_sel_hi:[1,1,1]
	v_pk_fma_f32 v[164:165], v[156:157], v[108:109], v[164:165] op_sel:[0,1,0] op_sel_hi:[1,1,1]
	v_pk_fma_f32 v[166:167], v[158:159], v[108:109], v[166:167] op_sel:[0,1,0] op_sel_hi:[1,1,1]
	v_pk_fma_f32 v[168:169], v[160:161], v[108:109], v[168:169] op_sel:[0,1,0] op_sel_hi:[1,1,1]
	ds_read_b128 v[154:157], v192 offset:30720
	ds_read_b128 v[158:161], v192 offset:31744
	s_waitcnt lgkmcnt(6)
	v_pk_fma_f32 v[162:163], v[130:131], v[110:111], v[162:163] op_sel_hi:[1,0,1]
	v_pk_fma_f32 v[164:165], v[132:133], v[110:111], v[164:165] op_sel_hi:[1,0,1]
	v_pk_fma_f32 v[166:167], v[134:135], v[110:111], v[166:167] op_sel_hi:[1,0,1]
	v_pk_fma_f32 v[168:169], v[136:137], v[110:111], v[168:169] op_sel_hi:[1,0,1]
	ds_read_b128 v[130:133], v192 offset:32768
	ds_read_b128 v[134:137], v192 offset:33792
	s_waitcnt lgkmcnt(6)
	v_pk_fma_f32 v[162:163], v[138:139], v[110:111], v[162:163] op_sel:[0,1,0] op_sel_hi:[1,1,1]
	v_pk_fma_f32 v[164:165], v[140:141], v[110:111], v[164:165] op_sel:[0,1,0] op_sel_hi:[1,1,1]
	v_pk_fma_f32 v[166:167], v[142:143], v[110:111], v[166:167] op_sel:[0,1,0] op_sel_hi:[1,1,1]
	v_pk_fma_f32 v[168:169], v[144:145], v[110:111], v[168:169] op_sel:[0,1,0] op_sel_hi:[1,1,1]
	ds_read_b128 v[138:141], v192 offset:34816
	ds_read_b128 v[142:145], v192 offset:35840
	s_waitcnt lgkmcnt(6)
	v_pk_fma_f32 v[162:163], v[146:147], v[112:113], v[162:163] op_sel_hi:[1,0,1]
	v_pk_fma_f32 v[164:165], v[148:149], v[112:113], v[164:165] op_sel_hi:[1,0,1]
	v_pk_fma_f32 v[166:167], v[150:151], v[112:113], v[166:167] op_sel_hi:[1,0,1]
	v_pk_fma_f32 v[168:169], v[152:153], v[112:113], v[168:169] op_sel_hi:[1,0,1]
	ds_read_b128 v[146:149], v192 offset:36864
	ds_read_b128 v[150:153], v192 offset:37888
	s_waitcnt lgkmcnt(6)
	v_pk_fma_f32 v[162:163], v[154:155], v[112:113], v[162:163] op_sel:[0,1,0] op_sel_hi:[1,1,1]
	v_pk_fma_f32 v[164:165], v[156:157], v[112:113], v[164:165] op_sel:[0,1,0] op_sel_hi:[1,1,1]
	v_pk_fma_f32 v[166:167], v[158:159], v[112:113], v[166:167] op_sel:[0,1,0] op_sel_hi:[1,1,1]
	v_pk_fma_f32 v[168:169], v[160:161], v[112:113], v[168:169] op_sel:[0,1,0] op_sel_hi:[1,1,1]
	ds_read_b128 v[154:157], v192 offset:38912
	ds_read_b128 v[158:161], v192 offset:39936
	s_waitcnt lgkmcnt(6)
	v_pk_fma_f32 v[162:163], v[130:131], v[114:115], v[162:163] op_sel_hi:[1,0,1]
	v_pk_fma_f32 v[164:165], v[132:133], v[114:115], v[164:165] op_sel_hi:[1,0,1]
	v_pk_fma_f32 v[166:167], v[134:135], v[114:115], v[166:167] op_sel_hi:[1,0,1]
	v_pk_fma_f32 v[168:169], v[136:137], v[114:115], v[168:169] op_sel_hi:[1,0,1]
	ds_read_b128 v[130:133], v192 offset:40960
	ds_read_b128 v[134:137], v192 offset:41984
	s_waitcnt lgkmcnt(6)
	v_pk_fma_f32 v[162:163], v[138:139], v[114:115], v[162:163] op_sel:[0,1,0] op_sel_hi:[1,1,1]
	v_pk_fma_f32 v[164:165], v[140:141], v[114:115], v[164:165] op_sel:[0,1,0] op_sel_hi:[1,1,1]
	v_pk_fma_f32 v[166:167], v[142:143], v[114:115], v[166:167] op_sel:[0,1,0] op_sel_hi:[1,1,1]
	v_pk_fma_f32 v[168:169], v[144:145], v[114:115], v[168:169] op_sel:[0,1,0] op_sel_hi:[1,1,1]
	ds_read_b128 v[138:141], v192 offset:43008
	ds_read_b128 v[142:145], v192 offset:44032
	s_waitcnt lgkmcnt(6)
	v_pk_fma_f32 v[162:163], v[146:147], v[116:117], v[162:163] op_sel_hi:[1,0,1]
	v_pk_fma_f32 v[164:165], v[148:149], v[116:117], v[164:165] op_sel_hi:[1,0,1]
	v_pk_fma_f32 v[166:167], v[150:151], v[116:117], v[166:167] op_sel_hi:[1,0,1]
	v_pk_fma_f32 v[168:169], v[152:153], v[116:117], v[168:169] op_sel_hi:[1,0,1]
	ds_read_b128 v[146:149], v192 offset:45056
	ds_read_b128 v[150:153], v192 offset:46080
	s_waitcnt lgkmcnt(6)
	v_pk_fma_f32 v[162:163], v[154:155], v[116:117], v[162:163] op_sel:[0,1,0] op_sel_hi:[1,1,1]
	v_pk_fma_f32 v[164:165], v[156:157], v[116:117], v[164:165] op_sel:[0,1,0] op_sel_hi:[1,1,1]
	v_pk_fma_f32 v[166:167], v[158:159], v[116:117], v[166:167] op_sel:[0,1,0] op_sel_hi:[1,1,1]
	v_pk_fma_f32 v[168:169], v[160:161], v[116:117], v[168:169] op_sel:[0,1,0] op_sel_hi:[1,1,1]
	ds_read_b128 v[154:157], v192 offset:47104
	ds_read_b128 v[158:161], v192 offset:48128
	s_waitcnt lgkmcnt(6)
	v_pk_fma_f32 v[162:163], v[130:131], v[118:119], v[162:163] op_sel_hi:[1,0,1]
	v_pk_fma_f32 v[164:165], v[132:133], v[118:119], v[164:165] op_sel_hi:[1,0,1]
	v_pk_fma_f32 v[166:167], v[134:135], v[118:119], v[166:167] op_sel_hi:[1,0,1]
	v_pk_fma_f32 v[168:169], v[136:137], v[118:119], v[168:169] op_sel_hi:[1,0,1]
	ds_read_b128 v[130:133], v192 offset:49152
	ds_read_b128 v[134:137], v192 offset:50176
	s_waitcnt lgkmcnt(6)
	v_pk_fma_f32 v[162:163], v[138:139], v[118:119], v[162:163] op_sel:[0,1,0] op_sel_hi:[1,1,1]
	v_pk_fma_f32 v[164:165], v[140:141], v[118:119], v[164:165] op_sel:[0,1,0] op_sel_hi:[1,1,1]
	v_pk_fma_f32 v[166:167], v[142:143], v[118:119], v[166:167] op_sel:[0,1,0] op_sel_hi:[1,1,1]
	v_pk_fma_f32 v[168:169], v[144:145], v[118:119], v[168:169] op_sel:[0,1,0] op_sel_hi:[1,1,1]
	ds_read_b128 v[138:141], v192 offset:51200
	ds_read_b128 v[142:145], v192 offset:52224
	s_waitcnt lgkmcnt(6)
	v_pk_fma_f32 v[162:163], v[146:147], v[120:121], v[162:163] op_sel_hi:[1,0,1]
	v_pk_fma_f32 v[164:165], v[148:149], v[120:121], v[164:165] op_sel_hi:[1,0,1]
	v_pk_fma_f32 v[166:167], v[150:151], v[120:121], v[166:167] op_sel_hi:[1,0,1]
	v_pk_fma_f32 v[168:169], v[152:153], v[120:121], v[168:169] op_sel_hi:[1,0,1]
	ds_read_b128 v[146:149], v192 offset:53248
	ds_read_b128 v[150:153], v192 offset:54272
	s_waitcnt lgkmcnt(6)
	v_pk_fma_f32 v[162:163], v[154:155], v[120:121], v[162:163] op_sel:[0,1,0] op_sel_hi:[1,1,1]
	v_pk_fma_f32 v[164:165], v[156:157], v[120:121], v[164:165] op_sel:[0,1,0] op_sel_hi:[1,1,1]
	v_pk_fma_f32 v[166:167], v[158:159], v[120:121], v[166:167] op_sel:[0,1,0] op_sel_hi:[1,1,1]
	v_pk_fma_f32 v[168:169], v[160:161], v[120:121], v[168:169] op_sel:[0,1,0] op_sel_hi:[1,1,1]
	ds_read_b128 v[154:157], v192 offset:55296
	ds_read_b128 v[158:161], v192 offset:56320
	s_waitcnt lgkmcnt(6)
	v_pk_fma_f32 v[162:163], v[130:131], v[122:123], v[162:163] op_sel_hi:[1,0,1]
	v_pk_fma_f32 v[164:165], v[132:133], v[122:123], v[164:165] op_sel_hi:[1,0,1]
	v_pk_fma_f32 v[166:167], v[134:135], v[122:123], v[166:167] op_sel_hi:[1,0,1]
	v_pk_fma_f32 v[168:169], v[136:137], v[122:123], v[168:169] op_sel_hi:[1,0,1]
	ds_read_b128 v[130:133], v192 offset:57344
	ds_read_b128 v[134:137], v192 offset:58368
	s_waitcnt lgkmcnt(6)
	v_pk_fma_f32 v[162:163], v[138:139], v[122:123], v[162:163] op_sel:[0,1,0] op_sel_hi:[1,1,1]
	v_pk_fma_f32 v[164:165], v[140:141], v[122:123], v[164:165] op_sel:[0,1,0] op_sel_hi:[1,1,1]
	v_pk_fma_f32 v[166:167], v[142:143], v[122:123], v[166:167] op_sel:[0,1,0] op_sel_hi:[1,1,1]
	v_pk_fma_f32 v[168:169], v[144:145], v[122:123], v[168:169] op_sel:[0,1,0] op_sel_hi:[1,1,1]
	ds_read_b128 v[138:141], v192 offset:59392
	ds_read_b128 v[142:145], v192 offset:60416
	s_waitcnt lgkmcnt(6)
	v_pk_fma_f32 v[162:163], v[146:147], v[124:125], v[162:163] op_sel_hi:[1,0,1]
	v_pk_fma_f32 v[164:165], v[148:149], v[124:125], v[164:165] op_sel_hi:[1,0,1]
	v_pk_fma_f32 v[166:167], v[150:151], v[124:125], v[166:167] op_sel_hi:[1,0,1]
	v_pk_fma_f32 v[168:169], v[152:153], v[124:125], v[168:169] op_sel_hi:[1,0,1]
	ds_read_b128 v[146:149], v192 offset:61440
	ds_read_b128 v[150:153], v192 offset:62464
	s_waitcnt lgkmcnt(6)
	v_pk_fma_f32 v[162:163], v[154:155], v[124:125], v[162:163] op_sel:[0,1,0] op_sel_hi:[1,1,1]
	v_pk_fma_f32 v[164:165], v[156:157], v[124:125], v[164:165] op_sel:[0,1,0] op_sel_hi:[1,1,1]
	v_pk_fma_f32 v[166:167], v[158:159], v[124:125], v[166:167] op_sel:[0,1,0] op_sel_hi:[1,1,1]
	v_pk_fma_f32 v[168:169], v[160:161], v[124:125], v[168:169] op_sel:[0,1,0] op_sel_hi:[1,1,1]
	ds_read_b128 v[154:157], v192 offset:63488
	ds_read_b128 v[158:161], v192 offset:64512
	s_waitcnt lgkmcnt(6)
	v_pk_fma_f32 v[162:163], v[130:131], v[126:127], v[162:163] op_sel_hi:[1,0,1]
	v_pk_fma_f32 v[164:165], v[132:133], v[126:127], v[164:165] op_sel_hi:[1,0,1]
	v_pk_fma_f32 v[166:167], v[134:135], v[126:127], v[166:167] op_sel_hi:[1,0,1]
	v_pk_fma_f32 v[168:169], v[136:137], v[126:127], v[168:169] op_sel_hi:[1,0,1]
	s_waitcnt lgkmcnt(4)
	v_pk_fma_f32 v[162:163], v[138:139], v[126:127], v[162:163] op_sel:[0,1,0] op_sel_hi:[1,1,1]
	v_pk_fma_f32 v[164:165], v[140:141], v[126:127], v[164:165] op_sel:[0,1,0] op_sel_hi:[1,1,1]
	v_pk_fma_f32 v[166:167], v[142:143], v[126:127], v[166:167] op_sel:[0,1,0] op_sel_hi:[1,1,1]
	v_pk_fma_f32 v[168:169], v[144:145], v[126:127], v[168:169] op_sel:[0,1,0] op_sel_hi:[1,1,1]
	s_waitcnt lgkmcnt(2)
	v_pk_fma_f32 v[162:163], v[146:147], v[128:129], v[162:163] op_sel_hi:[1,0,1]
	v_pk_fma_f32 v[164:165], v[148:149], v[128:129], v[164:165] op_sel_hi:[1,0,1]
	v_pk_fma_f32 v[166:167], v[150:151], v[128:129], v[166:167] op_sel_hi:[1,0,1]
	v_pk_fma_f32 v[168:169], v[152:153], v[128:129], v[168:169] op_sel_hi:[1,0,1]
	s_waitcnt lgkmcnt(0)
	v_pk_fma_f32 v[162:163], v[154:155], v[128:129], v[162:163] op_sel:[0,1,0] op_sel_hi:[1,1,1]
	v_pk_fma_f32 v[164:165], v[156:157], v[128:129], v[164:165] op_sel:[0,1,0] op_sel_hi:[1,1,1]
	v_pk_fma_f32 v[166:167], v[158:159], v[128:129], v[166:167] op_sel:[0,1,0] op_sel_hi:[1,1,1]
	v_pk_fma_f32 v[168:169], v[160:161], v[128:129], v[168:169] op_sel:[0,1,0] op_sel_hi:[1,1,1]
	s_nop 1
	v_add_f32_dpp v162, v162, v162 quad_perm:[1,0,3,2] row_mask:0xf bank_mask:0xf
	v_add_f32_dpp v163, v163, v163 quad_perm:[1,0,3,2] row_mask:0xf bank_mask:0xf
	v_add_f32_dpp v164, v164, v164 quad_perm:[1,0,3,2] row_mask:0xf bank_mask:0xf
	v_add_f32_dpp v165, v165, v165 quad_perm:[1,0,3,2] row_mask:0xf bank_mask:0xf
	v_add_f32_dpp v166, v166, v166 quad_perm:[1,0,3,2] row_mask:0xf bank_mask:0xf
	v_add_f32_dpp v167, v167, v167 quad_perm:[1,0,3,2] row_mask:0xf bank_mask:0xf
	v_add_f32_dpp v168, v168, v168 quad_perm:[1,0,3,2] row_mask:0xf bank_mask:0xf
	v_add_f32_dpp v169, v169, v169 quad_perm:[1,0,3,2] row_mask:0xf bank_mask:0xf
	v_add_f32_dpp v162, v162, v162 quad_perm:[2,3,0,1] row_mask:0xf bank_mask:0xf
	v_add_f32_dpp v163, v163, v163 quad_perm:[2,3,0,1] row_mask:0xf bank_mask:0xf
	v_add_f32_dpp v164, v164, v164 quad_perm:[2,3,0,1] row_mask:0xf bank_mask:0xf
	v_add_f32_dpp v165, v165, v165 quad_perm:[2,3,0,1] row_mask:0xf bank_mask:0xf
	v_add_f32_dpp v166, v166, v166 quad_perm:[2,3,0,1] row_mask:0xf bank_mask:0xf
	v_add_f32_dpp v167, v167, v167 quad_perm:[2,3,0,1] row_mask:0xf bank_mask:0xf
	v_add_f32_dpp v168, v168, v168 quad_perm:[2,3,0,1] row_mask:0xf bank_mask:0xf
	v_add_f32_dpp v169, v169, v169 quad_perm:[2,3,0,1] row_mask:0xf bank_mask:0xf
	v_add_f32_dpp v162, v162, v162 row_half_mirror row_mask:0xf bank_mask:0xf
	v_add_f32_dpp v163, v163, v163 row_half_mirror row_mask:0xf bank_mask:0xf
	v_add_f32_dpp v164, v164, v164 row_half_mirror row_mask:0xf bank_mask:0xf
	v_add_f32_dpp v165, v165, v165 row_half_mirror row_mask:0xf bank_mask:0xf
	v_add_f32_dpp v166, v166, v166 row_half_mirror row_mask:0xf bank_mask:0xf
	v_add_f32_dpp v167, v167, v167 row_half_mirror row_mask:0xf bank_mask:0xf
	v_add_f32_dpp v168, v168, v168 row_half_mirror row_mask:0xf bank_mask:0xf
	v_add_f32_dpp v169, v169, v169 row_half_mirror row_mask:0xf bank_mask:0xf
	v_add_f32_dpp v162, v162, v162 row_mirror row_mask:0xf bank_mask:0xf
	v_add_f32_dpp v163, v163, v163 row_mirror row_mask:0xf bank_mask:0xf
	v_add_f32_dpp v164, v164, v164 row_mirror row_mask:0xf bank_mask:0xf
	v_add_f32_dpp v165, v165, v165 row_mirror row_mask:0xf bank_mask:0xf
	v_add_f32_dpp v166, v166, v166 row_mirror row_mask:0xf bank_mask:0xf
	v_add_f32_dpp v167, v167, v167 row_mirror row_mask:0xf bank_mask:0xf
	v_add_f32_dpp v168, v168, v168 row_mirror row_mask:0xf bank_mask:0xf
	v_add_f32_dpp v169, v169, v169 row_mirror row_mask:0xf bank_mask:0xf
	v_mov_b32_e32 v170, v162
	v_mov_b32_e32 v171, v163
	v_mov_b32_e32 v172, v164
	v_mov_b32_e32 v173, v165
	v_mov_b32_e32 v174, v166
	v_mov_b32_e32 v175, v167
	v_mov_b32_e32 v176, v168
	v_mov_b32_e32 v177, v169
	v_permlane16_swap_b32 v170, v162
	v_permlane16_swap_b32 v171, v163
	v_permlane16_swap_b32 v172, v164
	v_permlane16_swap_b32 v173, v165
	v_permlane16_swap_b32 v174, v166
	v_permlane16_swap_b32 v175, v167
	v_permlane16_swap_b32 v176, v168
	v_permlane16_swap_b32 v177, v169
	v_add_f32_e32 v162, v162, v170
	v_add_f32_e32 v163, v163, v171
	v_add_f32_e32 v164, v164, v172
	v_add_f32_e32 v165, v165, v173
	v_add_f32_e32 v166, v166, v174
	v_add_f32_e32 v167, v167, v175
	v_add_f32_e32 v168, v168, v176
	v_add_f32_e32 v169, v169, v177
	v_mov_b32_e32 v170, v162
	v_mov_b32_e32 v171, v163
	v_mov_b32_e32 v172, v164
	v_mov_b32_e32 v173, v165
	v_mov_b32_e32 v174, v166
	v_mov_b32_e32 v175, v167
	v_mov_b32_e32 v176, v168
	v_mov_b32_e32 v177, v169
	v_permlane32_swap_b32 v170, v162
	v_permlane32_swap_b32 v171, v163
	v_permlane32_swap_b32 v172, v164
	v_permlane32_swap_b32 v173, v165
	v_permlane32_swap_b32 v174, v166
	v_permlane32_swap_b32 v175, v167
	v_permlane32_swap_b32 v176, v168
	v_permlane32_swap_b32 v177, v169
	v_add_f32_e32 v162, v162, v170
	v_add_f32_e32 v163, v163, v171
	v_add_f32_e32 v164, v164, v172
	v_add_f32_e32 v165, v165, v173
	v_add_f32_e32 v166, v166, v174
	v_add_f32_e32 v167, v167, v175
	v_add_f32_e32 v168, v168, v176
	v_add_f32_e32 v169, v169, v177
	s_mov_b64 exec, 1
	v_mov_b32_e32 v222, v162
	s_mov_b64 exec, 2
	v_mov_b32_e32 v222, v163
	s_mov_b64 exec, 4
	v_mov_b32_e32 v222, v164
	s_mov_b64 exec, 8
	v_mov_b32_e32 v222, v165
	s_mov_b64 exec, 16
	v_mov_b32_e32 v222, v166
	s_mov_b64 exec, 32
	v_mov_b32_e32 v222, v167
	s_mov_b64 exec, 64
	v_mov_b32_e32 v222, v168
	s_mov_b64 exec, 0x80
	v_mov_b32_e32 v222, v169
	s_mov_b64 exec, 0xff
	v_add_f32_e32 v223, v222, v196
	v_mul_f32_e64 v225, |v223|, s24
	v_exp_f32_e32 v210, v225
	v_min_f32_e32 v225, 0, v223
	s_nop 0
	v_add_f32_e32 v211, 1.0, v210
	v_add_f32_e32 v212, -1.0, v211
	v_frexp_mant_f32_e32 v213, v211
	v_cvt_f64_f32_e32 v[208:209], v211
	v_sub_f32_e32 v214, v212, v211
	v_frexp_exp_i32_f64_e32 v208, v[208:209]
	v_cmp_gt_f32_e32 vcc, s25, v213
	v_sub_f32_e32 v212, v210, v212
	v_add_f32_e32 v209, 1.0, v214
	v_subbrev_co_u32_e32 v208, vcc, 0, v208, vcc
	v_add_f32_e32 v209, v212, v209
	v_sub_u32_e32 v212, 0, v208
	v_cvt_f32_i32_e32 v208, v208
	v_ldexp_f32 v211, v211, v212
	v_ldexp_f32 v209, v209, v212
	v_add_f32_e32 v212, -1.0, v211
	v_add_f32_e32 v213, 1.0, v211
	v_add_f32_e32 v214, 1.0, v212
	v_add_f32_e32 v215, -1.0, v213
	v_sub_f32_e32 v214, v211, v214
	v_sub_f32_e32 v211, v211, v215
	v_mul_f32_e32 v215, 0x3f317218, v208
	v_add_f32_e32 v214, v209, v214
	v_add_f32_e32 v209, v209, v211
	v_fma_f32 v211, v208, s28, -v215
	v_add_f32_e32 v216, v212, v214
	v_add_f32_e32 v217, v213, v209
	v_fmac_f32_e32 v211, 0xb102e308, v208
	v_sub_f32_e32 v208, v216, v212
	v_sub_f32_e32 v212, v217, v213
	v_rcp_f32_e32 v213, v217
	v_add_f32_e32 v218, v215, v211
	v_sub_f32_e32 v209, v209, v212
	v_sub_f32_e32 v212, v218, v215
	v_sub_f32_e32 v211, v211, v212
	v_mul_f32_e32 v212, v216, v213
	v_sub_f32_e32 v208, v214, v208
	v_mul_f32_e32 v214, v217, v212
	v_fma_f32 v215, v212, v217, -v214
	v_fmac_f32_e32 v215, v212, v209
	v_add_f32_e32 v219, v214, v215
	v_sub_f32_e32 v220, v216, v219
	v_sub_f32_e32 v214, v219, v214
	v_sub_f32_e32 v216, v216, v220
	v_sub_f32_e32 v214, v214, v215
	v_sub_f32_e32 v215, v216, v219
	v_add_f32_e32 v208, v208, v215
	v_add_f32_e32 v208, v214, v208
	v_add_f32_e32 v214, v220, v208
	v_mul_f32_e32 v215, v213, v214
	v_sub_f32_e32 v216, v220, v214
	v_mul_f32_e32 v219, v217, v215
	v_add_f32_e32 v208, v208, v216
	v_add_f32_e32 v216, v212, v215
	v_fma_f32 v217, v215, v217, -v219
	v_sub_f32_e32 v212, v216, v212
	v_fmac_f32_e32 v217, v215, v209
	v_sub_f32_e32 v209, v215, v212
	v_add_f32_e32 v212, v219, v217
	v_sub_f32_e32 v215, v212, v219
	v_sub_f32_e32 v219, v214, v212
	v_sub_f32_e32 v214, v214, v219
	v_sub_f32_e32 v212, v214, v212
	v_sub_f32_e32 v215, v215, v217
	v_add_f32_e32 v208, v208, v212
	v_add_f32_e32 v208, v215, v208
	v_add_f32_e32 v208, v219, v208
	v_mul_f32_e32 v208, v213, v208
	v_add_f32_e32 v208, v209, v208
	v_add_f32_e32 v209, v216, v208
	v_mul_f32_e32 v212, v209, v209
	v_fmamk_f32 v215, v212, 0x3e9b6dac, v242
	v_sub_f32_e32 v213, v209, v216
	v_ldexp_f32 v214, v209, 1
	v_mul_f32_e32 v209, v209, v212
	v_fmaak_f32 v212, v212, v215, 0x3f2aaada
	v_mul_f32_e32 v209, v209, v212
	v_add_f32_e32 v212, v214, v209
	v_sub_f32_e32 v208, v208, v213
	v_sub_f32_e32 v213, v212, v214
	v_ldexp_f32 v208, v208, 1
	v_sub_f32_e32 v209, v209, v213
	v_add_f32_e32 v208, v208, v209
	v_add_f32_e32 v209, v212, v208
	v_sub_f32_e32 v212, v209, v212
	v_add_f32_e32 v213, v218, v209
	v_sub_f32_e32 v208, v208, v212
	v_sub_f32_e32 v212, v213, v218
	v_sub_f32_e32 v214, v213, v212
	v_sub_f32_e32 v209, v209, v212
	v_add_f32_e32 v212, v211, v208
	v_sub_f32_e32 v214, v218, v214
	v_sub_f32_e32 v215, v212, v211
	v_add_f32_e32 v209, v209, v214
	v_sub_f32_e32 v214, v212, v215
	v_sub_f32_e32 v208, v208, v215
	v_sub_f32_e32 v211, v211, v214
	v_add_f32_e32 v209, v212, v209
	v_add_f32_e32 v208, v208, v211
	v_add_f32_e32 v211, v213, v209
	v_sub_f32_e32 v212, v211, v213
	v_sub_f32_e32 v209, v209, v212
	v_add_f32_e32 v208, v208, v209
	v_add_f32_e32 v208, v211, v208
	v_cmp_neq_f32_e32 vcc, s29, v210
	s_nop 0
	s_nop 0
	v_cndmask_b32_e32 v208, v243, v208, vcc
	v_cmp_ngt_f32_e32 vcc, -1.0, v210
	s_nop 1
	v_cndmask_b32_e32 v208, v244, v208, vcc
	v_cmp_neq_f32_e32 vcc, -1.0, v210
	s_nop 1
	v_cndmask_b32_e32 v208, v245, v208, vcc
	v_cmp_lt_f32_e64 vcc, |v210|, s30
	s_nop 1
	v_cndmask_b32_e32 v208, v208, v210, vcc
	v_sub_f32_e32 v225, v225, v208
	global_store_dword v195, v225, s[74:75]
	s_mov_b64 exec, -1
	v_add_u32_e32 v195, 0x2000, v195
	s_waitcnt vmcnt(18)
	v_pk_mul_f32 v[198:199], v[34:35], v[34:35]
	v_pk_mul_f32 v[200:201], v[36:37], v[36:37]
	v_pk_fma_f32 v[198:199], v[38:39], v[38:39], v[198:199]
	v_pk_fma_f32 v[200:201], v[40:41], v[40:41], v[200:201]
	v_pk_fma_f32 v[198:199], v[42:43], v[42:43], v[198:199]
	v_pk_fma_f32 v[200:201], v[44:45], v[44:45], v[200:201]
	v_pk_fma_f32 v[198:199], v[46:47], v[46:47], v[198:199]
	v_pk_fma_f32 v[200:201], v[48:49], v[48:49], v[200:201]
	v_pk_fma_f32 v[198:199], v[50:51], v[50:51], v[198:199]
	v_pk_fma_f32 v[200:201], v[52:53], v[52:53], v[200:201]
	v_pk_fma_f32 v[198:199], v[54:55], v[54:55], v[198:199]
	v_pk_fma_f32 v[200:201], v[56:57], v[56:57], v[200:201]
	v_pk_fma_f32 v[198:199], v[58:59], v[58:59], v[198:199]
	v_pk_fma_f32 v[200:201], v[60:61], v[60:61], v[200:201]
	v_pk_fma_f32 v[198:199], v[62:63], v[62:63], v[198:199]
	v_pk_fma_f32 v[200:201], v[64:65], v[64:65], v[200:201]
	v_pk_add_f32 v[198:199], v[198:199], v[200:201]
	v_add_f32_e32 v198, v198, v199
	s_nop 1
	v_add_f32_dpp v198, v198, v198 quad_perm:[1,0,3,2] row_mask:0xf bank_mask:0xf
	s_nop 1
	v_add_f32_dpp v198, v198, v198 quad_perm:[2,3,0,1] row_mask:0xf bank_mask:0xf
	s_nop 1
	v_add_f32_dpp v198, v198, v198 row_half_mirror row_mask:0xf bank_mask:0xf
	s_nop 1
	v_add_f32_dpp v198, v198, v198 row_mirror row_mask:0xf bank_mask:0xf
	v_mov_b32_e32 v199, v198
	s_nop 1
	v_permlane16_swap_b32 v199, v198
	v_add_f32_e32 v198, v198, v199
	v_mov_b32_e32 v199, v198
	s_nop 1
	v_permlane32_swap_b32 v199, v198
	v_add_f32_e32 v198, v198, v199
	ds_read_b128 v[130:133], v192
	ds_read_b128 v[134:137], v192 offset:1024
	ds_read_b128 v[138:141], v192 offset:2048
	ds_read_b128 v[142:145], v192 offset:3072
	ds_read_b128 v[146:149], v192 offset:4096
	ds_read_b128 v[150:153], v192 offset:5120
	ds_read_b128 v[154:157], v192 offset:6144
	ds_read_b128 v[158:161], v192 offset:7168
	v_fmamk_f32 v198, v198, 0x3a000000, v241
	v_mul_f32_e32 v199, 0x4b800000, v198
	v_cmp_gt_f32_e32 vcc, s17, v198
	s_nop 1
	v_cndmask_b32_e32 v198, v198, v199, vcc
	v_rsq_f32_e32 v198, v198
	s_nop 0
	v_mul_f32_e32 v199, 0x45800000, v198
	v_cndmask_b32_e32 v202, v198, v199, vcc
	v_pk_mul_f32 v[98:99], v[34:35], v[202:203] op_sel_hi:[1,0]
	v_pk_mul_f32 v[98:99], v[2:3], v[98:99]
	v_pk_mul_f32 v[100:101], v[36:37], v[202:203] op_sel_hi:[1,0]
	v_pk_mul_f32 v[100:101], v[4:5], v[100:101]
	v_cvt_pk_bf16_f32 v206, v98, v99
	v_cvt_pk_bf16_f32 v207, v100, v101
	global_store_dwordx2 v194, v[206:207], s[52:53]
	v_pk_mul_f32 v[102:103], v[38:39], v[202:203] op_sel_hi:[1,0]
	v_pk_mul_f32 v[102:103], v[6:7], v[102:103]
	v_pk_mul_f32 v[104:105], v[40:41], v[202:203] op_sel_hi:[1,0]
	v_pk_mul_f32 v[104:105], v[8:9], v[104:105]
	v_cvt_pk_bf16_f32 v206, v102, v103
	v_cvt_pk_bf16_f32 v207, v104, v105
	global_store_dwordx2 v194, v[206:207], s[52:53] offset:512
	v_pk_mul_f32 v[106:107], v[42:43], v[202:203] op_sel_hi:[1,0]
	v_pk_mul_f32 v[106:107], v[10:11], v[106:107]
	v_pk_mul_f32 v[108:109], v[44:45], v[202:203] op_sel_hi:[1,0]
	v_pk_mul_f32 v[108:109], v[12:13], v[108:109]
	v_cvt_pk_bf16_f32 v206, v106, v107
	v_cvt_pk_bf16_f32 v207, v108, v109
	global_store_dwordx2 v194, v[206:207], s[52:53] offset:1024
	v_pk_mul_f32 v[110:111], v[46:47], v[202:203] op_sel_hi:[1,0]
	v_pk_mul_f32 v[110:111], v[14:15], v[110:111]
	v_pk_mul_f32 v[112:113], v[48:49], v[202:203] op_sel_hi:[1,0]
	v_pk_mul_f32 v[112:113], v[16:17], v[112:113]
	v_cvt_pk_bf16_f32 v206, v110, v111
	v_cvt_pk_bf16_f32 v207, v112, v113
	global_store_dwordx2 v194, v[206:207], s[52:53] offset:1536
	v_pk_mul_f32 v[114:115], v[50:51], v[202:203] op_sel_hi:[1,0]
	v_pk_mul_f32 v[114:115], v[18:19], v[114:115]
	v_pk_mul_f32 v[116:117], v[52:53], v[202:203] op_sel_hi:[1,0]
	v_pk_mul_f32 v[116:117], v[20:21], v[116:117]
	v_cvt_pk_bf16_f32 v206, v114, v115
	v_cvt_pk_bf16_f32 v207, v116, v117
	global_store_dwordx2 v194, v[206:207], s[52:53] offset:2048
	v_pk_mul_f32 v[118:119], v[54:55], v[202:203] op_sel_hi:[1,0]
	v_pk_mul_f32 v[118:119], v[22:23], v[118:119]
	v_pk_mul_f32 v[120:121], v[56:57], v[202:203] op_sel_hi:[1,0]
	v_pk_mul_f32 v[120:121], v[24:25], v[120:121]
	v_cvt_pk_bf16_f32 v206, v118, v119
	v_cvt_pk_bf16_f32 v207, v120, v121
	global_store_dwordx2 v194, v[206:207], s[52:53] offset:2560
	v_pk_mul_f32 v[122:123], v[58:59], v[202:203] op_sel_hi:[1,0]
	v_pk_mul_f32 v[122:123], v[26:27], v[122:123]
	v_pk_mul_f32 v[124:125], v[60:61], v[202:203] op_sel_hi:[1,0]
	v_pk_mul_f32 v[124:125], v[28:29], v[124:125]
	v_cvt_pk_bf16_f32 v206, v122, v123
	v_cvt_pk_bf16_f32 v207, v124, v125
	global_store_dwordx2 v194, v[206:207], s[52:53] offset:3072
	v_pk_mul_f32 v[126:127], v[62:63], v[202:203] op_sel_hi:[1,0]
	v_pk_mul_f32 v[126:127], v[30:31], v[126:127]
	v_pk_mul_f32 v[128:129], v[64:65], v[202:203] op_sel_hi:[1,0]
	v_pk_mul_f32 v[128:129], v[32:33], v[128:129]
	v_cvt_pk_bf16_f32 v206, v126, v127
	v_cvt_pk_bf16_f32 v207, v128, v129
	global_store_dwordx2 v194, v[206:207], s[52:53] offset:3584
	v_add_u32_e32 v194, 0x800000, v194
	global_load_dwordx4 v[34:37], v193, s[12:13] offset:-4096 nt
	global_load_dwordx4 v[38:41], v193, s[12:13] offset:-3072 nt
	global_load_dwordx4 v[42:45], v193, s[12:13] offset:-2048 nt
	global_load_dwordx4 v[46:49], v193, s[12:13] offset:-1024 nt
	global_load_dwordx4 v[50:53], v193, s[12:13] offset:0 nt
	global_load_dwordx4 v[54:57], v193, s[12:13] offset:1024 nt
	global_load_dwordx4 v[58:61], v193, s[12:13] offset:2048 nt
	global_load_dwordx4 v[62:65], v193, s[12:13] offset:3072 nt
	v_add_u32_e32 v193, s0, v193
	s_waitcnt lgkmcnt(6)
	v_pk_mul_f32 v[162:163], v[130:131], v[98:99] op_sel_hi:[1,0]
	v_pk_mul_f32 v[164:165], v[132:133], v[98:99] op_sel_hi:[1,0]
	v_pk_mul_f32 v[166:167], v[134:135], v[98:99] op_sel_hi:[1,0]
	v_pk_mul_f32 v[168:169], v[136:137], v[98:99] op_sel_hi:[1,0]
	ds_read_b128 v[130:133], v192 offset:8192
	ds_read_b128 v[134:137], v192 offset:9216
	s_waitcnt lgkmcnt(6)
	v_pk_fma_f32 v[162:163], v[138:139], v[98:99], v[162:163] op_sel:[0,1,0] op_sel_hi:[1,1,1]
	v_pk_fma_f32 v[164:165], v[140:141], v[98:99], v[164:165] op_sel:[0,1,0] op_sel_hi:[1,1,1]
	v_pk_fma_f32 v[166:167], v[142:143], v[98:99], v[166:167] op_sel:[0,1,0] op_sel_hi:[1,1,1]
	v_pk_fma_f32 v[168:169], v[144:145], v[98:99], v[168:169] op_sel:[0,1,0] op_sel_hi:[1,1,1]
	ds_read_b128 v[138:141], v192 offset:10240
	ds_read_b128 v[142:145], v192 offset:11264
	s_waitcnt lgkmcnt(6)
	v_pk_fma_f32 v[162:163], v[146:147], v[100:101], v[162:163] op_sel_hi:[1,0,1]
	v_pk_fma_f32 v[164:165], v[148:149], v[100:101], v[164:165] op_sel_hi:[1,0,1]
	v_pk_fma_f32 v[166:167], v[150:151], v[100:101], v[166:167] op_sel_hi:[1,0,1]
	v_pk_fma_f32 v[168:169], v[152:153], v[100:101], v[168:169] op_sel_hi:[1,0,1]
	ds_read_b128 v[146:149], v192 offset:12288
	ds_read_b128 v[150:153], v192 offset:13312
	s_waitcnt lgkmcnt(6)
	v_pk_fma_f32 v[162:163], v[154:155], v[100:101], v[162:163] op_sel:[0,1,0] op_sel_hi:[1,1,1]
	v_pk_fma_f32 v[164:165], v[156:157], v[100:101], v[164:165] op_sel:[0,1,0] op_sel_hi:[1,1,1]
	v_pk_fma_f32 v[166:167], v[158:159], v[100:101], v[166:167] op_sel:[0,1,0] op_sel_hi:[1,1,1]
	v_pk_fma_f32 v[168:169], v[160:161], v[100:101], v[168:169] op_sel:[0,1,0] op_sel_hi:[1,1,1]
	ds_read_b128 v[154:157], v192 offset:14336
	ds_read_b128 v[158:161], v192 offset:15360
	s_waitcnt lgkmcnt(6)
	v_pk_fma_f32 v[162:163], v[130:131], v[102:103], v[162:163] op_sel_hi:[1,0,1]
	v_pk_fma_f32 v[164:165], v[132:133], v[102:103], v[164:165] op_sel_hi:[1,0,1]
	v_pk_fma_f32 v[166:167], v[134:135], v[102:103], v[166:167] op_sel_hi:[1,0,1]
	v_pk_fma_f32 v[168:169], v[136:137], v[102:103], v[168:169] op_sel_hi:[1,0,1]
	ds_read_b128 v[130:133], v192 offset:16384
	ds_read_b128 v[134:137], v192 offset:17408
	s_waitcnt lgkmcnt(6)
	v_pk_fma_f32 v[162:163], v[138:139], v[102:103], v[162:163] op_sel:[0,1,0] op_sel_hi:[1,1,1]
	v_pk_fma_f32 v[164:165], v[140:141], v[102:103], v[164:165] op_sel:[0,1,0] op_sel_hi:[1,1,1]
	v_pk_fma_f32 v[166:167], v[142:143], v[102:103], v[166:167] op_sel:[0,1,0] op_sel_hi:[1,1,1]
	v_pk_fma_f32 v[168:169], v[144:145], v[102:103], v[168:169] op_sel:[0,1,0] op_sel_hi:[1,1,1]
	ds_read_b128 v[138:141], v192 offset:18432
	ds_read_b128 v[142:145], v192 offset:19456
	s_waitcnt lgkmcnt(6)
	v_pk_fma_f32 v[162:163], v[146:147], v[104:105], v[162:163] op_sel_hi:[1,0,1]
	v_pk_fma_f32 v[164:165], v[148:149], v[104:105], v[164:165] op_sel_hi:[1,0,1]
	v_pk_fma_f32 v[166:167], v[150:151], v[104:105], v[166:167] op_sel_hi:[1,0,1]
	v_pk_fma_f32 v[168:169], v[152:153], v[104:105], v[168:169] op_sel_hi:[1,0,1]
	ds_read_b128 v[146:149], v192 offset:20480
	ds_read_b128 v[150:153], v192 offset:21504
	s_waitcnt lgkmcnt(6)
	v_pk_fma_f32 v[162:163], v[154:155], v[104:105], v[162:163] op_sel:[0,1,0] op_sel_hi:[1,1,1]
	v_pk_fma_f32 v[164:165], v[156:157], v[104:105], v[164:165] op_sel:[0,1,0] op_sel_hi:[1,1,1]
	v_pk_fma_f32 v[166:167], v[158:159], v[104:105], v[166:167] op_sel:[0,1,0] op_sel_hi:[1,1,1]
	v_pk_fma_f32 v[168:169], v[160:161], v[104:105], v[168:169] op_sel:[0,1,0] op_sel_hi:[1,1,1]
	ds_read_b128 v[154:157], v192 offset:22528
	ds_read_b128 v[158:161], v192 offset:23552
	s_waitcnt lgkmcnt(6)
	v_pk_fma_f32 v[162:163], v[130:131], v[106:107], v[162:163] op_sel_hi:[1,0,1]
	v_pk_fma_f32 v[164:165], v[132:133], v[106:107], v[164:165] op_sel_hi:[1,0,1]
	v_pk_fma_f32 v[166:167], v[134:135], v[106:107], v[166:167] op_sel_hi:[1,0,1]
	v_pk_fma_f32 v[168:169], v[136:137], v[106:107], v[168:169] op_sel_hi:[1,0,1]
	ds_read_b128 v[130:133], v192 offset:24576
	ds_read_b128 v[134:137], v192 offset:25600
	s_waitcnt lgkmcnt(6)
	v_pk_fma_f32 v[162:163], v[138:139], v[106:107], v[162:163] op_sel:[0,1,0] op_sel_hi:[1,1,1]
	v_pk_fma_f32 v[164:165], v[140:141], v[106:107], v[164:165] op_sel:[0,1,0] op_sel_hi:[1,1,1]
	v_pk_fma_f32 v[166:167], v[142:143], v[106:107], v[166:167] op_sel:[0,1,0] op_sel_hi:[1,1,1]
	v_pk_fma_f32 v[168:169], v[144:145], v[106:107], v[168:169] op_sel:[0,1,0] op_sel_hi:[1,1,1]
	ds_read_b128 v[138:141], v192 offset:26624
	ds_read_b128 v[142:145], v192 offset:27648
	s_waitcnt lgkmcnt(6)
	v_pk_fma_f32 v[162:163], v[146:147], v[108:109], v[162:163] op_sel_hi:[1,0,1]
	v_pk_fma_f32 v[164:165], v[148:149], v[108:109], v[164:165] op_sel_hi:[1,0,1]
	v_pk_fma_f32 v[166:167], v[150:151], v[108:109], v[166:167] op_sel_hi:[1,0,1]
	v_pk_fma_f32 v[168:169], v[152:153], v[108:109], v[168:169] op_sel_hi:[1,0,1]
	ds_read_b128 v[146:149], v192 offset:28672
	ds_read_b128 v[150:153], v192 offset:29696
	s_waitcnt lgkmcnt(6)
	v_pk_fma_f32 v[162:163], v[154:155], v[108:109], v[162:163] op_sel:[0,1,0] op_sel_hi:[1,1,1]
	v_pk_fma_f32 v[164:165], v[156:157], v[108:109], v[164:165] op_sel:[0,1,0] op_sel_hi:[1,1,1]
	v_pk_fma_f32 v[166:167], v[158:159], v[108:109], v[166:167] op_sel:[0,1,0] op_sel_hi:[1,1,1]
	v_pk_fma_f32 v[168:169], v[160:161], v[108:109], v[168:169] op_sel:[0,1,0] op_sel_hi:[1,1,1]
	ds_read_b128 v[154:157], v192 offset:30720
	ds_read_b128 v[158:161], v192 offset:31744
	s_waitcnt lgkmcnt(6)
	v_pk_fma_f32 v[162:163], v[130:131], v[110:111], v[162:163] op_sel_hi:[1,0,1]
	v_pk_fma_f32 v[164:165], v[132:133], v[110:111], v[164:165] op_sel_hi:[1,0,1]
	v_pk_fma_f32 v[166:167], v[134:135], v[110:111], v[166:167] op_sel_hi:[1,0,1]
	v_pk_fma_f32 v[168:169], v[136:137], v[110:111], v[168:169] op_sel_hi:[1,0,1]
	ds_read_b128 v[130:133], v192 offset:32768
	ds_read_b128 v[134:137], v192 offset:33792
	s_waitcnt lgkmcnt(6)
	v_pk_fma_f32 v[162:163], v[138:139], v[110:111], v[162:163] op_sel:[0,1,0] op_sel_hi:[1,1,1]
	v_pk_fma_f32 v[164:165], v[140:141], v[110:111], v[164:165] op_sel:[0,1,0] op_sel_hi:[1,1,1]
	v_pk_fma_f32 v[166:167], v[142:143], v[110:111], v[166:167] op_sel:[0,1,0] op_sel_hi:[1,1,1]
	v_pk_fma_f32 v[168:169], v[144:145], v[110:111], v[168:169] op_sel:[0,1,0] op_sel_hi:[1,1,1]
	ds_read_b128 v[138:141], v192 offset:34816
	ds_read_b128 v[142:145], v192 offset:35840
	s_waitcnt lgkmcnt(6)
	v_pk_fma_f32 v[162:163], v[146:147], v[112:113], v[162:163] op_sel_hi:[1,0,1]
	v_pk_fma_f32 v[164:165], v[148:149], v[112:113], v[164:165] op_sel_hi:[1,0,1]
	v_pk_fma_f32 v[166:167], v[150:151], v[112:113], v[166:167] op_sel_hi:[1,0,1]
	v_pk_fma_f32 v[168:169], v[152:153], v[112:113], v[168:169] op_sel_hi:[1,0,1]
	ds_read_b128 v[146:149], v192 offset:36864
	ds_read_b128 v[150:153], v192 offset:37888
	s_waitcnt lgkmcnt(6)
	v_pk_fma_f32 v[162:163], v[154:155], v[112:113], v[162:163] op_sel:[0,1,0] op_sel_hi:[1,1,1]
	v_pk_fma_f32 v[164:165], v[156:157], v[112:113], v[164:165] op_sel:[0,1,0] op_sel_hi:[1,1,1]
	v_pk_fma_f32 v[166:167], v[158:159], v[112:113], v[166:167] op_sel:[0,1,0] op_sel_hi:[1,1,1]
	v_pk_fma_f32 v[168:169], v[160:161], v[112:113], v[168:169] op_sel:[0,1,0] op_sel_hi:[1,1,1]
	ds_read_b128 v[154:157], v192 offset:38912
	ds_read_b128 v[158:161], v192 offset:39936
	s_waitcnt lgkmcnt(6)
	v_pk_fma_f32 v[162:163], v[130:131], v[114:115], v[162:163] op_sel_hi:[1,0,1]
	v_pk_fma_f32 v[164:165], v[132:133], v[114:115], v[164:165] op_sel_hi:[1,0,1]
	v_pk_fma_f32 v[166:167], v[134:135], v[114:115], v[166:167] op_sel_hi:[1,0,1]
	v_pk_fma_f32 v[168:169], v[136:137], v[114:115], v[168:169] op_sel_hi:[1,0,1]
	ds_read_b128 v[130:133], v192 offset:40960
	ds_read_b128 v[134:137], v192 offset:41984
	s_waitcnt lgkmcnt(6)
	v_pk_fma_f32 v[162:163], v[138:139], v[114:115], v[162:163] op_sel:[0,1,0] op_sel_hi:[1,1,1]
	v_pk_fma_f32 v[164:165], v[140:141], v[114:115], v[164:165] op_sel:[0,1,0] op_sel_hi:[1,1,1]
	v_pk_fma_f32 v[166:167], v[142:143], v[114:115], v[166:167] op_sel:[0,1,0] op_sel_hi:[1,1,1]
	v_pk_fma_f32 v[168:169], v[144:145], v[114:115], v[168:169] op_sel:[0,1,0] op_sel_hi:[1,1,1]
	ds_read_b128 v[138:141], v192 offset:43008
	ds_read_b128 v[142:145], v192 offset:44032
	s_waitcnt lgkmcnt(6)
	v_pk_fma_f32 v[162:163], v[146:147], v[116:117], v[162:163] op_sel_hi:[1,0,1]
	v_pk_fma_f32 v[164:165], v[148:149], v[116:117], v[164:165] op_sel_hi:[1,0,1]
	v_pk_fma_f32 v[166:167], v[150:151], v[116:117], v[166:167] op_sel_hi:[1,0,1]
	v_pk_fma_f32 v[168:169], v[152:153], v[116:117], v[168:169] op_sel_hi:[1,0,1]
	ds_read_b128 v[146:149], v192 offset:45056
	ds_read_b128 v[150:153], v192 offset:46080
	s_waitcnt lgkmcnt(6)
	v_pk_fma_f32 v[162:163], v[154:155], v[116:117], v[162:163] op_sel:[0,1,0] op_sel_hi:[1,1,1]
	v_pk_fma_f32 v[164:165], v[156:157], v[116:117], v[164:165] op_sel:[0,1,0] op_sel_hi:[1,1,1]
	v_pk_fma_f32 v[166:167], v[158:159], v[116:117], v[166:167] op_sel:[0,1,0] op_sel_hi:[1,1,1]
	v_pk_fma_f32 v[168:169], v[160:161], v[116:117], v[168:169] op_sel:[0,1,0] op_sel_hi:[1,1,1]
	ds_read_b128 v[154:157], v192 offset:47104
	ds_read_b128 v[158:161], v192 offset:48128
	s_waitcnt lgkmcnt(6)
	v_pk_fma_f32 v[162:163], v[130:131], v[118:119], v[162:163] op_sel_hi:[1,0,1]
	v_pk_fma_f32 v[164:165], v[132:133], v[118:119], v[164:165] op_sel_hi:[1,0,1]
	v_pk_fma_f32 v[166:167], v[134:135], v[118:119], v[166:167] op_sel_hi:[1,0,1]
	v_pk_fma_f32 v[168:169], v[136:137], v[118:119], v[168:169] op_sel_hi:[1,0,1]
	ds_read_b128 v[130:133], v192 offset:49152
	ds_read_b128 v[134:137], v192 offset:50176
	s_waitcnt lgkmcnt(6)
	v_pk_fma_f32 v[162:163], v[138:139], v[118:119], v[162:163] op_sel:[0,1,0] op_sel_hi:[1,1,1]
	v_pk_fma_f32 v[164:165], v[140:141], v[118:119], v[164:165] op_sel:[0,1,0] op_sel_hi:[1,1,1]
	v_pk_fma_f32 v[166:167], v[142:143], v[118:119], v[166:167] op_sel:[0,1,0] op_sel_hi:[1,1,1]
	v_pk_fma_f32 v[168:169], v[144:145], v[118:119], v[168:169] op_sel:[0,1,0] op_sel_hi:[1,1,1]
	ds_read_b128 v[138:141], v192 offset:51200
	ds_read_b128 v[142:145], v192 offset:52224
	s_waitcnt lgkmcnt(6)
	v_pk_fma_f32 v[162:163], v[146:147], v[120:121], v[162:163] op_sel_hi:[1,0,1]
	v_pk_fma_f32 v[164:165], v[148:149], v[120:121], v[164:165] op_sel_hi:[1,0,1]
	v_pk_fma_f32 v[166:167], v[150:151], v[120:121], v[166:167] op_sel_hi:[1,0,1]
	v_pk_fma_f32 v[168:169], v[152:153], v[120:121], v[168:169] op_sel_hi:[1,0,1]
	ds_read_b128 v[146:149], v192 offset:53248
	ds_read_b128 v[150:153], v192 offset:54272
	s_waitcnt lgkmcnt(6)
	v_pk_fma_f32 v[162:163], v[154:155], v[120:121], v[162:163] op_sel:[0,1,0] op_sel_hi:[1,1,1]
	v_pk_fma_f32 v[164:165], v[156:157], v[120:121], v[164:165] op_sel:[0,1,0] op_sel_hi:[1,1,1]
	v_pk_fma_f32 v[166:167], v[158:159], v[120:121], v[166:167] op_sel:[0,1,0] op_sel_hi:[1,1,1]
	v_pk_fma_f32 v[168:169], v[160:161], v[120:121], v[168:169] op_sel:[0,1,0] op_sel_hi:[1,1,1]
	ds_read_b128 v[154:157], v192 offset:55296
	ds_read_b128 v[158:161], v192 offset:56320
	s_waitcnt lgkmcnt(6)
	v_pk_fma_f32 v[162:163], v[130:131], v[122:123], v[162:163] op_sel_hi:[1,0,1]
	v_pk_fma_f32 v[164:165], v[132:133], v[122:123], v[164:165] op_sel_hi:[1,0,1]
	v_pk_fma_f32 v[166:167], v[134:135], v[122:123], v[166:167] op_sel_hi:[1,0,1]
	v_pk_fma_f32 v[168:169], v[136:137], v[122:123], v[168:169] op_sel_hi:[1,0,1]
	ds_read_b128 v[130:133], v192 offset:57344
	ds_read_b128 v[134:137], v192 offset:58368
	s_waitcnt lgkmcnt(6)
	v_pk_fma_f32 v[162:163], v[138:139], v[122:123], v[162:163] op_sel:[0,1,0] op_sel_hi:[1,1,1]
	v_pk_fma_f32 v[164:165], v[140:141], v[122:123], v[164:165] op_sel:[0,1,0] op_sel_hi:[1,1,1]
	v_pk_fma_f32 v[166:167], v[142:143], v[122:123], v[166:167] op_sel:[0,1,0] op_sel_hi:[1,1,1]
	v_pk_fma_f32 v[168:169], v[144:145], v[122:123], v[168:169] op_sel:[0,1,0] op_sel_hi:[1,1,1]
	ds_read_b128 v[138:141], v192 offset:59392
	ds_read_b128 v[142:145], v192 offset:60416
	s_waitcnt lgkmcnt(6)
	v_pk_fma_f32 v[162:163], v[146:147], v[124:125], v[162:163] op_sel_hi:[1,0,1]
	v_pk_fma_f32 v[164:165], v[148:149], v[124:125], v[164:165] op_sel_hi:[1,0,1]
	v_pk_fma_f32 v[166:167], v[150:151], v[124:125], v[166:167] op_sel_hi:[1,0,1]
	v_pk_fma_f32 v[168:169], v[152:153], v[124:125], v[168:169] op_sel_hi:[1,0,1]
	ds_read_b128 v[146:149], v192 offset:61440
	ds_read_b128 v[150:153], v192 offset:62464
	s_waitcnt lgkmcnt(6)
	v_pk_fma_f32 v[162:163], v[154:155], v[124:125], v[162:163] op_sel:[0,1,0] op_sel_hi:[1,1,1]
	v_pk_fma_f32 v[164:165], v[156:157], v[124:125], v[164:165] op_sel:[0,1,0] op_sel_hi:[1,1,1]
	v_pk_fma_f32 v[166:167], v[158:159], v[124:125], v[166:167] op_sel:[0,1,0] op_sel_hi:[1,1,1]
	v_pk_fma_f32 v[168:169], v[160:161], v[124:125], v[168:169] op_sel:[0,1,0] op_sel_hi:[1,1,1]
	ds_read_b128 v[154:157], v192 offset:63488
	ds_read_b128 v[158:161], v192 offset:64512
	s_waitcnt lgkmcnt(6)
	v_pk_fma_f32 v[162:163], v[130:131], v[126:127], v[162:163] op_sel_hi:[1,0,1]
	v_pk_fma_f32 v[164:165], v[132:133], v[126:127], v[164:165] op_sel_hi:[1,0,1]
	v_pk_fma_f32 v[166:167], v[134:135], v[126:127], v[166:167] op_sel_hi:[1,0,1]
	v_pk_fma_f32 v[168:169], v[136:137], v[126:127], v[168:169] op_sel_hi:[1,0,1]
	s_waitcnt lgkmcnt(4)
	v_pk_fma_f32 v[162:163], v[138:139], v[126:127], v[162:163] op_sel:[0,1,0] op_sel_hi:[1,1,1]
	v_pk_fma_f32 v[164:165], v[140:141], v[126:127], v[164:165] op_sel:[0,1,0] op_sel_hi:[1,1,1]
	v_pk_fma_f32 v[166:167], v[142:143], v[126:127], v[166:167] op_sel:[0,1,0] op_sel_hi:[1,1,1]
	v_pk_fma_f32 v[168:169], v[144:145], v[126:127], v[168:169] op_sel:[0,1,0] op_sel_hi:[1,1,1]
	s_waitcnt lgkmcnt(2)
	v_pk_fma_f32 v[162:163], v[146:147], v[128:129], v[162:163] op_sel_hi:[1,0,1]
	v_pk_fma_f32 v[164:165], v[148:149], v[128:129], v[164:165] op_sel_hi:[1,0,1]
	v_pk_fma_f32 v[166:167], v[150:151], v[128:129], v[166:167] op_sel_hi:[1,0,1]
	v_pk_fma_f32 v[168:169], v[152:153], v[128:129], v[168:169] op_sel_hi:[1,0,1]
	s_waitcnt lgkmcnt(0)
	v_pk_fma_f32 v[162:163], v[154:155], v[128:129], v[162:163] op_sel:[0,1,0] op_sel_hi:[1,1,1]
	v_pk_fma_f32 v[164:165], v[156:157], v[128:129], v[164:165] op_sel:[0,1,0] op_sel_hi:[1,1,1]
	v_pk_fma_f32 v[166:167], v[158:159], v[128:129], v[166:167] op_sel:[0,1,0] op_sel_hi:[1,1,1]
	v_pk_fma_f32 v[168:169], v[160:161], v[128:129], v[168:169] op_sel:[0,1,0] op_sel_hi:[1,1,1]
	s_nop 1
	v_add_f32_dpp v162, v162, v162 quad_perm:[1,0,3,2] row_mask:0xf bank_mask:0xf
	v_add_f32_dpp v163, v163, v163 quad_perm:[1,0,3,2] row_mask:0xf bank_mask:0xf
	v_add_f32_dpp v164, v164, v164 quad_perm:[1,0,3,2] row_mask:0xf bank_mask:0xf
	v_add_f32_dpp v165, v165, v165 quad_perm:[1,0,3,2] row_mask:0xf bank_mask:0xf
	v_add_f32_dpp v166, v166, v166 quad_perm:[1,0,3,2] row_mask:0xf bank_mask:0xf
	v_add_f32_dpp v167, v167, v167 quad_perm:[1,0,3,2] row_mask:0xf bank_mask:0xf
	v_add_f32_dpp v168, v168, v168 quad_perm:[1,0,3,2] row_mask:0xf bank_mask:0xf
	v_add_f32_dpp v169, v169, v169 quad_perm:[1,0,3,2] row_mask:0xf bank_mask:0xf
	v_add_f32_dpp v162, v162, v162 quad_perm:[2,3,0,1] row_mask:0xf bank_mask:0xf
	v_add_f32_dpp v163, v163, v163 quad_perm:[2,3,0,1] row_mask:0xf bank_mask:0xf
	v_add_f32_dpp v164, v164, v164 quad_perm:[2,3,0,1] row_mask:0xf bank_mask:0xf
	v_add_f32_dpp v165, v165, v165 quad_perm:[2,3,0,1] row_mask:0xf bank_mask:0xf
	v_add_f32_dpp v166, v166, v166 quad_perm:[2,3,0,1] row_mask:0xf bank_mask:0xf
	v_add_f32_dpp v167, v167, v167 quad_perm:[2,3,0,1] row_mask:0xf bank_mask:0xf
	v_add_f32_dpp v168, v168, v168 quad_perm:[2,3,0,1] row_mask:0xf bank_mask:0xf
	v_add_f32_dpp v169, v169, v169 quad_perm:[2,3,0,1] row_mask:0xf bank_mask:0xf
	v_add_f32_dpp v162, v162, v162 row_half_mirror row_mask:0xf bank_mask:0xf
	v_add_f32_dpp v163, v163, v163 row_half_mirror row_mask:0xf bank_mask:0xf
	v_add_f32_dpp v164, v164, v164 row_half_mirror row_mask:0xf bank_mask:0xf
	v_add_f32_dpp v165, v165, v165 row_half_mirror row_mask:0xf bank_mask:0xf
	v_add_f32_dpp v166, v166, v166 row_half_mirror row_mask:0xf bank_mask:0xf
	v_add_f32_dpp v167, v167, v167 row_half_mirror row_mask:0xf bank_mask:0xf
	v_add_f32_dpp v168, v168, v168 row_half_mirror row_mask:0xf bank_mask:0xf
	v_add_f32_dpp v169, v169, v169 row_half_mirror row_mask:0xf bank_mask:0xf
	v_add_f32_dpp v162, v162, v162 row_mirror row_mask:0xf bank_mask:0xf
	v_add_f32_dpp v163, v163, v163 row_mirror row_mask:0xf bank_mask:0xf
	v_add_f32_dpp v164, v164, v164 row_mirror row_mask:0xf bank_mask:0xf
	v_add_f32_dpp v165, v165, v165 row_mirror row_mask:0xf bank_mask:0xf
	v_add_f32_dpp v166, v166, v166 row_mirror row_mask:0xf bank_mask:0xf
	v_add_f32_dpp v167, v167, v167 row_mirror row_mask:0xf bank_mask:0xf
	v_add_f32_dpp v168, v168, v168 row_mirror row_mask:0xf bank_mask:0xf
	v_add_f32_dpp v169, v169, v169 row_mirror row_mask:0xf bank_mask:0xf
	v_mov_b32_e32 v170, v162
	v_mov_b32_e32 v171, v163
	v_mov_b32_e32 v172, v164
	v_mov_b32_e32 v173, v165
	v_mov_b32_e32 v174, v166
	v_mov_b32_e32 v175, v167
	v_mov_b32_e32 v176, v168
	v_mov_b32_e32 v177, v169
	v_permlane16_swap_b32 v170, v162
	v_permlane16_swap_b32 v171, v163
	v_permlane16_swap_b32 v172, v164
	v_permlane16_swap_b32 v173, v165
	v_permlane16_swap_b32 v174, v166
	v_permlane16_swap_b32 v175, v167
	v_permlane16_swap_b32 v176, v168
	v_permlane16_swap_b32 v177, v169
	v_add_f32_e32 v162, v162, v170
	v_add_f32_e32 v163, v163, v171
	v_add_f32_e32 v164, v164, v172
	v_add_f32_e32 v165, v165, v173
	v_add_f32_e32 v166, v166, v174
	v_add_f32_e32 v167, v167, v175
	v_add_f32_e32 v168, v168, v176
	v_add_f32_e32 v169, v169, v177
	v_mov_b32_e32 v170, v162
	v_mov_b32_e32 v171, v163
	v_mov_b32_e32 v172, v164
	v_mov_b32_e32 v173, v165
	v_mov_b32_e32 v174, v166
	v_mov_b32_e32 v175, v167
	v_mov_b32_e32 v176, v168
	v_mov_b32_e32 v177, v169
	v_permlane32_swap_b32 v170, v162
	v_permlane32_swap_b32 v171, v163
	v_permlane32_swap_b32 v172, v164
	v_permlane32_swap_b32 v173, v165
	v_permlane32_swap_b32 v174, v166
	v_permlane32_swap_b32 v175, v167
	v_permlane32_swap_b32 v176, v168
	v_permlane32_swap_b32 v177, v169
	v_add_f32_e32 v162, v162, v170
	v_add_f32_e32 v163, v163, v171
	v_add_f32_e32 v164, v164, v172
	v_add_f32_e32 v165, v165, v173
	v_add_f32_e32 v166, v166, v174
	v_add_f32_e32 v167, v167, v175
	v_add_f32_e32 v168, v168, v176
	v_add_f32_e32 v169, v169, v177
	s_mov_b64 exec, 1
	v_mov_b32_e32 v222, v162
	s_mov_b64 exec, 2
	v_mov_b32_e32 v222, v163
	s_mov_b64 exec, 4
	v_mov_b32_e32 v222, v164
	s_mov_b64 exec, 8
	v_mov_b32_e32 v222, v165
	s_mov_b64 exec, 16
	v_mov_b32_e32 v222, v166
	s_mov_b64 exec, 32
	v_mov_b32_e32 v222, v167
	s_mov_b64 exec, 64
	v_mov_b32_e32 v222, v168
	s_mov_b64 exec, 0x80
	v_mov_b32_e32 v222, v169
	s_mov_b64 exec, 0xff
	v_add_f32_e32 v223, v222, v196
	v_mul_f32_e64 v225, |v223|, s24
	v_exp_f32_e32 v210, v225
	v_min_f32_e32 v225, 0, v223
	s_nop 0
	v_add_f32_e32 v211, 1.0, v210
	v_add_f32_e32 v212, -1.0, v211
	v_frexp_mant_f32_e32 v213, v211
	v_cvt_f64_f32_e32 v[208:209], v211
	v_sub_f32_e32 v214, v212, v211
	v_frexp_exp_i32_f64_e32 v208, v[208:209]
	v_cmp_gt_f32_e32 vcc, s25, v213
	v_sub_f32_e32 v212, v210, v212
	v_add_f32_e32 v209, 1.0, v214
	v_subbrev_co_u32_e32 v208, vcc, 0, v208, vcc
	v_add_f32_e32 v209, v212, v209
	v_sub_u32_e32 v212, 0, v208
	v_cvt_f32_i32_e32 v208, v208
	v_ldexp_f32 v211, v211, v212
	v_ldexp_f32 v209, v209, v212
	v_add_f32_e32 v212, -1.0, v211
	v_add_f32_e32 v213, 1.0, v211
	v_add_f32_e32 v214, 1.0, v212
	v_add_f32_e32 v215, -1.0, v213
	v_sub_f32_e32 v214, v211, v214
	v_sub_f32_e32 v211, v211, v215
	v_mul_f32_e32 v215, 0x3f317218, v208
	v_add_f32_e32 v214, v209, v214
	v_add_f32_e32 v209, v209, v211
	v_fma_f32 v211, v208, s28, -v215
	v_add_f32_e32 v216, v212, v214
	v_add_f32_e32 v217, v213, v209
	v_fmac_f32_e32 v211, 0xb102e308, v208
	v_sub_f32_e32 v208, v216, v212
	v_sub_f32_e32 v212, v217, v213
	v_rcp_f32_e32 v213, v217
	v_add_f32_e32 v218, v215, v211
	v_sub_f32_e32 v209, v209, v212
	v_sub_f32_e32 v212, v218, v215
	v_sub_f32_e32 v211, v211, v212
	v_mul_f32_e32 v212, v216, v213
	v_sub_f32_e32 v208, v214, v208
	v_mul_f32_e32 v214, v217, v212
	v_fma_f32 v215, v212, v217, -v214
	v_fmac_f32_e32 v215, v212, v209
	v_add_f32_e32 v219, v214, v215
	v_sub_f32_e32 v220, v216, v219
	v_sub_f32_e32 v214, v219, v214
	v_sub_f32_e32 v216, v216, v220
	v_sub_f32_e32 v214, v214, v215
	v_sub_f32_e32 v215, v216, v219
	v_add_f32_e32 v208, v208, v215
	v_add_f32_e32 v208, v214, v208
	v_add_f32_e32 v214, v220, v208
	v_mul_f32_e32 v215, v213, v214
	v_sub_f32_e32 v216, v220, v214
	v_mul_f32_e32 v219, v217, v215
	v_add_f32_e32 v208, v208, v216
	v_add_f32_e32 v216, v212, v215
	v_fma_f32 v217, v215, v217, -v219
	v_sub_f32_e32 v212, v216, v212
	v_fmac_f32_e32 v217, v215, v209
	v_sub_f32_e32 v209, v215, v212
	v_add_f32_e32 v212, v219, v217
	v_sub_f32_e32 v215, v212, v219
	v_sub_f32_e32 v219, v214, v212
	v_sub_f32_e32 v214, v214, v219
	v_sub_f32_e32 v212, v214, v212
	v_sub_f32_e32 v215, v215, v217
	v_add_f32_e32 v208, v208, v212
	v_add_f32_e32 v208, v215, v208
	v_add_f32_e32 v208, v219, v208
	v_mul_f32_e32 v208, v213, v208
	v_add_f32_e32 v208, v209, v208
	v_add_f32_e32 v209, v216, v208
	v_mul_f32_e32 v212, v209, v209
	v_fmamk_f32 v215, v212, 0x3e9b6dac, v242
	v_sub_f32_e32 v213, v209, v216
	v_ldexp_f32 v214, v209, 1
	v_mul_f32_e32 v209, v209, v212
	v_fmaak_f32 v212, v212, v215, 0x3f2aaada
	v_mul_f32_e32 v209, v209, v212
	v_add_f32_e32 v212, v214, v209
	v_sub_f32_e32 v208, v208, v213
	v_sub_f32_e32 v213, v212, v214
	v_ldexp_f32 v208, v208, 1
	v_sub_f32_e32 v209, v209, v213
	v_add_f32_e32 v208, v208, v209
	v_add_f32_e32 v209, v212, v208
	v_sub_f32_e32 v212, v209, v212
	v_add_f32_e32 v213, v218, v209
	v_sub_f32_e32 v208, v208, v212
	v_sub_f32_e32 v212, v213, v218
	v_sub_f32_e32 v214, v213, v212
	v_sub_f32_e32 v209, v209, v212
	v_add_f32_e32 v212, v211, v208
	v_sub_f32_e32 v214, v218, v214
	v_sub_f32_e32 v215, v212, v211
	v_add_f32_e32 v209, v209, v214
	v_sub_f32_e32 v214, v212, v215
	v_sub_f32_e32 v208, v208, v215
	v_sub_f32_e32 v211, v211, v214
	v_add_f32_e32 v209, v212, v209
	v_add_f32_e32 v208, v208, v211
	v_add_f32_e32 v211, v213, v209
	v_sub_f32_e32 v212, v211, v213
	v_sub_f32_e32 v209, v209, v212
	v_add_f32_e32 v208, v208, v209
	v_add_f32_e32 v208, v211, v208
	v_cmp_neq_f32_e32 vcc, s29, v210
	s_nop 0
	s_nop 0
	v_cndmask_b32_e32 v208, v243, v208, vcc
	v_cmp_ngt_f32_e32 vcc, -1.0, v210
	s_nop 1
	v_cndmask_b32_e32 v208, v244, v208, vcc
	v_cmp_neq_f32_e32 vcc, -1.0, v210
	s_nop 1
	v_cndmask_b32_e32 v208, v245, v208, vcc
	v_cmp_lt_f32_e64 vcc, |v210|, s30
	s_nop 1
	v_cndmask_b32_e32 v208, v208, v210, vcc
	v_sub_f32_e32 v225, v225, v208
	global_store_dword v195, v225, s[74:75]
	s_mov_b64 exec, -1
	v_add_u32_e32 v195, 0x2000, v195
	s_waitcnt vmcnt(18)
	v_pk_mul_f32 v[198:199], v[66:67], v[66:67]
	v_pk_mul_f32 v[200:201], v[68:69], v[68:69]
	v_pk_fma_f32 v[198:199], v[70:71], v[70:71], v[198:199]
	v_pk_fma_f32 v[200:201], v[72:73], v[72:73], v[200:201]
	v_pk_fma_f32 v[198:199], v[74:75], v[74:75], v[198:199]
	v_pk_fma_f32 v[200:201], v[76:77], v[76:77], v[200:201]
	v_pk_fma_f32 v[198:199], v[78:79], v[78:79], v[198:199]
	v_pk_fma_f32 v[200:201], v[80:81], v[80:81], v[200:201]
	v_pk_fma_f32 v[198:199], v[82:83], v[82:83], v[198:199]
	v_pk_fma_f32 v[200:201], v[84:85], v[84:85], v[200:201]
	v_pk_fma_f32 v[198:199], v[86:87], v[86:87], v[198:199]
	v_pk_fma_f32 v[200:201], v[88:89], v[88:89], v[200:201]
	v_pk_fma_f32 v[198:199], v[90:91], v[90:91], v[198:199]
	v_pk_fma_f32 v[200:201], v[92:93], v[92:93], v[200:201]
	v_pk_fma_f32 v[198:199], v[94:95], v[94:95], v[198:199]
	v_pk_fma_f32 v[200:201], v[96:97], v[96:97], v[200:201]
	v_pk_add_f32 v[198:199], v[198:199], v[200:201]
	v_add_f32_e32 v198, v198, v199
	s_nop 1
	v_add_f32_dpp v198, v198, v198 quad_perm:[1,0,3,2] row_mask:0xf bank_mask:0xf
	s_nop 1
	v_add_f32_dpp v198, v198, v198 quad_perm:[2,3,0,1] row_mask:0xf bank_mask:0xf
	s_nop 1
	v_add_f32_dpp v198, v198, v198 row_half_mirror row_mask:0xf bank_mask:0xf
	s_nop 1
	v_add_f32_dpp v198, v198, v198 row_mirror row_mask:0xf bank_mask:0xf
	v_mov_b32_e32 v199, v198
	s_nop 1
	v_permlane16_swap_b32 v199, v198
	v_add_f32_e32 v198, v198, v199
	v_mov_b32_e32 v199, v198
	s_nop 1
	v_permlane32_swap_b32 v199, v198
	v_add_f32_e32 v198, v198, v199
	ds_read_b128 v[130:133], v192
	ds_read_b128 v[134:137], v192 offset:1024
	ds_read_b128 v[138:141], v192 offset:2048
	ds_read_b128 v[142:145], v192 offset:3072
	ds_read_b128 v[146:149], v192 offset:4096
	ds_read_b128 v[150:153], v192 offset:5120
	ds_read_b128 v[154:157], v192 offset:6144
	ds_read_b128 v[158:161], v192 offset:7168
	v_fmamk_f32 v198, v198, 0x3a000000, v241
	v_mul_f32_e32 v199, 0x4b800000, v198
	v_cmp_gt_f32_e32 vcc, s17, v198
	s_nop 1
	v_cndmask_b32_e32 v198, v198, v199, vcc
	v_rsq_f32_e32 v198, v198
	s_nop 0
	v_mul_f32_e32 v199, 0x45800000, v198
	v_cndmask_b32_e32 v202, v198, v199, vcc
	v_pk_mul_f32 v[98:99], v[66:67], v[202:203] op_sel_hi:[1,0]
	v_pk_mul_f32 v[98:99], v[2:3], v[98:99]
	v_pk_mul_f32 v[100:101], v[68:69], v[202:203] op_sel_hi:[1,0]
	v_pk_mul_f32 v[100:101], v[4:5], v[100:101]
	v_cvt_pk_bf16_f32 v206, v98, v99
	v_cvt_pk_bf16_f32 v207, v100, v101
	global_store_dwordx2 v194, v[206:207], s[52:53]
	v_pk_mul_f32 v[102:103], v[70:71], v[202:203] op_sel_hi:[1,0]
	v_pk_mul_f32 v[102:103], v[6:7], v[102:103]
	v_pk_mul_f32 v[104:105], v[72:73], v[202:203] op_sel_hi:[1,0]
	v_pk_mul_f32 v[104:105], v[8:9], v[104:105]
	v_cvt_pk_bf16_f32 v206, v102, v103
	v_cvt_pk_bf16_f32 v207, v104, v105
	global_store_dwordx2 v194, v[206:207], s[52:53] offset:512
	v_pk_mul_f32 v[106:107], v[74:75], v[202:203] op_sel_hi:[1,0]
	v_pk_mul_f32 v[106:107], v[10:11], v[106:107]
	v_pk_mul_f32 v[108:109], v[76:77], v[202:203] op_sel_hi:[1,0]
	v_pk_mul_f32 v[108:109], v[12:13], v[108:109]
	v_cvt_pk_bf16_f32 v206, v106, v107
	v_cvt_pk_bf16_f32 v207, v108, v109
	global_store_dwordx2 v194, v[206:207], s[52:53] offset:1024
	v_pk_mul_f32 v[110:111], v[78:79], v[202:203] op_sel_hi:[1,0]
	v_pk_mul_f32 v[110:111], v[14:15], v[110:111]
	v_pk_mul_f32 v[112:113], v[80:81], v[202:203] op_sel_hi:[1,0]
	v_pk_mul_f32 v[112:113], v[16:17], v[112:113]
	v_cvt_pk_bf16_f32 v206, v110, v111
	v_cvt_pk_bf16_f32 v207, v112, v113
	global_store_dwordx2 v194, v[206:207], s[52:53] offset:1536
	v_pk_mul_f32 v[114:115], v[82:83], v[202:203] op_sel_hi:[1,0]
	v_pk_mul_f32 v[114:115], v[18:19], v[114:115]
	v_pk_mul_f32 v[116:117], v[84:85], v[202:203] op_sel_hi:[1,0]
	v_pk_mul_f32 v[116:117], v[20:21], v[116:117]
	v_cvt_pk_bf16_f32 v206, v114, v115
	v_cvt_pk_bf16_f32 v207, v116, v117
	global_store_dwordx2 v194, v[206:207], s[52:53] offset:2048
	v_pk_mul_f32 v[118:119], v[86:87], v[202:203] op_sel_hi:[1,0]
	v_pk_mul_f32 v[118:119], v[22:23], v[118:119]
	v_pk_mul_f32 v[120:121], v[88:89], v[202:203] op_sel_hi:[1,0]
	v_pk_mul_f32 v[120:121], v[24:25], v[120:121]
	v_cvt_pk_bf16_f32 v206, v118, v119
	v_cvt_pk_bf16_f32 v207, v120, v121
	global_store_dwordx2 v194, v[206:207], s[52:53] offset:2560
	v_pk_mul_f32 v[122:123], v[90:91], v[202:203] op_sel_hi:[1,0]
	v_pk_mul_f32 v[122:123], v[26:27], v[122:123]
	v_pk_mul_f32 v[124:125], v[92:93], v[202:203] op_sel_hi:[1,0]
	v_pk_mul_f32 v[124:125], v[28:29], v[124:125]
	v_cvt_pk_bf16_f32 v206, v122, v123
	v_cvt_pk_bf16_f32 v207, v124, v125
	global_store_dwordx2 v194, v[206:207], s[52:53] offset:3072
	v_pk_mul_f32 v[126:127], v[94:95], v[202:203] op_sel_hi:[1,0]
	v_pk_mul_f32 v[126:127], v[30:31], v[126:127]
	v_pk_mul_f32 v[128:129], v[96:97], v[202:203] op_sel_hi:[1,0]
	v_pk_mul_f32 v[128:129], v[32:33], v[128:129]
	v_cvt_pk_bf16_f32 v206, v126, v127
	v_cvt_pk_bf16_f32 v207, v128, v129
	global_store_dwordx2 v194, v[206:207], s[52:53] offset:3584
	v_add_u32_e32 v194, 0x800000, v194
	global_load_dwordx4 v[66:69], v193, s[12:13] offset:-4096 nt
	global_load_dwordx4 v[70:73], v193, s[12:13] offset:-3072 nt
	global_load_dwordx4 v[74:77], v193, s[12:13] offset:-2048 nt
	global_load_dwordx4 v[78:81], v193, s[12:13] offset:-1024 nt
	global_load_dwordx4 v[82:85], v193, s[12:13] offset:0 nt
	global_load_dwordx4 v[86:89], v193, s[12:13] offset:1024 nt
	global_load_dwordx4 v[90:93], v193, s[12:13] offset:2048 nt
	global_load_dwordx4 v[94:97], v193, s[12:13] offset:3072 nt
	v_add_u32_e32 v193, s0, v193
	s_waitcnt lgkmcnt(6)
	v_pk_mul_f32 v[162:163], v[130:131], v[98:99] op_sel_hi:[1,0]
	v_pk_mul_f32 v[164:165], v[132:133], v[98:99] op_sel_hi:[1,0]
	v_pk_mul_f32 v[166:167], v[134:135], v[98:99] op_sel_hi:[1,0]
	v_pk_mul_f32 v[168:169], v[136:137], v[98:99] op_sel_hi:[1,0]
	ds_read_b128 v[130:133], v192 offset:8192
	ds_read_b128 v[134:137], v192 offset:9216
	s_waitcnt lgkmcnt(6)
	v_pk_fma_f32 v[162:163], v[138:139], v[98:99], v[162:163] op_sel:[0,1,0] op_sel_hi:[1,1,1]
	v_pk_fma_f32 v[164:165], v[140:141], v[98:99], v[164:165] op_sel:[0,1,0] op_sel_hi:[1,1,1]
	v_pk_fma_f32 v[166:167], v[142:143], v[98:99], v[166:167] op_sel:[0,1,0] op_sel_hi:[1,1,1]
	v_pk_fma_f32 v[168:169], v[144:145], v[98:99], v[168:169] op_sel:[0,1,0] op_sel_hi:[1,1,1]
	ds_read_b128 v[138:141], v192 offset:10240
	ds_read_b128 v[142:145], v192 offset:11264
	s_waitcnt lgkmcnt(6)
	v_pk_fma_f32 v[162:163], v[146:147], v[100:101], v[162:163] op_sel_hi:[1,0,1]
	v_pk_fma_f32 v[164:165], v[148:149], v[100:101], v[164:165] op_sel_hi:[1,0,1]
	v_pk_fma_f32 v[166:167], v[150:151], v[100:101], v[166:167] op_sel_hi:[1,0,1]
	v_pk_fma_f32 v[168:169], v[152:153], v[100:101], v[168:169] op_sel_hi:[1,0,1]
	ds_read_b128 v[146:149], v192 offset:12288
	ds_read_b128 v[150:153], v192 offset:13312
	s_waitcnt lgkmcnt(6)
	v_pk_fma_f32 v[162:163], v[154:155], v[100:101], v[162:163] op_sel:[0,1,0] op_sel_hi:[1,1,1]
	v_pk_fma_f32 v[164:165], v[156:157], v[100:101], v[164:165] op_sel:[0,1,0] op_sel_hi:[1,1,1]
	v_pk_fma_f32 v[166:167], v[158:159], v[100:101], v[166:167] op_sel:[0,1,0] op_sel_hi:[1,1,1]
	v_pk_fma_f32 v[168:169], v[160:161], v[100:101], v[168:169] op_sel:[0,1,0] op_sel_hi:[1,1,1]
	ds_read_b128 v[154:157], v192 offset:14336
	ds_read_b128 v[158:161], v192 offset:15360
	s_waitcnt lgkmcnt(6)
	v_pk_fma_f32 v[162:163], v[130:131], v[102:103], v[162:163] op_sel_hi:[1,0,1]
	v_pk_fma_f32 v[164:165], v[132:133], v[102:103], v[164:165] op_sel_hi:[1,0,1]
	v_pk_fma_f32 v[166:167], v[134:135], v[102:103], v[166:167] op_sel_hi:[1,0,1]
	v_pk_fma_f32 v[168:169], v[136:137], v[102:103], v[168:169] op_sel_hi:[1,0,1]
	ds_read_b128 v[130:133], v192 offset:16384
	ds_read_b128 v[134:137], v192 offset:17408
	s_waitcnt lgkmcnt(6)
	v_pk_fma_f32 v[162:163], v[138:139], v[102:103], v[162:163] op_sel:[0,1,0] op_sel_hi:[1,1,1]
	v_pk_fma_f32 v[164:165], v[140:141], v[102:103], v[164:165] op_sel:[0,1,0] op_sel_hi:[1,1,1]
	v_pk_fma_f32 v[166:167], v[142:143], v[102:103], v[166:167] op_sel:[0,1,0] op_sel_hi:[1,1,1]
	v_pk_fma_f32 v[168:169], v[144:145], v[102:103], v[168:169] op_sel:[0,1,0] op_sel_hi:[1,1,1]
	ds_read_b128 v[138:141], v192 offset:18432
	ds_read_b128 v[142:145], v192 offset:19456
	s_waitcnt lgkmcnt(6)
	v_pk_fma_f32 v[162:163], v[146:147], v[104:105], v[162:163] op_sel_hi:[1,0,1]
	v_pk_fma_f32 v[164:165], v[148:149], v[104:105], v[164:165] op_sel_hi:[1,0,1]
	v_pk_fma_f32 v[166:167], v[150:151], v[104:105], v[166:167] op_sel_hi:[1,0,1]
	v_pk_fma_f32 v[168:169], v[152:153], v[104:105], v[168:169] op_sel_hi:[1,0,1]
	ds_read_b128 v[146:149], v192 offset:20480
	ds_read_b128 v[150:153], v192 offset:21504
	s_waitcnt lgkmcnt(6)
	v_pk_fma_f32 v[162:163], v[154:155], v[104:105], v[162:163] op_sel:[0,1,0] op_sel_hi:[1,1,1]
	v_pk_fma_f32 v[164:165], v[156:157], v[104:105], v[164:165] op_sel:[0,1,0] op_sel_hi:[1,1,1]
	v_pk_fma_f32 v[166:167], v[158:159], v[104:105], v[166:167] op_sel:[0,1,0] op_sel_hi:[1,1,1]
	v_pk_fma_f32 v[168:169], v[160:161], v[104:105], v[168:169] op_sel:[0,1,0] op_sel_hi:[1,1,1]
	ds_read_b128 v[154:157], v192 offset:22528
	ds_read_b128 v[158:161], v192 offset:23552
	s_waitcnt lgkmcnt(6)
	v_pk_fma_f32 v[162:163], v[130:131], v[106:107], v[162:163] op_sel_hi:[1,0,1]
	v_pk_fma_f32 v[164:165], v[132:133], v[106:107], v[164:165] op_sel_hi:[1,0,1]
	v_pk_fma_f32 v[166:167], v[134:135], v[106:107], v[166:167] op_sel_hi:[1,0,1]
	v_pk_fma_f32 v[168:169], v[136:137], v[106:107], v[168:169] op_sel_hi:[1,0,1]
	ds_read_b128 v[130:133], v192 offset:24576
	ds_read_b128 v[134:137], v192 offset:25600
	s_waitcnt lgkmcnt(6)
	v_pk_fma_f32 v[162:163], v[138:139], v[106:107], v[162:163] op_sel:[0,1,0] op_sel_hi:[1,1,1]
	v_pk_fma_f32 v[164:165], v[140:141], v[106:107], v[164:165] op_sel:[0,1,0] op_sel_hi:[1,1,1]
	v_pk_fma_f32 v[166:167], v[142:143], v[106:107], v[166:167] op_sel:[0,1,0] op_sel_hi:[1,1,1]
	v_pk_fma_f32 v[168:169], v[144:145], v[106:107], v[168:169] op_sel:[0,1,0] op_sel_hi:[1,1,1]
	ds_read_b128 v[138:141], v192 offset:26624
	ds_read_b128 v[142:145], v192 offset:27648
	s_waitcnt lgkmcnt(6)
	v_pk_fma_f32 v[162:163], v[146:147], v[108:109], v[162:163] op_sel_hi:[1,0,1]
	v_pk_fma_f32 v[164:165], v[148:149], v[108:109], v[164:165] op_sel_hi:[1,0,1]
	v_pk_fma_f32 v[166:167], v[150:151], v[108:109], v[166:167] op_sel_hi:[1,0,1]
	v_pk_fma_f32 v[168:169], v[152:153], v[108:109], v[168:169] op_sel_hi:[1,0,1]
	ds_read_b128 v[146:149], v192 offset:28672
	ds_read_b128 v[150:153], v192 offset:29696
	s_waitcnt lgkmcnt(6)
	v_pk_fma_f32 v[162:163], v[154:155], v[108:109], v[162:163] op_sel:[0,1,0] op_sel_hi:[1,1,1]
	v_pk_fma_f32 v[164:165], v[156:157], v[108:109], v[164:165] op_sel:[0,1,0] op_sel_hi:[1,1,1]
	v_pk_fma_f32 v[166:167], v[158:159], v[108:109], v[166:167] op_sel:[0,1,0] op_sel_hi:[1,1,1]
	v_pk_fma_f32 v[168:169], v[160:161], v[108:109], v[168:169] op_sel:[0,1,0] op_sel_hi:[1,1,1]
	ds_read_b128 v[154:157], v192 offset:30720
	ds_read_b128 v[158:161], v192 offset:31744
	s_waitcnt lgkmcnt(6)
	v_pk_fma_f32 v[162:163], v[130:131], v[110:111], v[162:163] op_sel_hi:[1,0,1]
	v_pk_fma_f32 v[164:165], v[132:133], v[110:111], v[164:165] op_sel_hi:[1,0,1]
	v_pk_fma_f32 v[166:167], v[134:135], v[110:111], v[166:167] op_sel_hi:[1,0,1]
	v_pk_fma_f32 v[168:169], v[136:137], v[110:111], v[168:169] op_sel_hi:[1,0,1]
	ds_read_b128 v[130:133], v192 offset:32768
	ds_read_b128 v[134:137], v192 offset:33792
	s_waitcnt lgkmcnt(6)
	v_pk_fma_f32 v[162:163], v[138:139], v[110:111], v[162:163] op_sel:[0,1,0] op_sel_hi:[1,1,1]
	v_pk_fma_f32 v[164:165], v[140:141], v[110:111], v[164:165] op_sel:[0,1,0] op_sel_hi:[1,1,1]
	v_pk_fma_f32 v[166:167], v[142:143], v[110:111], v[166:167] op_sel:[0,1,0] op_sel_hi:[1,1,1]
	v_pk_fma_f32 v[168:169], v[144:145], v[110:111], v[168:169] op_sel:[0,1,0] op_sel_hi:[1,1,1]
	ds_read_b128 v[138:141], v192 offset:34816
	ds_read_b128 v[142:145], v192 offset:35840
	s_waitcnt lgkmcnt(6)
	v_pk_fma_f32 v[162:163], v[146:147], v[112:113], v[162:163] op_sel_hi:[1,0,1]
	v_pk_fma_f32 v[164:165], v[148:149], v[112:113], v[164:165] op_sel_hi:[1,0,1]
	v_pk_fma_f32 v[166:167], v[150:151], v[112:113], v[166:167] op_sel_hi:[1,0,1]
	v_pk_fma_f32 v[168:169], v[152:153], v[112:113], v[168:169] op_sel_hi:[1,0,1]
	ds_read_b128 v[146:149], v192 offset:36864
	ds_read_b128 v[150:153], v192 offset:37888
	s_waitcnt lgkmcnt(6)
	v_pk_fma_f32 v[162:163], v[154:155], v[112:113], v[162:163] op_sel:[0,1,0] op_sel_hi:[1,1,1]
	v_pk_fma_f32 v[164:165], v[156:157], v[112:113], v[164:165] op_sel:[0,1,0] op_sel_hi:[1,1,1]
	v_pk_fma_f32 v[166:167], v[158:159], v[112:113], v[166:167] op_sel:[0,1,0] op_sel_hi:[1,1,1]
	v_pk_fma_f32 v[168:169], v[160:161], v[112:113], v[168:169] op_sel:[0,1,0] op_sel_hi:[1,1,1]
	ds_read_b128 v[154:157], v192 offset:38912
	ds_read_b128 v[158:161], v192 offset:39936
	s_waitcnt lgkmcnt(6)
	v_pk_fma_f32 v[162:163], v[130:131], v[114:115], v[162:163] op_sel_hi:[1,0,1]
	v_pk_fma_f32 v[164:165], v[132:133], v[114:115], v[164:165] op_sel_hi:[1,0,1]
	v_pk_fma_f32 v[166:167], v[134:135], v[114:115], v[166:167] op_sel_hi:[1,0,1]
	v_pk_fma_f32 v[168:169], v[136:137], v[114:115], v[168:169] op_sel_hi:[1,0,1]
	ds_read_b128 v[130:133], v192 offset:40960
	ds_read_b128 v[134:137], v192 offset:41984
	s_waitcnt lgkmcnt(6)
	v_pk_fma_f32 v[162:163], v[138:139], v[114:115], v[162:163] op_sel:[0,1,0] op_sel_hi:[1,1,1]
	v_pk_fma_f32 v[164:165], v[140:141], v[114:115], v[164:165] op_sel:[0,1,0] op_sel_hi:[1,1,1]
	v_pk_fma_f32 v[166:167], v[142:143], v[114:115], v[166:167] op_sel:[0,1,0] op_sel_hi:[1,1,1]
	v_pk_fma_f32 v[168:169], v[144:145], v[114:115], v[168:169] op_sel:[0,1,0] op_sel_hi:[1,1,1]
	ds_read_b128 v[138:141], v192 offset:43008
	ds_read_b128 v[142:145], v192 offset:44032
	s_waitcnt lgkmcnt(6)
	v_pk_fma_f32 v[162:163], v[146:147], v[116:117], v[162:163] op_sel_hi:[1,0,1]
	v_pk_fma_f32 v[164:165], v[148:149], v[116:117], v[164:165] op_sel_hi:[1,0,1]
	v_pk_fma_f32 v[166:167], v[150:151], v[116:117], v[166:167] op_sel_hi:[1,0,1]
	v_pk_fma_f32 v[168:169], v[152:153], v[116:117], v[168:169] op_sel_hi:[1,0,1]
	ds_read_b128 v[146:149], v192 offset:45056
	ds_read_b128 v[150:153], v192 offset:46080
	s_waitcnt lgkmcnt(6)
	v_pk_fma_f32 v[162:163], v[154:155], v[116:117], v[162:163] op_sel:[0,1,0] op_sel_hi:[1,1,1]
	v_pk_fma_f32 v[164:165], v[156:157], v[116:117], v[164:165] op_sel:[0,1,0] op_sel_hi:[1,1,1]
	v_pk_fma_f32 v[166:167], v[158:159], v[116:117], v[166:167] op_sel:[0,1,0] op_sel_hi:[1,1,1]
	v_pk_fma_f32 v[168:169], v[160:161], v[116:117], v[168:169] op_sel:[0,1,0] op_sel_hi:[1,1,1]
	ds_read_b128 v[154:157], v192 offset:47104
	ds_read_b128 v[158:161], v192 offset:48128
	s_waitcnt lgkmcnt(6)
	v_pk_fma_f32 v[162:163], v[130:131], v[118:119], v[162:163] op_sel_hi:[1,0,1]
	v_pk_fma_f32 v[164:165], v[132:133], v[118:119], v[164:165] op_sel_hi:[1,0,1]
	v_pk_fma_f32 v[166:167], v[134:135], v[118:119], v[166:167] op_sel_hi:[1,0,1]
	v_pk_fma_f32 v[168:169], v[136:137], v[118:119], v[168:169] op_sel_hi:[1,0,1]
	ds_read_b128 v[130:133], v192 offset:49152
	ds_read_b128 v[134:137], v192 offset:50176
	s_waitcnt lgkmcnt(6)
	v_pk_fma_f32 v[162:163], v[138:139], v[118:119], v[162:163] op_sel:[0,1,0] op_sel_hi:[1,1,1]
	v_pk_fma_f32 v[164:165], v[140:141], v[118:119], v[164:165] op_sel:[0,1,0] op_sel_hi:[1,1,1]
	v_pk_fma_f32 v[166:167], v[142:143], v[118:119], v[166:167] op_sel:[0,1,0] op_sel_hi:[1,1,1]
	v_pk_fma_f32 v[168:169], v[144:145], v[118:119], v[168:169] op_sel:[0,1,0] op_sel_hi:[1,1,1]
	ds_read_b128 v[138:141], v192 offset:51200
	ds_read_b128 v[142:145], v192 offset:52224
	s_waitcnt lgkmcnt(6)
	v_pk_fma_f32 v[162:163], v[146:147], v[120:121], v[162:163] op_sel_hi:[1,0,1]
	v_pk_fma_f32 v[164:165], v[148:149], v[120:121], v[164:165] op_sel_hi:[1,0,1]
	v_pk_fma_f32 v[166:167], v[150:151], v[120:121], v[166:167] op_sel_hi:[1,0,1]
	v_pk_fma_f32 v[168:169], v[152:153], v[120:121], v[168:169] op_sel_hi:[1,0,1]
	ds_read_b128 v[146:149], v192 offset:53248
	ds_read_b128 v[150:153], v192 offset:54272
	s_waitcnt lgkmcnt(6)
	v_pk_fma_f32 v[162:163], v[154:155], v[120:121], v[162:163] op_sel:[0,1,0] op_sel_hi:[1,1,1]
	v_pk_fma_f32 v[164:165], v[156:157], v[120:121], v[164:165] op_sel:[0,1,0] op_sel_hi:[1,1,1]
	v_pk_fma_f32 v[166:167], v[158:159], v[120:121], v[166:167] op_sel:[0,1,0] op_sel_hi:[1,1,1]
	v_pk_fma_f32 v[168:169], v[160:161], v[120:121], v[168:169] op_sel:[0,1,0] op_sel_hi:[1,1,1]
	ds_read_b128 v[154:157], v192 offset:55296
	ds_read_b128 v[158:161], v192 offset:56320
	s_waitcnt lgkmcnt(6)
	v_pk_fma_f32 v[162:163], v[130:131], v[122:123], v[162:163] op_sel_hi:[1,0,1]
	v_pk_fma_f32 v[164:165], v[132:133], v[122:123], v[164:165] op_sel_hi:[1,0,1]
	v_pk_fma_f32 v[166:167], v[134:135], v[122:123], v[166:167] op_sel_hi:[1,0,1]
	v_pk_fma_f32 v[168:169], v[136:137], v[122:123], v[168:169] op_sel_hi:[1,0,1]
	ds_read_b128 v[130:133], v192 offset:57344
	ds_read_b128 v[134:137], v192 offset:58368
	s_waitcnt lgkmcnt(6)
	v_pk_fma_f32 v[162:163], v[138:139], v[122:123], v[162:163] op_sel:[0,1,0] op_sel_hi:[1,1,1]
	v_pk_fma_f32 v[164:165], v[140:141], v[122:123], v[164:165] op_sel:[0,1,0] op_sel_hi:[1,1,1]
	v_pk_fma_f32 v[166:167], v[142:143], v[122:123], v[166:167] op_sel:[0,1,0] op_sel_hi:[1,1,1]
	v_pk_fma_f32 v[168:169], v[144:145], v[122:123], v[168:169] op_sel:[0,1,0] op_sel_hi:[1,1,1]
	ds_read_b128 v[138:141], v192 offset:59392
	ds_read_b128 v[142:145], v192 offset:60416
	s_waitcnt lgkmcnt(6)
	v_pk_fma_f32 v[162:163], v[146:147], v[124:125], v[162:163] op_sel_hi:[1,0,1]
	v_pk_fma_f32 v[164:165], v[148:149], v[124:125], v[164:165] op_sel_hi:[1,0,1]
	v_pk_fma_f32 v[166:167], v[150:151], v[124:125], v[166:167] op_sel_hi:[1,0,1]
	v_pk_fma_f32 v[168:169], v[152:153], v[124:125], v[168:169] op_sel_hi:[1,0,1]
	ds_read_b128 v[146:149], v192 offset:61440
	ds_read_b128 v[150:153], v192 offset:62464
	s_waitcnt lgkmcnt(6)
	v_pk_fma_f32 v[162:163], v[154:155], v[124:125], v[162:163] op_sel:[0,1,0] op_sel_hi:[1,1,1]
	v_pk_fma_f32 v[164:165], v[156:157], v[124:125], v[164:165] op_sel:[0,1,0] op_sel_hi:[1,1,1]
	v_pk_fma_f32 v[166:167], v[158:159], v[124:125], v[166:167] op_sel:[0,1,0] op_sel_hi:[1,1,1]
	v_pk_fma_f32 v[168:169], v[160:161], v[124:125], v[168:169] op_sel:[0,1,0] op_sel_hi:[1,1,1]
	ds_read_b128 v[154:157], v192 offset:63488
	ds_read_b128 v[158:161], v192 offset:64512
	s_waitcnt lgkmcnt(6)
	v_pk_fma_f32 v[162:163], v[130:131], v[126:127], v[162:163] op_sel_hi:[1,0,1]
	v_pk_fma_f32 v[164:165], v[132:133], v[126:127], v[164:165] op_sel_hi:[1,0,1]
	v_pk_fma_f32 v[166:167], v[134:135], v[126:127], v[166:167] op_sel_hi:[1,0,1]
	v_pk_fma_f32 v[168:169], v[136:137], v[126:127], v[168:169] op_sel_hi:[1,0,1]
	s_waitcnt lgkmcnt(4)
	v_pk_fma_f32 v[162:163], v[138:139], v[126:127], v[162:163] op_sel:[0,1,0] op_sel_hi:[1,1,1]
	v_pk_fma_f32 v[164:165], v[140:141], v[126:127], v[164:165] op_sel:[0,1,0] op_sel_hi:[1,1,1]
	v_pk_fma_f32 v[166:167], v[142:143], v[126:127], v[166:167] op_sel:[0,1,0] op_sel_hi:[1,1,1]
	v_pk_fma_f32 v[168:169], v[144:145], v[126:127], v[168:169] op_sel:[0,1,0] op_sel_hi:[1,1,1]
	s_waitcnt lgkmcnt(2)
	v_pk_fma_f32 v[162:163], v[146:147], v[128:129], v[162:163] op_sel_hi:[1,0,1]
	v_pk_fma_f32 v[164:165], v[148:149], v[128:129], v[164:165] op_sel_hi:[1,0,1]
	v_pk_fma_f32 v[166:167], v[150:151], v[128:129], v[166:167] op_sel_hi:[1,0,1]
	v_pk_fma_f32 v[168:169], v[152:153], v[128:129], v[168:169] op_sel_hi:[1,0,1]
	s_waitcnt lgkmcnt(0)
	v_pk_fma_f32 v[162:163], v[154:155], v[128:129], v[162:163] op_sel:[0,1,0] op_sel_hi:[1,1,1]
	v_pk_fma_f32 v[164:165], v[156:157], v[128:129], v[164:165] op_sel:[0,1,0] op_sel_hi:[1,1,1]
	v_pk_fma_f32 v[166:167], v[158:159], v[128:129], v[166:167] op_sel:[0,1,0] op_sel_hi:[1,1,1]
	v_pk_fma_f32 v[168:169], v[160:161], v[128:129], v[168:169] op_sel:[0,1,0] op_sel_hi:[1,1,1]
	s_nop 1
	v_add_f32_dpp v162, v162, v162 quad_perm:[1,0,3,2] row_mask:0xf bank_mask:0xf
	v_add_f32_dpp v163, v163, v163 quad_perm:[1,0,3,2] row_mask:0xf bank_mask:0xf
	v_add_f32_dpp v164, v164, v164 quad_perm:[1,0,3,2] row_mask:0xf bank_mask:0xf
	v_add_f32_dpp v165, v165, v165 quad_perm:[1,0,3,2] row_mask:0xf bank_mask:0xf
	v_add_f32_dpp v166, v166, v166 quad_perm:[1,0,3,2] row_mask:0xf bank_mask:0xf
	v_add_f32_dpp v167, v167, v167 quad_perm:[1,0,3,2] row_mask:0xf bank_mask:0xf
	v_add_f32_dpp v168, v168, v168 quad_perm:[1,0,3,2] row_mask:0xf bank_mask:0xf
	v_add_f32_dpp v169, v169, v169 quad_perm:[1,0,3,2] row_mask:0xf bank_mask:0xf
	v_add_f32_dpp v162, v162, v162 quad_perm:[2,3,0,1] row_mask:0xf bank_mask:0xf
	v_add_f32_dpp v163, v163, v163 quad_perm:[2,3,0,1] row_mask:0xf bank_mask:0xf
	v_add_f32_dpp v164, v164, v164 quad_perm:[2,3,0,1] row_mask:0xf bank_mask:0xf
	v_add_f32_dpp v165, v165, v165 quad_perm:[2,3,0,1] row_mask:0xf bank_mask:0xf
	v_add_f32_dpp v166, v166, v166 quad_perm:[2,3,0,1] row_mask:0xf bank_mask:0xf
	v_add_f32_dpp v167, v167, v167 quad_perm:[2,3,0,1] row_mask:0xf bank_mask:0xf
	v_add_f32_dpp v168, v168, v168 quad_perm:[2,3,0,1] row_mask:0xf bank_mask:0xf
	v_add_f32_dpp v169, v169, v169 quad_perm:[2,3,0,1] row_mask:0xf bank_mask:0xf
	v_add_f32_dpp v162, v162, v162 row_half_mirror row_mask:0xf bank_mask:0xf
	v_add_f32_dpp v163, v163, v163 row_half_mirror row_mask:0xf bank_mask:0xf
	v_add_f32_dpp v164, v164, v164 row_half_mirror row_mask:0xf bank_mask:0xf
	v_add_f32_dpp v165, v165, v165 row_half_mirror row_mask:0xf bank_mask:0xf
	v_add_f32_dpp v166, v166, v166 row_half_mirror row_mask:0xf bank_mask:0xf
	v_add_f32_dpp v167, v167, v167 row_half_mirror row_mask:0xf bank_mask:0xf
	v_add_f32_dpp v168, v168, v168 row_half_mirror row_mask:0xf bank_mask:0xf
	v_add_f32_dpp v169, v169, v169 row_half_mirror row_mask:0xf bank_mask:0xf
	v_add_f32_dpp v162, v162, v162 row_mirror row_mask:0xf bank_mask:0xf
	v_add_f32_dpp v163, v163, v163 row_mirror row_mask:0xf bank_mask:0xf
	v_add_f32_dpp v164, v164, v164 row_mirror row_mask:0xf bank_mask:0xf
	v_add_f32_dpp v165, v165, v165 row_mirror row_mask:0xf bank_mask:0xf
	v_add_f32_dpp v166, v166, v166 row_mirror row_mask:0xf bank_mask:0xf
	v_add_f32_dpp v167, v167, v167 row_mirror row_mask:0xf bank_mask:0xf
	v_add_f32_dpp v168, v168, v168 row_mirror row_mask:0xf bank_mask:0xf
	v_add_f32_dpp v169, v169, v169 row_mirror row_mask:0xf bank_mask:0xf
	v_mov_b32_e32 v170, v162
	v_mov_b32_e32 v171, v163
	v_mov_b32_e32 v172, v164
	v_mov_b32_e32 v173, v165
	v_mov_b32_e32 v174, v166
	v_mov_b32_e32 v175, v167
	v_mov_b32_e32 v176, v168
	v_mov_b32_e32 v177, v169
	v_permlane16_swap_b32 v170, v162
	v_permlane16_swap_b32 v171, v163
	v_permlane16_swap_b32 v172, v164
	v_permlane16_swap_b32 v173, v165
	v_permlane16_swap_b32 v174, v166
	v_permlane16_swap_b32 v175, v167
	v_permlane16_swap_b32 v176, v168
	v_permlane16_swap_b32 v177, v169
	v_add_f32_e32 v162, v162, v170
	v_add_f32_e32 v163, v163, v171
	v_add_f32_e32 v164, v164, v172
	v_add_f32_e32 v165, v165, v173
	v_add_f32_e32 v166, v166, v174
	v_add_f32_e32 v167, v167, v175
	v_add_f32_e32 v168, v168, v176
	v_add_f32_e32 v169, v169, v177
	v_mov_b32_e32 v170, v162
	v_mov_b32_e32 v171, v163
	v_mov_b32_e32 v172, v164
	v_mov_b32_e32 v173, v165
	v_mov_b32_e32 v174, v166
	v_mov_b32_e32 v175, v167
	v_mov_b32_e32 v176, v168
	v_mov_b32_e32 v177, v169
	v_permlane32_swap_b32 v170, v162
	v_permlane32_swap_b32 v171, v163
	v_permlane32_swap_b32 v172, v164
	v_permlane32_swap_b32 v173, v165
	v_permlane32_swap_b32 v174, v166
	v_permlane32_swap_b32 v175, v167
	v_permlane32_swap_b32 v176, v168
	v_permlane32_swap_b32 v177, v169
	v_add_f32_e32 v162, v162, v170
	v_add_f32_e32 v163, v163, v171
	v_add_f32_e32 v164, v164, v172
	v_add_f32_e32 v165, v165, v173
	v_add_f32_e32 v166, v166, v174
	v_add_f32_e32 v167, v167, v175
	v_add_f32_e32 v168, v168, v176
	v_add_f32_e32 v169, v169, v177
	s_mov_b64 exec, 1
	v_mov_b32_e32 v222, v162
	s_mov_b64 exec, 2
	v_mov_b32_e32 v222, v163
	s_mov_b64 exec, 4
	v_mov_b32_e32 v222, v164
	s_mov_b64 exec, 8
	v_mov_b32_e32 v222, v165
	s_mov_b64 exec, 16
	v_mov_b32_e32 v222, v166
	s_mov_b64 exec, 32
	v_mov_b32_e32 v222, v167
	s_mov_b64 exec, 64
	v_mov_b32_e32 v222, v168
	s_mov_b64 exec, 0x80
	v_mov_b32_e32 v222, v169
	s_mov_b64 exec, 0xff
	v_add_f32_e32 v223, v222, v196
	v_mul_f32_e64 v225, |v223|, s24
	v_exp_f32_e32 v210, v225
	v_min_f32_e32 v225, 0, v223
	s_nop 0
	v_add_f32_e32 v211, 1.0, v210
	v_add_f32_e32 v212, -1.0, v211
	v_frexp_mant_f32_e32 v213, v211
	v_cvt_f64_f32_e32 v[208:209], v211
	v_sub_f32_e32 v214, v212, v211
	v_frexp_exp_i32_f64_e32 v208, v[208:209]
	v_cmp_gt_f32_e32 vcc, s25, v213
	v_sub_f32_e32 v212, v210, v212
	v_add_f32_e32 v209, 1.0, v214
	v_subbrev_co_u32_e32 v208, vcc, 0, v208, vcc
	v_add_f32_e32 v209, v212, v209
	v_sub_u32_e32 v212, 0, v208
	v_cvt_f32_i32_e32 v208, v208
	v_ldexp_f32 v211, v211, v212
	v_ldexp_f32 v209, v209, v212
	v_add_f32_e32 v212, -1.0, v211
	v_add_f32_e32 v213, 1.0, v211
	v_add_f32_e32 v214, 1.0, v212
	v_add_f32_e32 v215, -1.0, v213
	v_sub_f32_e32 v214, v211, v214
	v_sub_f32_e32 v211, v211, v215
	v_mul_f32_e32 v215, 0x3f317218, v208
	v_add_f32_e32 v214, v209, v214
	v_add_f32_e32 v209, v209, v211
	v_fma_f32 v211, v208, s28, -v215
	v_add_f32_e32 v216, v212, v214
	v_add_f32_e32 v217, v213, v209
	v_fmac_f32_e32 v211, 0xb102e308, v208
	v_sub_f32_e32 v208, v216, v212
	v_sub_f32_e32 v212, v217, v213
	v_rcp_f32_e32 v213, v217
	v_add_f32_e32 v218, v215, v211
	v_sub_f32_e32 v209, v209, v212
	v_sub_f32_e32 v212, v218, v215
	v_sub_f32_e32 v211, v211, v212
	v_mul_f32_e32 v212, v216, v213
	v_sub_f32_e32 v208, v214, v208
	v_mul_f32_e32 v214, v217, v212
	v_fma_f32 v215, v212, v217, -v214
	v_fmac_f32_e32 v215, v212, v209
	v_add_f32_e32 v219, v214, v215
	v_sub_f32_e32 v220, v216, v219
	v_sub_f32_e32 v214, v219, v214
	v_sub_f32_e32 v216, v216, v220
	v_sub_f32_e32 v214, v214, v215
	v_sub_f32_e32 v215, v216, v219
	v_add_f32_e32 v208, v208, v215
	v_add_f32_e32 v208, v214, v208
	v_add_f32_e32 v214, v220, v208
	v_mul_f32_e32 v215, v213, v214
	v_sub_f32_e32 v216, v220, v214
	v_mul_f32_e32 v219, v217, v215
	v_add_f32_e32 v208, v208, v216
	v_add_f32_e32 v216, v212, v215
	v_fma_f32 v217, v215, v217, -v219
	v_sub_f32_e32 v212, v216, v212
	v_fmac_f32_e32 v217, v215, v209
	v_sub_f32_e32 v209, v215, v212
	v_add_f32_e32 v212, v219, v217
	v_sub_f32_e32 v215, v212, v219
	v_sub_f32_e32 v219, v214, v212
	v_sub_f32_e32 v214, v214, v219
	v_sub_f32_e32 v212, v214, v212
	v_sub_f32_e32 v215, v215, v217
	v_add_f32_e32 v208, v208, v212
	v_add_f32_e32 v208, v215, v208
	v_add_f32_e32 v208, v219, v208
	v_mul_f32_e32 v208, v213, v208
	v_add_f32_e32 v208, v209, v208
	v_add_f32_e32 v209, v216, v208
	v_mul_f32_e32 v212, v209, v209
	v_fmamk_f32 v215, v212, 0x3e9b6dac, v242
	v_sub_f32_e32 v213, v209, v216
	v_ldexp_f32 v214, v209, 1
	v_mul_f32_e32 v209, v209, v212
	v_fmaak_f32 v212, v212, v215, 0x3f2aaada
	v_mul_f32_e32 v209, v209, v212
	v_add_f32_e32 v212, v214, v209
	v_sub_f32_e32 v208, v208, v213
	v_sub_f32_e32 v213, v212, v214
	v_ldexp_f32 v208, v208, 1
	v_sub_f32_e32 v209, v209, v213
	v_add_f32_e32 v208, v208, v209
	v_add_f32_e32 v209, v212, v208
	v_sub_f32_e32 v212, v209, v212
	v_add_f32_e32 v213, v218, v209
	v_sub_f32_e32 v208, v208, v212
	v_sub_f32_e32 v212, v213, v218
	v_sub_f32_e32 v214, v213, v212
	v_sub_f32_e32 v209, v209, v212
	v_add_f32_e32 v212, v211, v208
	v_sub_f32_e32 v214, v218, v214
	v_sub_f32_e32 v215, v212, v211
	v_add_f32_e32 v209, v209, v214
	v_sub_f32_e32 v214, v212, v215
	v_sub_f32_e32 v208, v208, v215
	v_sub_f32_e32 v211, v211, v214
	v_add_f32_e32 v209, v212, v209
	v_add_f32_e32 v208, v208, v211
	v_add_f32_e32 v211, v213, v209
	v_sub_f32_e32 v212, v211, v213
	v_sub_f32_e32 v209, v209, v212
	v_add_f32_e32 v208, v208, v209
	v_add_f32_e32 v208, v211, v208
	v_cmp_neq_f32_e32 vcc, s29, v210
	s_nop 0
	s_nop 0
	v_cndmask_b32_e32 v208, v243, v208, vcc
	v_cmp_ngt_f32_e32 vcc, -1.0, v210
	s_nop 1
	v_cndmask_b32_e32 v208, v244, v208, vcc
	v_cmp_neq_f32_e32 vcc, -1.0, v210
	s_nop 1
	v_cndmask_b32_e32 v208, v245, v208, vcc
	v_cmp_lt_f32_e64 vcc, |v210|, s30
	s_nop 1
	v_cndmask_b32_e32 v208, v208, v210, vcc
	v_sub_f32_e32 v225, v225, v208
	global_store_dword v195, v225, s[74:75]
	s_mov_b64 exec, -1
	v_add_u32_e32 v195, 0x3a000, v195
	s_waitcnt vmcnt(18)
	v_pk_mul_f32 v[198:199], v[34:35], v[34:35]
	v_pk_mul_f32 v[200:201], v[36:37], v[36:37]
	v_pk_fma_f32 v[198:199], v[38:39], v[38:39], v[198:199]
	v_pk_fma_f32 v[200:201], v[40:41], v[40:41], v[200:201]
	v_pk_fma_f32 v[198:199], v[42:43], v[42:43], v[198:199]
	v_pk_fma_f32 v[200:201], v[44:45], v[44:45], v[200:201]
	v_pk_fma_f32 v[198:199], v[46:47], v[46:47], v[198:199]
	v_pk_fma_f32 v[200:201], v[48:49], v[48:49], v[200:201]
	v_pk_fma_f32 v[198:199], v[50:51], v[50:51], v[198:199]
	v_pk_fma_f32 v[200:201], v[52:53], v[52:53], v[200:201]
	v_pk_fma_f32 v[198:199], v[54:55], v[54:55], v[198:199]
	v_pk_fma_f32 v[200:201], v[56:57], v[56:57], v[200:201]
	v_pk_fma_f32 v[198:199], v[58:59], v[58:59], v[198:199]
	v_pk_fma_f32 v[200:201], v[60:61], v[60:61], v[200:201]
	v_pk_fma_f32 v[198:199], v[62:63], v[62:63], v[198:199]
	v_pk_fma_f32 v[200:201], v[64:65], v[64:65], v[200:201]
	v_pk_add_f32 v[198:199], v[198:199], v[200:201]
	v_add_f32_e32 v198, v198, v199
	s_nop 1
	v_add_f32_dpp v198, v198, v198 quad_perm:[1,0,3,2] row_mask:0xf bank_mask:0xf
	s_nop 1
	v_add_f32_dpp v198, v198, v198 quad_perm:[2,3,0,1] row_mask:0xf bank_mask:0xf
	s_nop 1
	v_add_f32_dpp v198, v198, v198 row_half_mirror row_mask:0xf bank_mask:0xf
	s_nop 1
	v_add_f32_dpp v198, v198, v198 row_mirror row_mask:0xf bank_mask:0xf
	v_mov_b32_e32 v199, v198
	s_nop 1
	v_permlane16_swap_b32 v199, v198
	v_add_f32_e32 v198, v198, v199
	v_mov_b32_e32 v199, v198
	s_nop 1
	v_permlane32_swap_b32 v199, v198
	v_add_f32_e32 v198, v198, v199
	ds_read_b128 v[130:133], v192
	ds_read_b128 v[134:137], v192 offset:1024
	ds_read_b128 v[138:141], v192 offset:2048
	ds_read_b128 v[142:145], v192 offset:3072
	ds_read_b128 v[146:149], v192 offset:4096
	ds_read_b128 v[150:153], v192 offset:5120
	ds_read_b128 v[154:157], v192 offset:6144
	ds_read_b128 v[158:161], v192 offset:7168
	v_fmamk_f32 v198, v198, 0x3a000000, v241
	v_mul_f32_e32 v199, 0x4b800000, v198
	v_cmp_gt_f32_e32 vcc, s17, v198
	s_nop 1
	v_cndmask_b32_e32 v198, v198, v199, vcc
	v_rsq_f32_e32 v198, v198
	s_nop 0
	v_mul_f32_e32 v199, 0x45800000, v198
	v_cndmask_b32_e32 v202, v198, v199, vcc
	v_pk_mul_f32 v[98:99], v[34:35], v[202:203] op_sel_hi:[1,0]
	v_pk_mul_f32 v[98:99], v[2:3], v[98:99]
	v_pk_mul_f32 v[100:101], v[36:37], v[202:203] op_sel_hi:[1,0]
	v_pk_mul_f32 v[100:101], v[4:5], v[100:101]
	v_cvt_pk_bf16_f32 v206, v98, v99
	v_cvt_pk_bf16_f32 v207, v100, v101
	global_store_dwordx2 v194, v[206:207], s[52:53]
	v_pk_mul_f32 v[102:103], v[38:39], v[202:203] op_sel_hi:[1,0]
	v_pk_mul_f32 v[102:103], v[6:7], v[102:103]
	v_pk_mul_f32 v[104:105], v[40:41], v[202:203] op_sel_hi:[1,0]
	v_pk_mul_f32 v[104:105], v[8:9], v[104:105]
	v_cvt_pk_bf16_f32 v206, v102, v103
	v_cvt_pk_bf16_f32 v207, v104, v105
	global_store_dwordx2 v194, v[206:207], s[52:53] offset:512
	v_pk_mul_f32 v[106:107], v[42:43], v[202:203] op_sel_hi:[1,0]
	v_pk_mul_f32 v[106:107], v[10:11], v[106:107]
	v_pk_mul_f32 v[108:109], v[44:45], v[202:203] op_sel_hi:[1,0]
	v_pk_mul_f32 v[108:109], v[12:13], v[108:109]
	v_cvt_pk_bf16_f32 v206, v106, v107
	v_cvt_pk_bf16_f32 v207, v108, v109
	global_store_dwordx2 v194, v[206:207], s[52:53] offset:1024
	v_pk_mul_f32 v[110:111], v[46:47], v[202:203] op_sel_hi:[1,0]
	v_pk_mul_f32 v[110:111], v[14:15], v[110:111]
	v_pk_mul_f32 v[112:113], v[48:49], v[202:203] op_sel_hi:[1,0]
	v_pk_mul_f32 v[112:113], v[16:17], v[112:113]
	v_cvt_pk_bf16_f32 v206, v110, v111
	v_cvt_pk_bf16_f32 v207, v112, v113
	global_store_dwordx2 v194, v[206:207], s[52:53] offset:1536
	v_pk_mul_f32 v[114:115], v[50:51], v[202:203] op_sel_hi:[1,0]
	v_pk_mul_f32 v[114:115], v[18:19], v[114:115]
	v_pk_mul_f32 v[116:117], v[52:53], v[202:203] op_sel_hi:[1,0]
	v_pk_mul_f32 v[116:117], v[20:21], v[116:117]
	v_cvt_pk_bf16_f32 v206, v114, v115
	v_cvt_pk_bf16_f32 v207, v116, v117
	global_store_dwordx2 v194, v[206:207], s[52:53] offset:2048
	v_pk_mul_f32 v[118:119], v[54:55], v[202:203] op_sel_hi:[1,0]
	v_pk_mul_f32 v[118:119], v[22:23], v[118:119]
	v_pk_mul_f32 v[120:121], v[56:57], v[202:203] op_sel_hi:[1,0]
	v_pk_mul_f32 v[120:121], v[24:25], v[120:121]
	v_cvt_pk_bf16_f32 v206, v118, v119
	v_cvt_pk_bf16_f32 v207, v120, v121
	global_store_dwordx2 v194, v[206:207], s[52:53] offset:2560
	v_pk_mul_f32 v[122:123], v[58:59], v[202:203] op_sel_hi:[1,0]
	v_pk_mul_f32 v[122:123], v[26:27], v[122:123]
	v_pk_mul_f32 v[124:125], v[60:61], v[202:203] op_sel_hi:[1,0]
	v_pk_mul_f32 v[124:125], v[28:29], v[124:125]
	v_cvt_pk_bf16_f32 v206, v122, v123
	v_cvt_pk_bf16_f32 v207, v124, v125
	global_store_dwordx2 v194, v[206:207], s[52:53] offset:3072
	v_pk_mul_f32 v[126:127], v[62:63], v[202:203] op_sel_hi:[1,0]
	v_pk_mul_f32 v[126:127], v[30:31], v[126:127]
	v_pk_mul_f32 v[128:129], v[64:65], v[202:203] op_sel_hi:[1,0]
	v_pk_mul_f32 v[128:129], v[32:33], v[128:129]
	v_cvt_pk_bf16_f32 v206, v126, v127
	v_cvt_pk_bf16_f32 v207, v128, v129
	global_store_dwordx2 v194, v[206:207], s[52:53] offset:3584
	v_add_u32_e32 v194, 0x800000, v194
	global_load_dwordx4 v[34:37], v193, s[12:13] offset:-4096 nt
	global_load_dwordx4 v[38:41], v193, s[12:13] offset:-3072 nt
	global_load_dwordx4 v[42:45], v193, s[12:13] offset:-2048 nt
	global_load_dwordx4 v[46:49], v193, s[12:13] offset:-1024 nt
	global_load_dwordx4 v[50:53], v193, s[12:13] offset:0 nt
	global_load_dwordx4 v[54:57], v193, s[12:13] offset:1024 nt
	global_load_dwordx4 v[58:61], v193, s[12:13] offset:2048 nt
	global_load_dwordx4 v[62:65], v193, s[12:13] offset:3072 nt
	v_add_u32_e32 v193, s0, v193
	s_waitcnt lgkmcnt(6)
	v_pk_mul_f32 v[162:163], v[130:131], v[98:99] op_sel_hi:[1,0]
	v_pk_mul_f32 v[164:165], v[132:133], v[98:99] op_sel_hi:[1,0]
	v_pk_mul_f32 v[166:167], v[134:135], v[98:99] op_sel_hi:[1,0]
	v_pk_mul_f32 v[168:169], v[136:137], v[98:99] op_sel_hi:[1,0]
	ds_read_b128 v[130:133], v192 offset:8192
	ds_read_b128 v[134:137], v192 offset:9216
	s_waitcnt lgkmcnt(6)
	v_pk_fma_f32 v[162:163], v[138:139], v[98:99], v[162:163] op_sel:[0,1,0] op_sel_hi:[1,1,1]
	v_pk_fma_f32 v[164:165], v[140:141], v[98:99], v[164:165] op_sel:[0,1,0] op_sel_hi:[1,1,1]
	v_pk_fma_f32 v[166:167], v[142:143], v[98:99], v[166:167] op_sel:[0,1,0] op_sel_hi:[1,1,1]
	v_pk_fma_f32 v[168:169], v[144:145], v[98:99], v[168:169] op_sel:[0,1,0] op_sel_hi:[1,1,1]
	ds_read_b128 v[138:141], v192 offset:10240
	ds_read_b128 v[142:145], v192 offset:11264
	s_waitcnt lgkmcnt(6)
	v_pk_fma_f32 v[162:163], v[146:147], v[100:101], v[162:163] op_sel_hi:[1,0,1]
	v_pk_fma_f32 v[164:165], v[148:149], v[100:101], v[164:165] op_sel_hi:[1,0,1]
	v_pk_fma_f32 v[166:167], v[150:151], v[100:101], v[166:167] op_sel_hi:[1,0,1]
	v_pk_fma_f32 v[168:169], v[152:153], v[100:101], v[168:169] op_sel_hi:[1,0,1]
	ds_read_b128 v[146:149], v192 offset:12288
	ds_read_b128 v[150:153], v192 offset:13312
	s_waitcnt lgkmcnt(6)
	v_pk_fma_f32 v[162:163], v[154:155], v[100:101], v[162:163] op_sel:[0,1,0] op_sel_hi:[1,1,1]
	v_pk_fma_f32 v[164:165], v[156:157], v[100:101], v[164:165] op_sel:[0,1,0] op_sel_hi:[1,1,1]
	v_pk_fma_f32 v[166:167], v[158:159], v[100:101], v[166:167] op_sel:[0,1,0] op_sel_hi:[1,1,1]
	v_pk_fma_f32 v[168:169], v[160:161], v[100:101], v[168:169] op_sel:[0,1,0] op_sel_hi:[1,1,1]
	ds_read_b128 v[154:157], v192 offset:14336
	ds_read_b128 v[158:161], v192 offset:15360
	s_waitcnt lgkmcnt(6)
	v_pk_fma_f32 v[162:163], v[130:131], v[102:103], v[162:163] op_sel_hi:[1,0,1]
	v_pk_fma_f32 v[164:165], v[132:133], v[102:103], v[164:165] op_sel_hi:[1,0,1]
	v_pk_fma_f32 v[166:167], v[134:135], v[102:103], v[166:167] op_sel_hi:[1,0,1]
	v_pk_fma_f32 v[168:169], v[136:137], v[102:103], v[168:169] op_sel_hi:[1,0,1]
	ds_read_b128 v[130:133], v192 offset:16384
	ds_read_b128 v[134:137], v192 offset:17408
	s_waitcnt lgkmcnt(6)
	v_pk_fma_f32 v[162:163], v[138:139], v[102:103], v[162:163] op_sel:[0,1,0] op_sel_hi:[1,1,1]
	v_pk_fma_f32 v[164:165], v[140:141], v[102:103], v[164:165] op_sel:[0,1,0] op_sel_hi:[1,1,1]
	v_pk_fma_f32 v[166:167], v[142:143], v[102:103], v[166:167] op_sel:[0,1,0] op_sel_hi:[1,1,1]
	v_pk_fma_f32 v[168:169], v[144:145], v[102:103], v[168:169] op_sel:[0,1,0] op_sel_hi:[1,1,1]
	ds_read_b128 v[138:141], v192 offset:18432
	ds_read_b128 v[142:145], v192 offset:19456
	s_waitcnt lgkmcnt(6)
	v_pk_fma_f32 v[162:163], v[146:147], v[104:105], v[162:163] op_sel_hi:[1,0,1]
	v_pk_fma_f32 v[164:165], v[148:149], v[104:105], v[164:165] op_sel_hi:[1,0,1]
	v_pk_fma_f32 v[166:167], v[150:151], v[104:105], v[166:167] op_sel_hi:[1,0,1]
	v_pk_fma_f32 v[168:169], v[152:153], v[104:105], v[168:169] op_sel_hi:[1,0,1]
	ds_read_b128 v[146:149], v192 offset:20480
	ds_read_b128 v[150:153], v192 offset:21504
	s_waitcnt lgkmcnt(6)
	v_pk_fma_f32 v[162:163], v[154:155], v[104:105], v[162:163] op_sel:[0,1,0] op_sel_hi:[1,1,1]
	v_pk_fma_f32 v[164:165], v[156:157], v[104:105], v[164:165] op_sel:[0,1,0] op_sel_hi:[1,1,1]
	v_pk_fma_f32 v[166:167], v[158:159], v[104:105], v[166:167] op_sel:[0,1,0] op_sel_hi:[1,1,1]
	v_pk_fma_f32 v[168:169], v[160:161], v[104:105], v[168:169] op_sel:[0,1,0] op_sel_hi:[1,1,1]
	ds_read_b128 v[154:157], v192 offset:22528
	ds_read_b128 v[158:161], v192 offset:23552
	s_waitcnt lgkmcnt(6)
	v_pk_fma_f32 v[162:163], v[130:131], v[106:107], v[162:163] op_sel_hi:[1,0,1]
	v_pk_fma_f32 v[164:165], v[132:133], v[106:107], v[164:165] op_sel_hi:[1,0,1]
	v_pk_fma_f32 v[166:167], v[134:135], v[106:107], v[166:167] op_sel_hi:[1,0,1]
	v_pk_fma_f32 v[168:169], v[136:137], v[106:107], v[168:169] op_sel_hi:[1,0,1]
	ds_read_b128 v[130:133], v192 offset:24576
	ds_read_b128 v[134:137], v192 offset:25600
	s_waitcnt lgkmcnt(6)
	v_pk_fma_f32 v[162:163], v[138:139], v[106:107], v[162:163] op_sel:[0,1,0] op_sel_hi:[1,1,1]
	v_pk_fma_f32 v[164:165], v[140:141], v[106:107], v[164:165] op_sel:[0,1,0] op_sel_hi:[1,1,1]
	v_pk_fma_f32 v[166:167], v[142:143], v[106:107], v[166:167] op_sel:[0,1,0] op_sel_hi:[1,1,1]
	v_pk_fma_f32 v[168:169], v[144:145], v[106:107], v[168:169] op_sel:[0,1,0] op_sel_hi:[1,1,1]
	ds_read_b128 v[138:141], v192 offset:26624
	ds_read_b128 v[142:145], v192 offset:27648
	s_waitcnt lgkmcnt(6)
	v_pk_fma_f32 v[162:163], v[146:147], v[108:109], v[162:163] op_sel_hi:[1,0,1]
	v_pk_fma_f32 v[164:165], v[148:149], v[108:109], v[164:165] op_sel_hi:[1,0,1]
	v_pk_fma_f32 v[166:167], v[150:151], v[108:109], v[166:167] op_sel_hi:[1,0,1]
	v_pk_fma_f32 v[168:169], v[152:153], v[108:109], v[168:169] op_sel_hi:[1,0,1]
	ds_read_b128 v[146:149], v192 offset:28672
	ds_read_b128 v[150:153], v192 offset:29696
	s_waitcnt lgkmcnt(6)
	v_pk_fma_f32 v[162:163], v[154:155], v[108:109], v[162:163] op_sel:[0,1,0] op_sel_hi:[1,1,1]
	v_pk_fma_f32 v[164:165], v[156:157], v[108:109], v[164:165] op_sel:[0,1,0] op_sel_hi:[1,1,1]
	v_pk_fma_f32 v[166:167], v[158:159], v[108:109], v[166:167] op_sel:[0,1,0] op_sel_hi:[1,1,1]
	v_pk_fma_f32 v[168:169], v[160:161], v[108:109], v[168:169] op_sel:[0,1,0] op_sel_hi:[1,1,1]
	ds_read_b128 v[154:157], v192 offset:30720
	ds_read_b128 v[158:161], v192 offset:31744
	s_waitcnt lgkmcnt(6)
	v_pk_fma_f32 v[162:163], v[130:131], v[110:111], v[162:163] op_sel_hi:[1,0,1]
	v_pk_fma_f32 v[164:165], v[132:133], v[110:111], v[164:165] op_sel_hi:[1,0,1]
	v_pk_fma_f32 v[166:167], v[134:135], v[110:111], v[166:167] op_sel_hi:[1,0,1]
	v_pk_fma_f32 v[168:169], v[136:137], v[110:111], v[168:169] op_sel_hi:[1,0,1]
	ds_read_b128 v[130:133], v192 offset:32768
	ds_read_b128 v[134:137], v192 offset:33792
	s_waitcnt lgkmcnt(6)
	v_pk_fma_f32 v[162:163], v[138:139], v[110:111], v[162:163] op_sel:[0,1,0] op_sel_hi:[1,1,1]
	v_pk_fma_f32 v[164:165], v[140:141], v[110:111], v[164:165] op_sel:[0,1,0] op_sel_hi:[1,1,1]
	v_pk_fma_f32 v[166:167], v[142:143], v[110:111], v[166:167] op_sel:[0,1,0] op_sel_hi:[1,1,1]
	v_pk_fma_f32 v[168:169], v[144:145], v[110:111], v[168:169] op_sel:[0,1,0] op_sel_hi:[1,1,1]
	ds_read_b128 v[138:141], v192 offset:34816
	ds_read_b128 v[142:145], v192 offset:35840
	s_waitcnt lgkmcnt(6)
	v_pk_fma_f32 v[162:163], v[146:147], v[112:113], v[162:163] op_sel_hi:[1,0,1]
	v_pk_fma_f32 v[164:165], v[148:149], v[112:113], v[164:165] op_sel_hi:[1,0,1]
	v_pk_fma_f32 v[166:167], v[150:151], v[112:113], v[166:167] op_sel_hi:[1,0,1]
	v_pk_fma_f32 v[168:169], v[152:153], v[112:113], v[168:169] op_sel_hi:[1,0,1]
	ds_read_b128 v[146:149], v192 offset:36864
	ds_read_b128 v[150:153], v192 offset:37888
	s_waitcnt lgkmcnt(6)
	v_pk_fma_f32 v[162:163], v[154:155], v[112:113], v[162:163] op_sel:[0,1,0] op_sel_hi:[1,1,1]
	v_pk_fma_f32 v[164:165], v[156:157], v[112:113], v[164:165] op_sel:[0,1,0] op_sel_hi:[1,1,1]
	v_pk_fma_f32 v[166:167], v[158:159], v[112:113], v[166:167] op_sel:[0,1,0] op_sel_hi:[1,1,1]
	v_pk_fma_f32 v[168:169], v[160:161], v[112:113], v[168:169] op_sel:[0,1,0] op_sel_hi:[1,1,1]
	ds_read_b128 v[154:157], v192 offset:38912
	ds_read_b128 v[158:161], v192 offset:39936
	s_waitcnt lgkmcnt(6)
	v_pk_fma_f32 v[162:163], v[130:131], v[114:115], v[162:163] op_sel_hi:[1,0,1]
	v_pk_fma_f32 v[164:165], v[132:133], v[114:115], v[164:165] op_sel_hi:[1,0,1]
	v_pk_fma_f32 v[166:167], v[134:135], v[114:115], v[166:167] op_sel_hi:[1,0,1]
	v_pk_fma_f32 v[168:169], v[136:137], v[114:115], v[168:169] op_sel_hi:[1,0,1]
	ds_read_b128 v[130:133], v192 offset:40960
	ds_read_b128 v[134:137], v192 offset:41984
	s_waitcnt lgkmcnt(6)
	v_pk_fma_f32 v[162:163], v[138:139], v[114:115], v[162:163] op_sel:[0,1,0] op_sel_hi:[1,1,1]
	v_pk_fma_f32 v[164:165], v[140:141], v[114:115], v[164:165] op_sel:[0,1,0] op_sel_hi:[1,1,1]
	v_pk_fma_f32 v[166:167], v[142:143], v[114:115], v[166:167] op_sel:[0,1,0] op_sel_hi:[1,1,1]
	v_pk_fma_f32 v[168:169], v[144:145], v[114:115], v[168:169] op_sel:[0,1,0] op_sel_hi:[1,1,1]
	ds_read_b128 v[138:141], v192 offset:43008
	ds_read_b128 v[142:145], v192 offset:44032
	s_waitcnt lgkmcnt(6)
	v_pk_fma_f32 v[162:163], v[146:147], v[116:117], v[162:163] op_sel_hi:[1,0,1]
	v_pk_fma_f32 v[164:165], v[148:149], v[116:117], v[164:165] op_sel_hi:[1,0,1]
	v_pk_fma_f32 v[166:167], v[150:151], v[116:117], v[166:167] op_sel_hi:[1,0,1]
	v_pk_fma_f32 v[168:169], v[152:153], v[116:117], v[168:169] op_sel_hi:[1,0,1]
	ds_read_b128 v[146:149], v192 offset:45056
	ds_read_b128 v[150:153], v192 offset:46080
	s_waitcnt lgkmcnt(6)
	v_pk_fma_f32 v[162:163], v[154:155], v[116:117], v[162:163] op_sel:[0,1,0] op_sel_hi:[1,1,1]
	v_pk_fma_f32 v[164:165], v[156:157], v[116:117], v[164:165] op_sel:[0,1,0] op_sel_hi:[1,1,1]
	v_pk_fma_f32 v[166:167], v[158:159], v[116:117], v[166:167] op_sel:[0,1,0] op_sel_hi:[1,1,1]
	v_pk_fma_f32 v[168:169], v[160:161], v[116:117], v[168:169] op_sel:[0,1,0] op_sel_hi:[1,1,1]
	ds_read_b128 v[154:157], v192 offset:47104
	ds_read_b128 v[158:161], v192 offset:48128
	s_waitcnt lgkmcnt(6)
	v_pk_fma_f32 v[162:163], v[130:131], v[118:119], v[162:163] op_sel_hi:[1,0,1]
	v_pk_fma_f32 v[164:165], v[132:133], v[118:119], v[164:165] op_sel_hi:[1,0,1]
	v_pk_fma_f32 v[166:167], v[134:135], v[118:119], v[166:167] op_sel_hi:[1,0,1]
	v_pk_fma_f32 v[168:169], v[136:137], v[118:119], v[168:169] op_sel_hi:[1,0,1]
	ds_read_b128 v[130:133], v192 offset:49152
	ds_read_b128 v[134:137], v192 offset:50176
	s_waitcnt lgkmcnt(6)
	v_pk_fma_f32 v[162:163], v[138:139], v[118:119], v[162:163] op_sel:[0,1,0] op_sel_hi:[1,1,1]
	v_pk_fma_f32 v[164:165], v[140:141], v[118:119], v[164:165] op_sel:[0,1,0] op_sel_hi:[1,1,1]
	v_pk_fma_f32 v[166:167], v[142:143], v[118:119], v[166:167] op_sel:[0,1,0] op_sel_hi:[1,1,1]
	v_pk_fma_f32 v[168:169], v[144:145], v[118:119], v[168:169] op_sel:[0,1,0] op_sel_hi:[1,1,1]
	ds_read_b128 v[138:141], v192 offset:51200
	ds_read_b128 v[142:145], v192 offset:52224
	s_waitcnt lgkmcnt(6)
	v_pk_fma_f32 v[162:163], v[146:147], v[120:121], v[162:163] op_sel_hi:[1,0,1]
	v_pk_fma_f32 v[164:165], v[148:149], v[120:121], v[164:165] op_sel_hi:[1,0,1]
	v_pk_fma_f32 v[166:167], v[150:151], v[120:121], v[166:167] op_sel_hi:[1,0,1]
	v_pk_fma_f32 v[168:169], v[152:153], v[120:121], v[168:169] op_sel_hi:[1,0,1]
	ds_read_b128 v[146:149], v192 offset:53248
	ds_read_b128 v[150:153], v192 offset:54272
	s_waitcnt lgkmcnt(6)
	v_pk_fma_f32 v[162:163], v[154:155], v[120:121], v[162:163] op_sel:[0,1,0] op_sel_hi:[1,1,1]
	v_pk_fma_f32 v[164:165], v[156:157], v[120:121], v[164:165] op_sel:[0,1,0] op_sel_hi:[1,1,1]
	v_pk_fma_f32 v[166:167], v[158:159], v[120:121], v[166:167] op_sel:[0,1,0] op_sel_hi:[1,1,1]
	v_pk_fma_f32 v[168:169], v[160:161], v[120:121], v[168:169] op_sel:[0,1,0] op_sel_hi:[1,1,1]
	ds_read_b128 v[154:157], v192 offset:55296
	ds_read_b128 v[158:161], v192 offset:56320
	s_waitcnt lgkmcnt(6)
	v_pk_fma_f32 v[162:163], v[130:131], v[122:123], v[162:163] op_sel_hi:[1,0,1]
	v_pk_fma_f32 v[164:165], v[132:133], v[122:123], v[164:165] op_sel_hi:[1,0,1]
	v_pk_fma_f32 v[166:167], v[134:135], v[122:123], v[166:167] op_sel_hi:[1,0,1]
	v_pk_fma_f32 v[168:169], v[136:137], v[122:123], v[168:169] op_sel_hi:[1,0,1]
	ds_read_b128 v[130:133], v192 offset:57344
	ds_read_b128 v[134:137], v192 offset:58368
	s_waitcnt lgkmcnt(6)
	v_pk_fma_f32 v[162:163], v[138:139], v[122:123], v[162:163] op_sel:[0,1,0] op_sel_hi:[1,1,1]
	v_pk_fma_f32 v[164:165], v[140:141], v[122:123], v[164:165] op_sel:[0,1,0] op_sel_hi:[1,1,1]
	v_pk_fma_f32 v[166:167], v[142:143], v[122:123], v[166:167] op_sel:[0,1,0] op_sel_hi:[1,1,1]
	v_pk_fma_f32 v[168:169], v[144:145], v[122:123], v[168:169] op_sel:[0,1,0] op_sel_hi:[1,1,1]
	ds_read_b128 v[138:141], v192 offset:59392
	ds_read_b128 v[142:145], v192 offset:60416
	s_waitcnt lgkmcnt(6)
	v_pk_fma_f32 v[162:163], v[146:147], v[124:125], v[162:163] op_sel_hi:[1,0,1]
	v_pk_fma_f32 v[164:165], v[148:149], v[124:125], v[164:165] op_sel_hi:[1,0,1]
	v_pk_fma_f32 v[166:167], v[150:151], v[124:125], v[166:167] op_sel_hi:[1,0,1]
	v_pk_fma_f32 v[168:169], v[152:153], v[124:125], v[168:169] op_sel_hi:[1,0,1]
	ds_read_b128 v[146:149], v192 offset:61440
	ds_read_b128 v[150:153], v192 offset:62464
	s_waitcnt lgkmcnt(6)
	v_pk_fma_f32 v[162:163], v[154:155], v[124:125], v[162:163] op_sel:[0,1,0] op_sel_hi:[1,1,1]
	v_pk_fma_f32 v[164:165], v[156:157], v[124:125], v[164:165] op_sel:[0,1,0] op_sel_hi:[1,1,1]
	v_pk_fma_f32 v[166:167], v[158:159], v[124:125], v[166:167] op_sel:[0,1,0] op_sel_hi:[1,1,1]
	v_pk_fma_f32 v[168:169], v[160:161], v[124:125], v[168:169] op_sel:[0,1,0] op_sel_hi:[1,1,1]
	ds_read_b128 v[154:157], v192 offset:63488
	ds_read_b128 v[158:161], v192 offset:64512
	s_waitcnt lgkmcnt(6)
	v_pk_fma_f32 v[162:163], v[130:131], v[126:127], v[162:163] op_sel_hi:[1,0,1]
	v_pk_fma_f32 v[164:165], v[132:133], v[126:127], v[164:165] op_sel_hi:[1,0,1]
	v_pk_fma_f32 v[166:167], v[134:135], v[126:127], v[166:167] op_sel_hi:[1,0,1]
	v_pk_fma_f32 v[168:169], v[136:137], v[126:127], v[168:169] op_sel_hi:[1,0,1]
	s_waitcnt lgkmcnt(4)
	v_pk_fma_f32 v[162:163], v[138:139], v[126:127], v[162:163] op_sel:[0,1,0] op_sel_hi:[1,1,1]
	v_pk_fma_f32 v[164:165], v[140:141], v[126:127], v[164:165] op_sel:[0,1,0] op_sel_hi:[1,1,1]
	v_pk_fma_f32 v[166:167], v[142:143], v[126:127], v[166:167] op_sel:[0,1,0] op_sel_hi:[1,1,1]
	v_pk_fma_f32 v[168:169], v[144:145], v[126:127], v[168:169] op_sel:[0,1,0] op_sel_hi:[1,1,1]
	s_waitcnt lgkmcnt(2)
	v_pk_fma_f32 v[162:163], v[146:147], v[128:129], v[162:163] op_sel_hi:[1,0,1]
	v_pk_fma_f32 v[164:165], v[148:149], v[128:129], v[164:165] op_sel_hi:[1,0,1]
	v_pk_fma_f32 v[166:167], v[150:151], v[128:129], v[166:167] op_sel_hi:[1,0,1]
	v_pk_fma_f32 v[168:169], v[152:153], v[128:129], v[168:169] op_sel_hi:[1,0,1]
	s_waitcnt lgkmcnt(0)
	v_pk_fma_f32 v[162:163], v[154:155], v[128:129], v[162:163] op_sel:[0,1,0] op_sel_hi:[1,1,1]
	v_pk_fma_f32 v[164:165], v[156:157], v[128:129], v[164:165] op_sel:[0,1,0] op_sel_hi:[1,1,1]
	v_pk_fma_f32 v[166:167], v[158:159], v[128:129], v[166:167] op_sel:[0,1,0] op_sel_hi:[1,1,1]
	v_pk_fma_f32 v[168:169], v[160:161], v[128:129], v[168:169] op_sel:[0,1,0] op_sel_hi:[1,1,1]
	s_nop 1
	v_add_f32_dpp v162, v162, v162 quad_perm:[1,0,3,2] row_mask:0xf bank_mask:0xf
	v_add_f32_dpp v163, v163, v163 quad_perm:[1,0,3,2] row_mask:0xf bank_mask:0xf
	v_add_f32_dpp v164, v164, v164 quad_perm:[1,0,3,2] row_mask:0xf bank_mask:0xf
	v_add_f32_dpp v165, v165, v165 quad_perm:[1,0,3,2] row_mask:0xf bank_mask:0xf
	v_add_f32_dpp v166, v166, v166 quad_perm:[1,0,3,2] row_mask:0xf bank_mask:0xf
	v_add_f32_dpp v167, v167, v167 quad_perm:[1,0,3,2] row_mask:0xf bank_mask:0xf
	v_add_f32_dpp v168, v168, v168 quad_perm:[1,0,3,2] row_mask:0xf bank_mask:0xf
	v_add_f32_dpp v169, v169, v169 quad_perm:[1,0,3,2] row_mask:0xf bank_mask:0xf
	v_add_f32_dpp v162, v162, v162 quad_perm:[2,3,0,1] row_mask:0xf bank_mask:0xf
	v_add_f32_dpp v163, v163, v163 quad_perm:[2,3,0,1] row_mask:0xf bank_mask:0xf
	v_add_f32_dpp v164, v164, v164 quad_perm:[2,3,0,1] row_mask:0xf bank_mask:0xf
	v_add_f32_dpp v165, v165, v165 quad_perm:[2,3,0,1] row_mask:0xf bank_mask:0xf
	v_add_f32_dpp v166, v166, v166 quad_perm:[2,3,0,1] row_mask:0xf bank_mask:0xf
	v_add_f32_dpp v167, v167, v167 quad_perm:[2,3,0,1] row_mask:0xf bank_mask:0xf
	v_add_f32_dpp v168, v168, v168 quad_perm:[2,3,0,1] row_mask:0xf bank_mask:0xf
	v_add_f32_dpp v169, v169, v169 quad_perm:[2,3,0,1] row_mask:0xf bank_mask:0xf
	v_add_f32_dpp v162, v162, v162 row_half_mirror row_mask:0xf bank_mask:0xf
	v_add_f32_dpp v163, v163, v163 row_half_mirror row_mask:0xf bank_mask:0xf
	v_add_f32_dpp v164, v164, v164 row_half_mirror row_mask:0xf bank_mask:0xf
	v_add_f32_dpp v165, v165, v165 row_half_mirror row_mask:0xf bank_mask:0xf
	v_add_f32_dpp v166, v166, v166 row_half_mirror row_mask:0xf bank_mask:0xf
	v_add_f32_dpp v167, v167, v167 row_half_mirror row_mask:0xf bank_mask:0xf
	v_add_f32_dpp v168, v168, v168 row_half_mirror row_mask:0xf bank_mask:0xf
	v_add_f32_dpp v169, v169, v169 row_half_mirror row_mask:0xf bank_mask:0xf
	v_add_f32_dpp v162, v162, v162 row_mirror row_mask:0xf bank_mask:0xf
	v_add_f32_dpp v163, v163, v163 row_mirror row_mask:0xf bank_mask:0xf
	v_add_f32_dpp v164, v164, v164 row_mirror row_mask:0xf bank_mask:0xf
	v_add_f32_dpp v165, v165, v165 row_mirror row_mask:0xf bank_mask:0xf
	v_add_f32_dpp v166, v166, v166 row_mirror row_mask:0xf bank_mask:0xf
	v_add_f32_dpp v167, v167, v167 row_mirror row_mask:0xf bank_mask:0xf
	v_add_f32_dpp v168, v168, v168 row_mirror row_mask:0xf bank_mask:0xf
	v_add_f32_dpp v169, v169, v169 row_mirror row_mask:0xf bank_mask:0xf
	v_mov_b32_e32 v170, v162
	v_mov_b32_e32 v171, v163
	v_mov_b32_e32 v172, v164
	v_mov_b32_e32 v173, v165
	v_mov_b32_e32 v174, v166
	v_mov_b32_e32 v175, v167
	v_mov_b32_e32 v176, v168
	v_mov_b32_e32 v177, v169
	v_permlane16_swap_b32 v170, v162
	v_permlane16_swap_b32 v171, v163
	v_permlane16_swap_b32 v172, v164
	v_permlane16_swap_b32 v173, v165
	v_permlane16_swap_b32 v174, v166
	v_permlane16_swap_b32 v175, v167
	v_permlane16_swap_b32 v176, v168
	v_permlane16_swap_b32 v177, v169
	v_add_f32_e32 v162, v162, v170
	v_add_f32_e32 v163, v163, v171
	v_add_f32_e32 v164, v164, v172
	v_add_f32_e32 v165, v165, v173
	v_add_f32_e32 v166, v166, v174
	v_add_f32_e32 v167, v167, v175
	v_add_f32_e32 v168, v168, v176
	v_add_f32_e32 v169, v169, v177
	v_mov_b32_e32 v170, v162
	v_mov_b32_e32 v171, v163
	v_mov_b32_e32 v172, v164
	v_mov_b32_e32 v173, v165
	v_mov_b32_e32 v174, v166
	v_mov_b32_e32 v175, v167
	v_mov_b32_e32 v176, v168
	v_mov_b32_e32 v177, v169
	v_permlane32_swap_b32 v170, v162
	v_permlane32_swap_b32 v171, v163
	v_permlane32_swap_b32 v172, v164
	v_permlane32_swap_b32 v173, v165
	v_permlane32_swap_b32 v174, v166
	v_permlane32_swap_b32 v175, v167
	v_permlane32_swap_b32 v176, v168
	v_permlane32_swap_b32 v177, v169
	v_add_f32_e32 v162, v162, v170
	v_add_f32_e32 v163, v163, v171
	v_add_f32_e32 v164, v164, v172
	v_add_f32_e32 v165, v165, v173
	v_add_f32_e32 v166, v166, v174
	v_add_f32_e32 v167, v167, v175
	v_add_f32_e32 v168, v168, v176
	v_add_f32_e32 v169, v169, v177
	s_mov_b64 exec, 1
	v_mov_b32_e32 v222, v162
	s_mov_b64 exec, 2
	v_mov_b32_e32 v222, v163
	s_mov_b64 exec, 4
	v_mov_b32_e32 v222, v164
	s_mov_b64 exec, 8
	v_mov_b32_e32 v222, v165
	s_mov_b64 exec, 16
	v_mov_b32_e32 v222, v166
	s_mov_b64 exec, 32
	v_mov_b32_e32 v222, v167
	s_mov_b64 exec, 64
	v_mov_b32_e32 v222, v168
	s_mov_b64 exec, 0x80
	v_mov_b32_e32 v222, v169
	s_mov_b64 exec, 0xff
	v_add_f32_e32 v223, v222, v196
	v_mul_f32_e64 v225, |v223|, s24
	v_exp_f32_e32 v210, v225
	v_min_f32_e32 v225, 0, v223
	s_nop 0
	v_add_f32_e32 v211, 1.0, v210
	v_add_f32_e32 v212, -1.0, v211
	v_frexp_mant_f32_e32 v213, v211
	v_cvt_f64_f32_e32 v[208:209], v211
	v_sub_f32_e32 v214, v212, v211
	v_frexp_exp_i32_f64_e32 v208, v[208:209]
	v_cmp_gt_f32_e32 vcc, s25, v213
	v_sub_f32_e32 v212, v210, v212
	v_add_f32_e32 v209, 1.0, v214
	v_subbrev_co_u32_e32 v208, vcc, 0, v208, vcc
	v_add_f32_e32 v209, v212, v209
	v_sub_u32_e32 v212, 0, v208
	v_cvt_f32_i32_e32 v208, v208
	v_ldexp_f32 v211, v211, v212
	v_ldexp_f32 v209, v209, v212
	v_add_f32_e32 v212, -1.0, v211
	v_add_f32_e32 v213, 1.0, v211
	v_add_f32_e32 v214, 1.0, v212
	v_add_f32_e32 v215, -1.0, v213
	v_sub_f32_e32 v214, v211, v214
	v_sub_f32_e32 v211, v211, v215
	v_mul_f32_e32 v215, 0x3f317218, v208
	v_add_f32_e32 v214, v209, v214
	v_add_f32_e32 v209, v209, v211
	v_fma_f32 v211, v208, s28, -v215
	v_add_f32_e32 v216, v212, v214
	v_add_f32_e32 v217, v213, v209
	v_fmac_f32_e32 v211, 0xb102e308, v208
	v_sub_f32_e32 v208, v216, v212
	v_sub_f32_e32 v212, v217, v213
	v_rcp_f32_e32 v213, v217
	v_add_f32_e32 v218, v215, v211
	v_sub_f32_e32 v209, v209, v212
	v_sub_f32_e32 v212, v218, v215
	v_sub_f32_e32 v211, v211, v212
	v_mul_f32_e32 v212, v216, v213
	v_sub_f32_e32 v208, v214, v208
	v_mul_f32_e32 v214, v217, v212
	v_fma_f32 v215, v212, v217, -v214
	v_fmac_f32_e32 v215, v212, v209
	v_add_f32_e32 v219, v214, v215
	v_sub_f32_e32 v220, v216, v219
	v_sub_f32_e32 v214, v219, v214
	v_sub_f32_e32 v216, v216, v220
	v_sub_f32_e32 v214, v214, v215
	v_sub_f32_e32 v215, v216, v219
	v_add_f32_e32 v208, v208, v215
	v_add_f32_e32 v208, v214, v208
	v_add_f32_e32 v214, v220, v208
	v_mul_f32_e32 v215, v213, v214
	v_sub_f32_e32 v216, v220, v214
	v_mul_f32_e32 v219, v217, v215
	v_add_f32_e32 v208, v208, v216
	v_add_f32_e32 v216, v212, v215
	v_fma_f32 v217, v215, v217, -v219
	v_sub_f32_e32 v212, v216, v212
	v_fmac_f32_e32 v217, v215, v209
	v_sub_f32_e32 v209, v215, v212
	v_add_f32_e32 v212, v219, v217
	v_sub_f32_e32 v215, v212, v219
	v_sub_f32_e32 v219, v214, v212
	v_sub_f32_e32 v214, v214, v219
	v_sub_f32_e32 v212, v214, v212
	v_sub_f32_e32 v215, v215, v217
	v_add_f32_e32 v208, v208, v212
	v_add_f32_e32 v208, v215, v208
	v_add_f32_e32 v208, v219, v208
	v_mul_f32_e32 v208, v213, v208
	v_add_f32_e32 v208, v209, v208
	v_add_f32_e32 v209, v216, v208
	v_mul_f32_e32 v212, v209, v209
	v_fmamk_f32 v215, v212, 0x3e9b6dac, v242
	v_sub_f32_e32 v213, v209, v216
	v_ldexp_f32 v214, v209, 1
	v_mul_f32_e32 v209, v209, v212
	v_fmaak_f32 v212, v212, v215, 0x3f2aaada
	v_mul_f32_e32 v209, v209, v212
	v_add_f32_e32 v212, v214, v209
	v_sub_f32_e32 v208, v208, v213
	v_sub_f32_e32 v213, v212, v214
	v_ldexp_f32 v208, v208, 1
	v_sub_f32_e32 v209, v209, v213
	v_add_f32_e32 v208, v208, v209
	v_add_f32_e32 v209, v212, v208
	v_sub_f32_e32 v212, v209, v212
	v_add_f32_e32 v213, v218, v209
	v_sub_f32_e32 v208, v208, v212
	v_sub_f32_e32 v212, v213, v218
	v_sub_f32_e32 v214, v213, v212
	v_sub_f32_e32 v209, v209, v212
	v_add_f32_e32 v212, v211, v208
	v_sub_f32_e32 v214, v218, v214
	v_sub_f32_e32 v215, v212, v211
	v_add_f32_e32 v209, v209, v214
	v_sub_f32_e32 v214, v212, v215
	v_sub_f32_e32 v208, v208, v215
	v_sub_f32_e32 v211, v211, v214
	v_add_f32_e32 v209, v212, v209
	v_add_f32_e32 v208, v208, v211
	v_add_f32_e32 v211, v213, v209
	v_sub_f32_e32 v212, v211, v213
	v_sub_f32_e32 v209, v209, v212
	v_add_f32_e32 v208, v208, v209
	v_add_f32_e32 v208, v211, v208
	v_cmp_neq_f32_e32 vcc, s29, v210
	s_nop 0
	s_nop 0
	v_cndmask_b32_e32 v208, v243, v208, vcc
	v_cmp_ngt_f32_e32 vcc, -1.0, v210
	s_nop 1
	v_cndmask_b32_e32 v208, v244, v208, vcc
	v_cmp_neq_f32_e32 vcc, -1.0, v210
	s_nop 1
	v_cndmask_b32_e32 v208, v245, v208, vcc
	v_cmp_lt_f32_e64 vcc, |v210|, s30
	s_nop 1
	v_cndmask_b32_e32 v208, v208, v210, vcc
	v_sub_f32_e32 v225, v225, v208
	global_store_dword v195, v225, s[74:75]
	s_mov_b64 exec, -1
	v_add_u32_e32 v195, 0x2000, v195
	s_waitcnt vmcnt(18)
	v_pk_mul_f32 v[198:199], v[66:67], v[66:67]
	v_pk_mul_f32 v[200:201], v[68:69], v[68:69]
	v_pk_fma_f32 v[198:199], v[70:71], v[70:71], v[198:199]
	v_pk_fma_f32 v[200:201], v[72:73], v[72:73], v[200:201]
	v_pk_fma_f32 v[198:199], v[74:75], v[74:75], v[198:199]
	v_pk_fma_f32 v[200:201], v[76:77], v[76:77], v[200:201]
	v_pk_fma_f32 v[198:199], v[78:79], v[78:79], v[198:199]
	v_pk_fma_f32 v[200:201], v[80:81], v[80:81], v[200:201]
	v_pk_fma_f32 v[198:199], v[82:83], v[82:83], v[198:199]
	v_pk_fma_f32 v[200:201], v[84:85], v[84:85], v[200:201]
	v_pk_fma_f32 v[198:199], v[86:87], v[86:87], v[198:199]
	v_pk_fma_f32 v[200:201], v[88:89], v[88:89], v[200:201]
	v_pk_fma_f32 v[198:199], v[90:91], v[90:91], v[198:199]
	v_pk_fma_f32 v[200:201], v[92:93], v[92:93], v[200:201]
	v_pk_fma_f32 v[198:199], v[94:95], v[94:95], v[198:199]
	v_pk_fma_f32 v[200:201], v[96:97], v[96:97], v[200:201]
	v_pk_add_f32 v[198:199], v[198:199], v[200:201]
	v_add_f32_e32 v198, v198, v199
	s_nop 1
	v_add_f32_dpp v198, v198, v198 quad_perm:[1,0,3,2] row_mask:0xf bank_mask:0xf
	s_nop 1
	v_add_f32_dpp v198, v198, v198 quad_perm:[2,3,0,1] row_mask:0xf bank_mask:0xf
	s_nop 1
	v_add_f32_dpp v198, v198, v198 row_half_mirror row_mask:0xf bank_mask:0xf
	s_nop 1
	v_add_f32_dpp v198, v198, v198 row_mirror row_mask:0xf bank_mask:0xf
	v_mov_b32_e32 v199, v198
	s_nop 1
	v_permlane16_swap_b32 v199, v198
	v_add_f32_e32 v198, v198, v199
	v_mov_b32_e32 v199, v198
	s_nop 1
	v_permlane32_swap_b32 v199, v198
	v_add_f32_e32 v198, v198, v199
	ds_read_b128 v[130:133], v192
	ds_read_b128 v[134:137], v192 offset:1024
	ds_read_b128 v[138:141], v192 offset:2048
	ds_read_b128 v[142:145], v192 offset:3072
	ds_read_b128 v[146:149], v192 offset:4096
	ds_read_b128 v[150:153], v192 offset:5120
	ds_read_b128 v[154:157], v192 offset:6144
	ds_read_b128 v[158:161], v192 offset:7168
	v_fmamk_f32 v198, v198, 0x3a000000, v241
	v_mul_f32_e32 v199, 0x4b800000, v198
	v_cmp_gt_f32_e32 vcc, s17, v198
	s_nop 1
	v_cndmask_b32_e32 v198, v198, v199, vcc
	v_rsq_f32_e32 v198, v198
	s_nop 0
	v_mul_f32_e32 v199, 0x45800000, v198
	v_cndmask_b32_e32 v202, v198, v199, vcc
	v_pk_mul_f32 v[98:99], v[66:67], v[202:203] op_sel_hi:[1,0]
	v_pk_mul_f32 v[98:99], v[2:3], v[98:99]
	v_pk_mul_f32 v[100:101], v[68:69], v[202:203] op_sel_hi:[1,0]
	v_pk_mul_f32 v[100:101], v[4:5], v[100:101]
	v_cvt_pk_bf16_f32 v206, v98, v99
	v_cvt_pk_bf16_f32 v207, v100, v101
	global_store_dwordx2 v194, v[206:207], s[52:53]
	v_pk_mul_f32 v[102:103], v[70:71], v[202:203] op_sel_hi:[1,0]
	v_pk_mul_f32 v[102:103], v[6:7], v[102:103]
	v_pk_mul_f32 v[104:105], v[72:73], v[202:203] op_sel_hi:[1,0]
	v_pk_mul_f32 v[104:105], v[8:9], v[104:105]
	v_cvt_pk_bf16_f32 v206, v102, v103
	v_cvt_pk_bf16_f32 v207, v104, v105
	global_store_dwordx2 v194, v[206:207], s[52:53] offset:512
	v_pk_mul_f32 v[106:107], v[74:75], v[202:203] op_sel_hi:[1,0]
	v_pk_mul_f32 v[106:107], v[10:11], v[106:107]
	v_pk_mul_f32 v[108:109], v[76:77], v[202:203] op_sel_hi:[1,0]
	v_pk_mul_f32 v[108:109], v[12:13], v[108:109]
	v_cvt_pk_bf16_f32 v206, v106, v107
	v_cvt_pk_bf16_f32 v207, v108, v109
	global_store_dwordx2 v194, v[206:207], s[52:53] offset:1024
	v_pk_mul_f32 v[110:111], v[78:79], v[202:203] op_sel_hi:[1,0]
	v_pk_mul_f32 v[110:111], v[14:15], v[110:111]
	v_pk_mul_f32 v[112:113], v[80:81], v[202:203] op_sel_hi:[1,0]
	v_pk_mul_f32 v[112:113], v[16:17], v[112:113]
	v_cvt_pk_bf16_f32 v206, v110, v111
	v_cvt_pk_bf16_f32 v207, v112, v113
	global_store_dwordx2 v194, v[206:207], s[52:53] offset:1536
	v_pk_mul_f32 v[114:115], v[82:83], v[202:203] op_sel_hi:[1,0]
	v_pk_mul_f32 v[114:115], v[18:19], v[114:115]
	v_pk_mul_f32 v[116:117], v[84:85], v[202:203] op_sel_hi:[1,0]
	v_pk_mul_f32 v[116:117], v[20:21], v[116:117]
	v_cvt_pk_bf16_f32 v206, v114, v115
	v_cvt_pk_bf16_f32 v207, v116, v117
	global_store_dwordx2 v194, v[206:207], s[52:53] offset:2048
	v_pk_mul_f32 v[118:119], v[86:87], v[202:203] op_sel_hi:[1,0]
	v_pk_mul_f32 v[118:119], v[22:23], v[118:119]
	v_pk_mul_f32 v[120:121], v[88:89], v[202:203] op_sel_hi:[1,0]
	v_pk_mul_f32 v[120:121], v[24:25], v[120:121]
	v_cvt_pk_bf16_f32 v206, v118, v119
	v_cvt_pk_bf16_f32 v207, v120, v121
	global_store_dwordx2 v194, v[206:207], s[52:53] offset:2560
	v_pk_mul_f32 v[122:123], v[90:91], v[202:203] op_sel_hi:[1,0]
	v_pk_mul_f32 v[122:123], v[26:27], v[122:123]
	v_pk_mul_f32 v[124:125], v[92:93], v[202:203] op_sel_hi:[1,0]
	v_pk_mul_f32 v[124:125], v[28:29], v[124:125]
	v_cvt_pk_bf16_f32 v206, v122, v123
	v_cvt_pk_bf16_f32 v207, v124, v125
	global_store_dwordx2 v194, v[206:207], s[52:53] offset:3072
	v_pk_mul_f32 v[126:127], v[94:95], v[202:203] op_sel_hi:[1,0]
	v_pk_mul_f32 v[126:127], v[30:31], v[126:127]
	v_pk_mul_f32 v[128:129], v[96:97], v[202:203] op_sel_hi:[1,0]
	v_pk_mul_f32 v[128:129], v[32:33], v[128:129]
	v_cvt_pk_bf16_f32 v206, v126, v127
	v_cvt_pk_bf16_f32 v207, v128, v129
	global_store_dwordx2 v194, v[206:207], s[52:53] offset:3584
	v_add_u32_e32 v194, 0x800000, v194
	global_load_dwordx4 v[66:69], v193, s[12:13] offset:-4096 nt
	global_load_dwordx4 v[70:73], v193, s[12:13] offset:-3072 nt
	global_load_dwordx4 v[74:77], v193, s[12:13] offset:-2048 nt
	global_load_dwordx4 v[78:81], v193, s[12:13] offset:-1024 nt
	global_load_dwordx4 v[82:85], v193, s[12:13] offset:0 nt
	global_load_dwordx4 v[86:89], v193, s[12:13] offset:1024 nt
	global_load_dwordx4 v[90:93], v193, s[12:13] offset:2048 nt
	global_load_dwordx4 v[94:97], v193, s[12:13] offset:3072 nt
	v_add_u32_e32 v193, s0, v193
	s_waitcnt lgkmcnt(6)
	v_pk_mul_f32 v[162:163], v[130:131], v[98:99] op_sel_hi:[1,0]
	v_pk_mul_f32 v[164:165], v[132:133], v[98:99] op_sel_hi:[1,0]
	v_pk_mul_f32 v[166:167], v[134:135], v[98:99] op_sel_hi:[1,0]
	v_pk_mul_f32 v[168:169], v[136:137], v[98:99] op_sel_hi:[1,0]
	ds_read_b128 v[130:133], v192 offset:8192
	ds_read_b128 v[134:137], v192 offset:9216
	s_waitcnt lgkmcnt(6)
	v_pk_fma_f32 v[162:163], v[138:139], v[98:99], v[162:163] op_sel:[0,1,0] op_sel_hi:[1,1,1]
	v_pk_fma_f32 v[164:165], v[140:141], v[98:99], v[164:165] op_sel:[0,1,0] op_sel_hi:[1,1,1]
	v_pk_fma_f32 v[166:167], v[142:143], v[98:99], v[166:167] op_sel:[0,1,0] op_sel_hi:[1,1,1]
	v_pk_fma_f32 v[168:169], v[144:145], v[98:99], v[168:169] op_sel:[0,1,0] op_sel_hi:[1,1,1]
	ds_read_b128 v[138:141], v192 offset:10240
	ds_read_b128 v[142:145], v192 offset:11264
	s_waitcnt lgkmcnt(6)
	v_pk_fma_f32 v[162:163], v[146:147], v[100:101], v[162:163] op_sel_hi:[1,0,1]
	v_pk_fma_f32 v[164:165], v[148:149], v[100:101], v[164:165] op_sel_hi:[1,0,1]
	v_pk_fma_f32 v[166:167], v[150:151], v[100:101], v[166:167] op_sel_hi:[1,0,1]
	v_pk_fma_f32 v[168:169], v[152:153], v[100:101], v[168:169] op_sel_hi:[1,0,1]
	ds_read_b128 v[146:149], v192 offset:12288
	ds_read_b128 v[150:153], v192 offset:13312
	s_waitcnt lgkmcnt(6)
	v_pk_fma_f32 v[162:163], v[154:155], v[100:101], v[162:163] op_sel:[0,1,0] op_sel_hi:[1,1,1]
	v_pk_fma_f32 v[164:165], v[156:157], v[100:101], v[164:165] op_sel:[0,1,0] op_sel_hi:[1,1,1]
	v_pk_fma_f32 v[166:167], v[158:159], v[100:101], v[166:167] op_sel:[0,1,0] op_sel_hi:[1,1,1]
	v_pk_fma_f32 v[168:169], v[160:161], v[100:101], v[168:169] op_sel:[0,1,0] op_sel_hi:[1,1,1]
	ds_read_b128 v[154:157], v192 offset:14336
	ds_read_b128 v[158:161], v192 offset:15360
	s_waitcnt lgkmcnt(6)
	v_pk_fma_f32 v[162:163], v[130:131], v[102:103], v[162:163] op_sel_hi:[1,0,1]
	v_pk_fma_f32 v[164:165], v[132:133], v[102:103], v[164:165] op_sel_hi:[1,0,1]
	v_pk_fma_f32 v[166:167], v[134:135], v[102:103], v[166:167] op_sel_hi:[1,0,1]
	v_pk_fma_f32 v[168:169], v[136:137], v[102:103], v[168:169] op_sel_hi:[1,0,1]
	ds_read_b128 v[130:133], v192 offset:16384
	ds_read_b128 v[134:137], v192 offset:17408
	s_waitcnt lgkmcnt(6)
	v_pk_fma_f32 v[162:163], v[138:139], v[102:103], v[162:163] op_sel:[0,1,0] op_sel_hi:[1,1,1]
	v_pk_fma_f32 v[164:165], v[140:141], v[102:103], v[164:165] op_sel:[0,1,0] op_sel_hi:[1,1,1]
	v_pk_fma_f32 v[166:167], v[142:143], v[102:103], v[166:167] op_sel:[0,1,0] op_sel_hi:[1,1,1]
	v_pk_fma_f32 v[168:169], v[144:145], v[102:103], v[168:169] op_sel:[0,1,0] op_sel_hi:[1,1,1]
	ds_read_b128 v[138:141], v192 offset:18432
	ds_read_b128 v[142:145], v192 offset:19456
	s_waitcnt lgkmcnt(6)
	v_pk_fma_f32 v[162:163], v[146:147], v[104:105], v[162:163] op_sel_hi:[1,0,1]
	v_pk_fma_f32 v[164:165], v[148:149], v[104:105], v[164:165] op_sel_hi:[1,0,1]
	v_pk_fma_f32 v[166:167], v[150:151], v[104:105], v[166:167] op_sel_hi:[1,0,1]
	v_pk_fma_f32 v[168:169], v[152:153], v[104:105], v[168:169] op_sel_hi:[1,0,1]
	ds_read_b128 v[146:149], v192 offset:20480
	ds_read_b128 v[150:153], v192 offset:21504
	s_waitcnt lgkmcnt(6)
	v_pk_fma_f32 v[162:163], v[154:155], v[104:105], v[162:163] op_sel:[0,1,0] op_sel_hi:[1,1,1]
	v_pk_fma_f32 v[164:165], v[156:157], v[104:105], v[164:165] op_sel:[0,1,0] op_sel_hi:[1,1,1]
	v_pk_fma_f32 v[166:167], v[158:159], v[104:105], v[166:167] op_sel:[0,1,0] op_sel_hi:[1,1,1]
	v_pk_fma_f32 v[168:169], v[160:161], v[104:105], v[168:169] op_sel:[0,1,0] op_sel_hi:[1,1,1]
	ds_read_b128 v[154:157], v192 offset:22528
	ds_read_b128 v[158:161], v192 offset:23552
	s_waitcnt lgkmcnt(6)
	v_pk_fma_f32 v[162:163], v[130:131], v[106:107], v[162:163] op_sel_hi:[1,0,1]
	v_pk_fma_f32 v[164:165], v[132:133], v[106:107], v[164:165] op_sel_hi:[1,0,1]
	v_pk_fma_f32 v[166:167], v[134:135], v[106:107], v[166:167] op_sel_hi:[1,0,1]
	v_pk_fma_f32 v[168:169], v[136:137], v[106:107], v[168:169] op_sel_hi:[1,0,1]
	ds_read_b128 v[130:133], v192 offset:24576
	ds_read_b128 v[134:137], v192 offset:25600
	s_waitcnt lgkmcnt(6)
	v_pk_fma_f32 v[162:163], v[138:139], v[106:107], v[162:163] op_sel:[0,1,0] op_sel_hi:[1,1,1]
	v_pk_fma_f32 v[164:165], v[140:141], v[106:107], v[164:165] op_sel:[0,1,0] op_sel_hi:[1,1,1]
	v_pk_fma_f32 v[166:167], v[142:143], v[106:107], v[166:167] op_sel:[0,1,0] op_sel_hi:[1,1,1]
	v_pk_fma_f32 v[168:169], v[144:145], v[106:107], v[168:169] op_sel:[0,1,0] op_sel_hi:[1,1,1]
	ds_read_b128 v[138:141], v192 offset:26624
	ds_read_b128 v[142:145], v192 offset:27648
	s_waitcnt lgkmcnt(6)
	v_pk_fma_f32 v[162:163], v[146:147], v[108:109], v[162:163] op_sel_hi:[1,0,1]
	v_pk_fma_f32 v[164:165], v[148:149], v[108:109], v[164:165] op_sel_hi:[1,0,1]
	v_pk_fma_f32 v[166:167], v[150:151], v[108:109], v[166:167] op_sel_hi:[1,0,1]
	v_pk_fma_f32 v[168:169], v[152:153], v[108:109], v[168:169] op_sel_hi:[1,0,1]
	ds_read_b128 v[146:149], v192 offset:28672
	ds_read_b128 v[150:153], v192 offset:29696
	s_waitcnt lgkmcnt(6)
	v_pk_fma_f32 v[162:163], v[154:155], v[108:109], v[162:163] op_sel:[0,1,0] op_sel_hi:[1,1,1]
	v_pk_fma_f32 v[164:165], v[156:157], v[108:109], v[164:165] op_sel:[0,1,0] op_sel_hi:[1,1,1]
	v_pk_fma_f32 v[166:167], v[158:159], v[108:109], v[166:167] op_sel:[0,1,0] op_sel_hi:[1,1,1]
	v_pk_fma_f32 v[168:169], v[160:161], v[108:109], v[168:169] op_sel:[0,1,0] op_sel_hi:[1,1,1]
	ds_read_b128 v[154:157], v192 offset:30720
	ds_read_b128 v[158:161], v192 offset:31744
	s_waitcnt lgkmcnt(6)
	v_pk_fma_f32 v[162:163], v[130:131], v[110:111], v[162:163] op_sel_hi:[1,0,1]
	v_pk_fma_f32 v[164:165], v[132:133], v[110:111], v[164:165] op_sel_hi:[1,0,1]
	v_pk_fma_f32 v[166:167], v[134:135], v[110:111], v[166:167] op_sel_hi:[1,0,1]
	v_pk_fma_f32 v[168:169], v[136:137], v[110:111], v[168:169] op_sel_hi:[1,0,1]
	ds_read_b128 v[130:133], v192 offset:32768
	ds_read_b128 v[134:137], v192 offset:33792
	s_waitcnt lgkmcnt(6)
	v_pk_fma_f32 v[162:163], v[138:139], v[110:111], v[162:163] op_sel:[0,1,0] op_sel_hi:[1,1,1]
	v_pk_fma_f32 v[164:165], v[140:141], v[110:111], v[164:165] op_sel:[0,1,0] op_sel_hi:[1,1,1]
	v_pk_fma_f32 v[166:167], v[142:143], v[110:111], v[166:167] op_sel:[0,1,0] op_sel_hi:[1,1,1]
	v_pk_fma_f32 v[168:169], v[144:145], v[110:111], v[168:169] op_sel:[0,1,0] op_sel_hi:[1,1,1]
	ds_read_b128 v[138:141], v192 offset:34816
	ds_read_b128 v[142:145], v192 offset:35840
	s_waitcnt lgkmcnt(6)
	v_pk_fma_f32 v[162:163], v[146:147], v[112:113], v[162:163] op_sel_hi:[1,0,1]
	v_pk_fma_f32 v[164:165], v[148:149], v[112:113], v[164:165] op_sel_hi:[1,0,1]
	v_pk_fma_f32 v[166:167], v[150:151], v[112:113], v[166:167] op_sel_hi:[1,0,1]
	v_pk_fma_f32 v[168:169], v[152:153], v[112:113], v[168:169] op_sel_hi:[1,0,1]
	ds_read_b128 v[146:149], v192 offset:36864
	ds_read_b128 v[150:153], v192 offset:37888
	s_waitcnt lgkmcnt(6)
	v_pk_fma_f32 v[162:163], v[154:155], v[112:113], v[162:163] op_sel:[0,1,0] op_sel_hi:[1,1,1]
	v_pk_fma_f32 v[164:165], v[156:157], v[112:113], v[164:165] op_sel:[0,1,0] op_sel_hi:[1,1,1]
	v_pk_fma_f32 v[166:167], v[158:159], v[112:113], v[166:167] op_sel:[0,1,0] op_sel_hi:[1,1,1]
	v_pk_fma_f32 v[168:169], v[160:161], v[112:113], v[168:169] op_sel:[0,1,0] op_sel_hi:[1,1,1]
	ds_read_b128 v[154:157], v192 offset:38912
	ds_read_b128 v[158:161], v192 offset:39936
	s_waitcnt lgkmcnt(6)
	v_pk_fma_f32 v[162:163], v[130:131], v[114:115], v[162:163] op_sel_hi:[1,0,1]
	v_pk_fma_f32 v[164:165], v[132:133], v[114:115], v[164:165] op_sel_hi:[1,0,1]
	v_pk_fma_f32 v[166:167], v[134:135], v[114:115], v[166:167] op_sel_hi:[1,0,1]
	v_pk_fma_f32 v[168:169], v[136:137], v[114:115], v[168:169] op_sel_hi:[1,0,1]
	ds_read_b128 v[130:133], v192 offset:40960
	ds_read_b128 v[134:137], v192 offset:41984
	s_waitcnt lgkmcnt(6)
	v_pk_fma_f32 v[162:163], v[138:139], v[114:115], v[162:163] op_sel:[0,1,0] op_sel_hi:[1,1,1]
	v_pk_fma_f32 v[164:165], v[140:141], v[114:115], v[164:165] op_sel:[0,1,0] op_sel_hi:[1,1,1]
	v_pk_fma_f32 v[166:167], v[142:143], v[114:115], v[166:167] op_sel:[0,1,0] op_sel_hi:[1,1,1]
	v_pk_fma_f32 v[168:169], v[144:145], v[114:115], v[168:169] op_sel:[0,1,0] op_sel_hi:[1,1,1]
	ds_read_b128 v[138:141], v192 offset:43008
	ds_read_b128 v[142:145], v192 offset:44032
	s_waitcnt lgkmcnt(6)
	v_pk_fma_f32 v[162:163], v[146:147], v[116:117], v[162:163] op_sel_hi:[1,0,1]
	v_pk_fma_f32 v[164:165], v[148:149], v[116:117], v[164:165] op_sel_hi:[1,0,1]
	v_pk_fma_f32 v[166:167], v[150:151], v[116:117], v[166:167] op_sel_hi:[1,0,1]
	v_pk_fma_f32 v[168:169], v[152:153], v[116:117], v[168:169] op_sel_hi:[1,0,1]
	ds_read_b128 v[146:149], v192 offset:45056
	ds_read_b128 v[150:153], v192 offset:46080
	s_waitcnt lgkmcnt(6)
	v_pk_fma_f32 v[162:163], v[154:155], v[116:117], v[162:163] op_sel:[0,1,0] op_sel_hi:[1,1,1]
	v_pk_fma_f32 v[164:165], v[156:157], v[116:117], v[164:165] op_sel:[0,1,0] op_sel_hi:[1,1,1]
	v_pk_fma_f32 v[166:167], v[158:159], v[116:117], v[166:167] op_sel:[0,1,0] op_sel_hi:[1,1,1]
	v_pk_fma_f32 v[168:169], v[160:161], v[116:117], v[168:169] op_sel:[0,1,0] op_sel_hi:[1,1,1]
	ds_read_b128 v[154:157], v192 offset:47104
	ds_read_b128 v[158:161], v192 offset:48128
	s_waitcnt lgkmcnt(6)
	v_pk_fma_f32 v[162:163], v[130:131], v[118:119], v[162:163] op_sel_hi:[1,0,1]
	v_pk_fma_f32 v[164:165], v[132:133], v[118:119], v[164:165] op_sel_hi:[1,0,1]
	v_pk_fma_f32 v[166:167], v[134:135], v[118:119], v[166:167] op_sel_hi:[1,0,1]
	v_pk_fma_f32 v[168:169], v[136:137], v[118:119], v[168:169] op_sel_hi:[1,0,1]
	ds_read_b128 v[130:133], v192 offset:49152
	ds_read_b128 v[134:137], v192 offset:50176
	s_waitcnt lgkmcnt(6)
	v_pk_fma_f32 v[162:163], v[138:139], v[118:119], v[162:163] op_sel:[0,1,0] op_sel_hi:[1,1,1]
	v_pk_fma_f32 v[164:165], v[140:141], v[118:119], v[164:165] op_sel:[0,1,0] op_sel_hi:[1,1,1]
	v_pk_fma_f32 v[166:167], v[142:143], v[118:119], v[166:167] op_sel:[0,1,0] op_sel_hi:[1,1,1]
	v_pk_fma_f32 v[168:169], v[144:145], v[118:119], v[168:169] op_sel:[0,1,0] op_sel_hi:[1,1,1]
	ds_read_b128 v[138:141], v192 offset:51200
	ds_read_b128 v[142:145], v192 offset:52224
	s_waitcnt lgkmcnt(6)
	v_pk_fma_f32 v[162:163], v[146:147], v[120:121], v[162:163] op_sel_hi:[1,0,1]
	v_pk_fma_f32 v[164:165], v[148:149], v[120:121], v[164:165] op_sel_hi:[1,0,1]
	v_pk_fma_f32 v[166:167], v[150:151], v[120:121], v[166:167] op_sel_hi:[1,0,1]
	v_pk_fma_f32 v[168:169], v[152:153], v[120:121], v[168:169] op_sel_hi:[1,0,1]
	ds_read_b128 v[146:149], v192 offset:53248
	ds_read_b128 v[150:153], v192 offset:54272
	s_waitcnt lgkmcnt(6)
	v_pk_fma_f32 v[162:163], v[154:155], v[120:121], v[162:163] op_sel:[0,1,0] op_sel_hi:[1,1,1]
	v_pk_fma_f32 v[164:165], v[156:157], v[120:121], v[164:165] op_sel:[0,1,0] op_sel_hi:[1,1,1]
	v_pk_fma_f32 v[166:167], v[158:159], v[120:121], v[166:167] op_sel:[0,1,0] op_sel_hi:[1,1,1]
	v_pk_fma_f32 v[168:169], v[160:161], v[120:121], v[168:169] op_sel:[0,1,0] op_sel_hi:[1,1,1]
	ds_read_b128 v[154:157], v192 offset:55296
	ds_read_b128 v[158:161], v192 offset:56320
	s_waitcnt lgkmcnt(6)
	v_pk_fma_f32 v[162:163], v[130:131], v[122:123], v[162:163] op_sel_hi:[1,0,1]
	v_pk_fma_f32 v[164:165], v[132:133], v[122:123], v[164:165] op_sel_hi:[1,0,1]
	v_pk_fma_f32 v[166:167], v[134:135], v[122:123], v[166:167] op_sel_hi:[1,0,1]
	v_pk_fma_f32 v[168:169], v[136:137], v[122:123], v[168:169] op_sel_hi:[1,0,1]
	ds_read_b128 v[130:133], v192 offset:57344
	ds_read_b128 v[134:137], v192 offset:58368
	s_waitcnt lgkmcnt(6)
	v_pk_fma_f32 v[162:163], v[138:139], v[122:123], v[162:163] op_sel:[0,1,0] op_sel_hi:[1,1,1]
	v_pk_fma_f32 v[164:165], v[140:141], v[122:123], v[164:165] op_sel:[0,1,0] op_sel_hi:[1,1,1]
	v_pk_fma_f32 v[166:167], v[142:143], v[122:123], v[166:167] op_sel:[0,1,0] op_sel_hi:[1,1,1]
	v_pk_fma_f32 v[168:169], v[144:145], v[122:123], v[168:169] op_sel:[0,1,0] op_sel_hi:[1,1,1]
	ds_read_b128 v[138:141], v192 offset:59392
	ds_read_b128 v[142:145], v192 offset:60416
	s_waitcnt lgkmcnt(6)
	v_pk_fma_f32 v[162:163], v[146:147], v[124:125], v[162:163] op_sel_hi:[1,0,1]
	v_pk_fma_f32 v[164:165], v[148:149], v[124:125], v[164:165] op_sel_hi:[1,0,1]
	v_pk_fma_f32 v[166:167], v[150:151], v[124:125], v[166:167] op_sel_hi:[1,0,1]
	v_pk_fma_f32 v[168:169], v[152:153], v[124:125], v[168:169] op_sel_hi:[1,0,1]
	ds_read_b128 v[146:149], v192 offset:61440
	ds_read_b128 v[150:153], v192 offset:62464
	s_waitcnt lgkmcnt(6)
	v_pk_fma_f32 v[162:163], v[154:155], v[124:125], v[162:163] op_sel:[0,1,0] op_sel_hi:[1,1,1]
	v_pk_fma_f32 v[164:165], v[156:157], v[124:125], v[164:165] op_sel:[0,1,0] op_sel_hi:[1,1,1]
	v_pk_fma_f32 v[166:167], v[158:159], v[124:125], v[166:167] op_sel:[0,1,0] op_sel_hi:[1,1,1]
	v_pk_fma_f32 v[168:169], v[160:161], v[124:125], v[168:169] op_sel:[0,1,0] op_sel_hi:[1,1,1]
	ds_read_b128 v[154:157], v192 offset:63488
	ds_read_b128 v[158:161], v192 offset:64512
	s_waitcnt lgkmcnt(6)
	v_pk_fma_f32 v[162:163], v[130:131], v[126:127], v[162:163] op_sel_hi:[1,0,1]
	v_pk_fma_f32 v[164:165], v[132:133], v[126:127], v[164:165] op_sel_hi:[1,0,1]
	v_pk_fma_f32 v[166:167], v[134:135], v[126:127], v[166:167] op_sel_hi:[1,0,1]
	v_pk_fma_f32 v[168:169], v[136:137], v[126:127], v[168:169] op_sel_hi:[1,0,1]
	s_waitcnt lgkmcnt(4)
	v_pk_fma_f32 v[162:163], v[138:139], v[126:127], v[162:163] op_sel:[0,1,0] op_sel_hi:[1,1,1]
	v_pk_fma_f32 v[164:165], v[140:141], v[126:127], v[164:165] op_sel:[0,1,0] op_sel_hi:[1,1,1]
	v_pk_fma_f32 v[166:167], v[142:143], v[126:127], v[166:167] op_sel:[0,1,0] op_sel_hi:[1,1,1]
	v_pk_fma_f32 v[168:169], v[144:145], v[126:127], v[168:169] op_sel:[0,1,0] op_sel_hi:[1,1,1]
	s_waitcnt lgkmcnt(2)
	v_pk_fma_f32 v[162:163], v[146:147], v[128:129], v[162:163] op_sel_hi:[1,0,1]
	v_pk_fma_f32 v[164:165], v[148:149], v[128:129], v[164:165] op_sel_hi:[1,0,1]
	v_pk_fma_f32 v[166:167], v[150:151], v[128:129], v[166:167] op_sel_hi:[1,0,1]
	v_pk_fma_f32 v[168:169], v[152:153], v[128:129], v[168:169] op_sel_hi:[1,0,1]
	s_waitcnt lgkmcnt(0)
	v_pk_fma_f32 v[162:163], v[154:155], v[128:129], v[162:163] op_sel:[0,1,0] op_sel_hi:[1,1,1]
	v_pk_fma_f32 v[164:165], v[156:157], v[128:129], v[164:165] op_sel:[0,1,0] op_sel_hi:[1,1,1]
	v_pk_fma_f32 v[166:167], v[158:159], v[128:129], v[166:167] op_sel:[0,1,0] op_sel_hi:[1,1,1]
	v_pk_fma_f32 v[168:169], v[160:161], v[128:129], v[168:169] op_sel:[0,1,0] op_sel_hi:[1,1,1]
	s_nop 1
	v_add_f32_dpp v162, v162, v162 quad_perm:[1,0,3,2] row_mask:0xf bank_mask:0xf
	v_add_f32_dpp v163, v163, v163 quad_perm:[1,0,3,2] row_mask:0xf bank_mask:0xf
	v_add_f32_dpp v164, v164, v164 quad_perm:[1,0,3,2] row_mask:0xf bank_mask:0xf
	v_add_f32_dpp v165, v165, v165 quad_perm:[1,0,3,2] row_mask:0xf bank_mask:0xf
	v_add_f32_dpp v166, v166, v166 quad_perm:[1,0,3,2] row_mask:0xf bank_mask:0xf
	v_add_f32_dpp v167, v167, v167 quad_perm:[1,0,3,2] row_mask:0xf bank_mask:0xf
	v_add_f32_dpp v168, v168, v168 quad_perm:[1,0,3,2] row_mask:0xf bank_mask:0xf
	v_add_f32_dpp v169, v169, v169 quad_perm:[1,0,3,2] row_mask:0xf bank_mask:0xf
	v_add_f32_dpp v162, v162, v162 quad_perm:[2,3,0,1] row_mask:0xf bank_mask:0xf
	v_add_f32_dpp v163, v163, v163 quad_perm:[2,3,0,1] row_mask:0xf bank_mask:0xf
	v_add_f32_dpp v164, v164, v164 quad_perm:[2,3,0,1] row_mask:0xf bank_mask:0xf
	v_add_f32_dpp v165, v165, v165 quad_perm:[2,3,0,1] row_mask:0xf bank_mask:0xf
	v_add_f32_dpp v166, v166, v166 quad_perm:[2,3,0,1] row_mask:0xf bank_mask:0xf
	v_add_f32_dpp v167, v167, v167 quad_perm:[2,3,0,1] row_mask:0xf bank_mask:0xf
	v_add_f32_dpp v168, v168, v168 quad_perm:[2,3,0,1] row_mask:0xf bank_mask:0xf
	v_add_f32_dpp v169, v169, v169 quad_perm:[2,3,0,1] row_mask:0xf bank_mask:0xf
	v_add_f32_dpp v162, v162, v162 row_half_mirror row_mask:0xf bank_mask:0xf
	v_add_f32_dpp v163, v163, v163 row_half_mirror row_mask:0xf bank_mask:0xf
	v_add_f32_dpp v164, v164, v164 row_half_mirror row_mask:0xf bank_mask:0xf
	v_add_f32_dpp v165, v165, v165 row_half_mirror row_mask:0xf bank_mask:0xf
	v_add_f32_dpp v166, v166, v166 row_half_mirror row_mask:0xf bank_mask:0xf
	v_add_f32_dpp v167, v167, v167 row_half_mirror row_mask:0xf bank_mask:0xf
	v_add_f32_dpp v168, v168, v168 row_half_mirror row_mask:0xf bank_mask:0xf
	v_add_f32_dpp v169, v169, v169 row_half_mirror row_mask:0xf bank_mask:0xf
	v_add_f32_dpp v162, v162, v162 row_mirror row_mask:0xf bank_mask:0xf
	v_add_f32_dpp v163, v163, v163 row_mirror row_mask:0xf bank_mask:0xf
	v_add_f32_dpp v164, v164, v164 row_mirror row_mask:0xf bank_mask:0xf
	v_add_f32_dpp v165, v165, v165 row_mirror row_mask:0xf bank_mask:0xf
	v_add_f32_dpp v166, v166, v166 row_mirror row_mask:0xf bank_mask:0xf
	v_add_f32_dpp v167, v167, v167 row_mirror row_mask:0xf bank_mask:0xf
	v_add_f32_dpp v168, v168, v168 row_mirror row_mask:0xf bank_mask:0xf
	v_add_f32_dpp v169, v169, v169 row_mirror row_mask:0xf bank_mask:0xf
	v_mov_b32_e32 v170, v162
	v_mov_b32_e32 v171, v163
	v_mov_b32_e32 v172, v164
	v_mov_b32_e32 v173, v165
	v_mov_b32_e32 v174, v166
	v_mov_b32_e32 v175, v167
	v_mov_b32_e32 v176, v168
	v_mov_b32_e32 v177, v169
	v_permlane16_swap_b32 v170, v162
	v_permlane16_swap_b32 v171, v163
	v_permlane16_swap_b32 v172, v164
	v_permlane16_swap_b32 v173, v165
	v_permlane16_swap_b32 v174, v166
	v_permlane16_swap_b32 v175, v167
	v_permlane16_swap_b32 v176, v168
	v_permlane16_swap_b32 v177, v169
	v_add_f32_e32 v162, v162, v170
	v_add_f32_e32 v163, v163, v171
	v_add_f32_e32 v164, v164, v172
	v_add_f32_e32 v165, v165, v173
	v_add_f32_e32 v166, v166, v174
	v_add_f32_e32 v167, v167, v175
	v_add_f32_e32 v168, v168, v176
	v_add_f32_e32 v169, v169, v177
	v_mov_b32_e32 v170, v162
	v_mov_b32_e32 v171, v163
	v_mov_b32_e32 v172, v164
	v_mov_b32_e32 v173, v165
	v_mov_b32_e32 v174, v166
	v_mov_b32_e32 v175, v167
	v_mov_b32_e32 v176, v168
	v_mov_b32_e32 v177, v169
	v_permlane32_swap_b32 v170, v162
	v_permlane32_swap_b32 v171, v163
	v_permlane32_swap_b32 v172, v164
	v_permlane32_swap_b32 v173, v165
	v_permlane32_swap_b32 v174, v166
	v_permlane32_swap_b32 v175, v167
	v_permlane32_swap_b32 v176, v168
	v_permlane32_swap_b32 v177, v169
	v_add_f32_e32 v162, v162, v170
	v_add_f32_e32 v163, v163, v171
	v_add_f32_e32 v164, v164, v172
	v_add_f32_e32 v165, v165, v173
	v_add_f32_e32 v166, v166, v174
	v_add_f32_e32 v167, v167, v175
	v_add_f32_e32 v168, v168, v176
	v_add_f32_e32 v169, v169, v177
	s_mov_b64 exec, 1
	v_mov_b32_e32 v222, v162
	s_mov_b64 exec, 2
	v_mov_b32_e32 v222, v163
	s_mov_b64 exec, 4
	v_mov_b32_e32 v222, v164
	s_mov_b64 exec, 8
	v_mov_b32_e32 v222, v165
	s_mov_b64 exec, 16
	v_mov_b32_e32 v222, v166
	s_mov_b64 exec, 32
	v_mov_b32_e32 v222, v167
	s_mov_b64 exec, 64
	v_mov_b32_e32 v222, v168
	s_mov_b64 exec, 0x80
	v_mov_b32_e32 v222, v169
	s_mov_b64 exec, 0xff
	v_add_f32_e32 v223, v222, v196
	v_mul_f32_e64 v225, |v223|, s24
	v_exp_f32_e32 v210, v225
	v_min_f32_e32 v225, 0, v223
	s_nop 0
	v_add_f32_e32 v211, 1.0, v210
	v_add_f32_e32 v212, -1.0, v211
	v_frexp_mant_f32_e32 v213, v211
	v_cvt_f64_f32_e32 v[208:209], v211
	v_sub_f32_e32 v214, v212, v211
	v_frexp_exp_i32_f64_e32 v208, v[208:209]
	v_cmp_gt_f32_e32 vcc, s25, v213
	v_sub_f32_e32 v212, v210, v212
	v_add_f32_e32 v209, 1.0, v214
	v_subbrev_co_u32_e32 v208, vcc, 0, v208, vcc
	v_add_f32_e32 v209, v212, v209
	v_sub_u32_e32 v212, 0, v208
	v_cvt_f32_i32_e32 v208, v208
	v_ldexp_f32 v211, v211, v212
	v_ldexp_f32 v209, v209, v212
	v_add_f32_e32 v212, -1.0, v211
	v_add_f32_e32 v213, 1.0, v211
	v_add_f32_e32 v214, 1.0, v212
	v_add_f32_e32 v215, -1.0, v213
	v_sub_f32_e32 v214, v211, v214
	v_sub_f32_e32 v211, v211, v215
	v_mul_f32_e32 v215, 0x3f317218, v208
	v_add_f32_e32 v214, v209, v214
	v_add_f32_e32 v209, v209, v211
	v_fma_f32 v211, v208, s28, -v215
	v_add_f32_e32 v216, v212, v214
	v_add_f32_e32 v217, v213, v209
	v_fmac_f32_e32 v211, 0xb102e308, v208
	v_sub_f32_e32 v208, v216, v212
	v_sub_f32_e32 v212, v217, v213
	v_rcp_f32_e32 v213, v217
	v_add_f32_e32 v218, v215, v211
	v_sub_f32_e32 v209, v209, v212
	v_sub_f32_e32 v212, v218, v215
	v_sub_f32_e32 v211, v211, v212
	v_mul_f32_e32 v212, v216, v213
	v_sub_f32_e32 v208, v214, v208
	v_mul_f32_e32 v214, v217, v212
	v_fma_f32 v215, v212, v217, -v214
	v_fmac_f32_e32 v215, v212, v209
	v_add_f32_e32 v219, v214, v215
	v_sub_f32_e32 v220, v216, v219
	v_sub_f32_e32 v214, v219, v214
	v_sub_f32_e32 v216, v216, v220
	v_sub_f32_e32 v214, v214, v215
	v_sub_f32_e32 v215, v216, v219
	v_add_f32_e32 v208, v208, v215
	v_add_f32_e32 v208, v214, v208
	v_add_f32_e32 v214, v220, v208
	v_mul_f32_e32 v215, v213, v214
	v_sub_f32_e32 v216, v220, v214
	v_mul_f32_e32 v219, v217, v215
	v_add_f32_e32 v208, v208, v216
	v_add_f32_e32 v216, v212, v215
	v_fma_f32 v217, v215, v217, -v219
	v_sub_f32_e32 v212, v216, v212
	v_fmac_f32_e32 v217, v215, v209
	v_sub_f32_e32 v209, v215, v212
	v_add_f32_e32 v212, v219, v217
	v_sub_f32_e32 v215, v212, v219
	v_sub_f32_e32 v219, v214, v212
	v_sub_f32_e32 v214, v214, v219
	v_sub_f32_e32 v212, v214, v212
	v_sub_f32_e32 v215, v215, v217
	v_add_f32_e32 v208, v208, v212
	v_add_f32_e32 v208, v215, v208
	v_add_f32_e32 v208, v219, v208
	v_mul_f32_e32 v208, v213, v208
	v_add_f32_e32 v208, v209, v208
	v_add_f32_e32 v209, v216, v208
	v_mul_f32_e32 v212, v209, v209
	v_fmamk_f32 v215, v212, 0x3e9b6dac, v242
	v_sub_f32_e32 v213, v209, v216
	v_ldexp_f32 v214, v209, 1
	v_mul_f32_e32 v209, v209, v212
	v_fmaak_f32 v212, v212, v215, 0x3f2aaada
	v_mul_f32_e32 v209, v209, v212
	v_add_f32_e32 v212, v214, v209
	v_sub_f32_e32 v208, v208, v213
	v_sub_f32_e32 v213, v212, v214
	v_ldexp_f32 v208, v208, 1
	v_sub_f32_e32 v209, v209, v213
	v_add_f32_e32 v208, v208, v209
	v_add_f32_e32 v209, v212, v208
	v_sub_f32_e32 v212, v209, v212
	v_add_f32_e32 v213, v218, v209
	v_sub_f32_e32 v208, v208, v212
	v_sub_f32_e32 v212, v213, v218
	v_sub_f32_e32 v214, v213, v212
	v_sub_f32_e32 v209, v209, v212
	v_add_f32_e32 v212, v211, v208
	v_sub_f32_e32 v214, v218, v214
	v_sub_f32_e32 v215, v212, v211
	v_add_f32_e32 v209, v209, v214
	v_sub_f32_e32 v214, v212, v215
	v_sub_f32_e32 v208, v208, v215
	v_sub_f32_e32 v211, v211, v214
	v_add_f32_e32 v209, v212, v209
	v_add_f32_e32 v208, v208, v211
	v_add_f32_e32 v211, v213, v209
	v_sub_f32_e32 v212, v211, v213
	v_sub_f32_e32 v209, v209, v212
	v_add_f32_e32 v208, v208, v209
	v_add_f32_e32 v208, v211, v208
	v_cmp_neq_f32_e32 vcc, s29, v210
	s_nop 0
	s_nop 0
	v_cndmask_b32_e32 v208, v243, v208, vcc
	v_cmp_ngt_f32_e32 vcc, -1.0, v210
	s_nop 1
	v_cndmask_b32_e32 v208, v244, v208, vcc
	v_cmp_neq_f32_e32 vcc, -1.0, v210
	s_nop 1
	v_cndmask_b32_e32 v208, v245, v208, vcc
	v_cmp_lt_f32_e64 vcc, |v210|, s30
	s_nop 1
	v_cndmask_b32_e32 v208, v208, v210, vcc
	v_sub_f32_e32 v225, v225, v208
	global_store_dword v195, v225, s[74:75]
	s_mov_b64 exec, -1
	v_add_u32_e32 v195, 0x2000, v195
	s_waitcnt vmcnt(18)
	v_pk_mul_f32 v[198:199], v[34:35], v[34:35]
	v_pk_mul_f32 v[200:201], v[36:37], v[36:37]
	v_pk_fma_f32 v[198:199], v[38:39], v[38:39], v[198:199]
	v_pk_fma_f32 v[200:201], v[40:41], v[40:41], v[200:201]
	v_pk_fma_f32 v[198:199], v[42:43], v[42:43], v[198:199]
	v_pk_fma_f32 v[200:201], v[44:45], v[44:45], v[200:201]
	v_pk_fma_f32 v[198:199], v[46:47], v[46:47], v[198:199]
	v_pk_fma_f32 v[200:201], v[48:49], v[48:49], v[200:201]
	v_pk_fma_f32 v[198:199], v[50:51], v[50:51], v[198:199]
	v_pk_fma_f32 v[200:201], v[52:53], v[52:53], v[200:201]
	v_pk_fma_f32 v[198:199], v[54:55], v[54:55], v[198:199]
	v_pk_fma_f32 v[200:201], v[56:57], v[56:57], v[200:201]
	v_pk_fma_f32 v[198:199], v[58:59], v[58:59], v[198:199]
	v_pk_fma_f32 v[200:201], v[60:61], v[60:61], v[200:201]
	v_pk_fma_f32 v[198:199], v[62:63], v[62:63], v[198:199]
	v_pk_fma_f32 v[200:201], v[64:65], v[64:65], v[200:201]
	v_pk_add_f32 v[198:199], v[198:199], v[200:201]
	v_add_f32_e32 v198, v198, v199
	s_nop 1
	v_add_f32_dpp v198, v198, v198 quad_perm:[1,0,3,2] row_mask:0xf bank_mask:0xf
	s_nop 1
	v_add_f32_dpp v198, v198, v198 quad_perm:[2,3,0,1] row_mask:0xf bank_mask:0xf
	s_nop 1
	v_add_f32_dpp v198, v198, v198 row_half_mirror row_mask:0xf bank_mask:0xf
	s_nop 1
	v_add_f32_dpp v198, v198, v198 row_mirror row_mask:0xf bank_mask:0xf
	v_mov_b32_e32 v199, v198
	s_nop 1
	v_permlane16_swap_b32 v199, v198
	v_add_f32_e32 v198, v198, v199
	v_mov_b32_e32 v199, v198
	s_nop 1
	v_permlane32_swap_b32 v199, v198
	v_add_f32_e32 v198, v198, v199
	ds_read_b128 v[130:133], v192
	ds_read_b128 v[134:137], v192 offset:1024
	ds_read_b128 v[138:141], v192 offset:2048
	ds_read_b128 v[142:145], v192 offset:3072
	ds_read_b128 v[146:149], v192 offset:4096
	ds_read_b128 v[150:153], v192 offset:5120
	ds_read_b128 v[154:157], v192 offset:6144
	ds_read_b128 v[158:161], v192 offset:7168
	v_fmamk_f32 v198, v198, 0x3a000000, v241
	v_mul_f32_e32 v199, 0x4b800000, v198
	v_cmp_gt_f32_e32 vcc, s17, v198
	s_nop 1
	v_cndmask_b32_e32 v198, v198, v199, vcc
	v_rsq_f32_e32 v198, v198
	s_nop 0
	v_mul_f32_e32 v199, 0x45800000, v198
	v_cndmask_b32_e32 v202, v198, v199, vcc
	v_pk_mul_f32 v[98:99], v[34:35], v[202:203] op_sel_hi:[1,0]
	v_pk_mul_f32 v[98:99], v[2:3], v[98:99]
	v_pk_mul_f32 v[100:101], v[36:37], v[202:203] op_sel_hi:[1,0]
	v_pk_mul_f32 v[100:101], v[4:5], v[100:101]
	v_cvt_pk_bf16_f32 v206, v98, v99
	v_cvt_pk_bf16_f32 v207, v100, v101
	global_store_dwordx2 v194, v[206:207], s[52:53]
	v_pk_mul_f32 v[102:103], v[38:39], v[202:203] op_sel_hi:[1,0]
	v_pk_mul_f32 v[102:103], v[6:7], v[102:103]
	v_pk_mul_f32 v[104:105], v[40:41], v[202:203] op_sel_hi:[1,0]
	v_pk_mul_f32 v[104:105], v[8:9], v[104:105]
	v_cvt_pk_bf16_f32 v206, v102, v103
	v_cvt_pk_bf16_f32 v207, v104, v105
	global_store_dwordx2 v194, v[206:207], s[52:53] offset:512
	v_pk_mul_f32 v[106:107], v[42:43], v[202:203] op_sel_hi:[1,0]
	v_pk_mul_f32 v[106:107], v[10:11], v[106:107]
	v_pk_mul_f32 v[108:109], v[44:45], v[202:203] op_sel_hi:[1,0]
	v_pk_mul_f32 v[108:109], v[12:13], v[108:109]
	v_cvt_pk_bf16_f32 v206, v106, v107
	v_cvt_pk_bf16_f32 v207, v108, v109
	global_store_dwordx2 v194, v[206:207], s[52:53] offset:1024
	v_pk_mul_f32 v[110:111], v[46:47], v[202:203] op_sel_hi:[1,0]
	v_pk_mul_f32 v[110:111], v[14:15], v[110:111]
	v_pk_mul_f32 v[112:113], v[48:49], v[202:203] op_sel_hi:[1,0]
	v_pk_mul_f32 v[112:113], v[16:17], v[112:113]
	v_cvt_pk_bf16_f32 v206, v110, v111
	v_cvt_pk_bf16_f32 v207, v112, v113
	global_store_dwordx2 v194, v[206:207], s[52:53] offset:1536
	v_pk_mul_f32 v[114:115], v[50:51], v[202:203] op_sel_hi:[1,0]
	v_pk_mul_f32 v[114:115], v[18:19], v[114:115]
	v_pk_mul_f32 v[116:117], v[52:53], v[202:203] op_sel_hi:[1,0]
	v_pk_mul_f32 v[116:117], v[20:21], v[116:117]
	v_cvt_pk_bf16_f32 v206, v114, v115
	v_cvt_pk_bf16_f32 v207, v116, v117
	global_store_dwordx2 v194, v[206:207], s[52:53] offset:2048
	v_pk_mul_f32 v[118:119], v[54:55], v[202:203] op_sel_hi:[1,0]
	v_pk_mul_f32 v[118:119], v[22:23], v[118:119]
	v_pk_mul_f32 v[120:121], v[56:57], v[202:203] op_sel_hi:[1,0]
	v_pk_mul_f32 v[120:121], v[24:25], v[120:121]
	v_cvt_pk_bf16_f32 v206, v118, v119
	v_cvt_pk_bf16_f32 v207, v120, v121
	global_store_dwordx2 v194, v[206:207], s[52:53] offset:2560
	v_pk_mul_f32 v[122:123], v[58:59], v[202:203] op_sel_hi:[1,0]
	v_pk_mul_f32 v[122:123], v[26:27], v[122:123]
	v_pk_mul_f32 v[124:125], v[60:61], v[202:203] op_sel_hi:[1,0]
	v_pk_mul_f32 v[124:125], v[28:29], v[124:125]
	v_cvt_pk_bf16_f32 v206, v122, v123
	v_cvt_pk_bf16_f32 v207, v124, v125
	global_store_dwordx2 v194, v[206:207], s[52:53] offset:3072
	v_pk_mul_f32 v[126:127], v[62:63], v[202:203] op_sel_hi:[1,0]
	v_pk_mul_f32 v[126:127], v[30:31], v[126:127]
	v_pk_mul_f32 v[128:129], v[64:65], v[202:203] op_sel_hi:[1,0]
	v_pk_mul_f32 v[128:129], v[32:33], v[128:129]
	v_cvt_pk_bf16_f32 v206, v126, v127
	v_cvt_pk_bf16_f32 v207, v128, v129
	global_store_dwordx2 v194, v[206:207], s[52:53] offset:3584
	v_add_u32_e32 v194, 0x800000, v194
	s_waitcnt lgkmcnt(6)
	v_pk_mul_f32 v[162:163], v[130:131], v[98:99] op_sel_hi:[1,0]
	v_pk_mul_f32 v[164:165], v[132:133], v[98:99] op_sel_hi:[1,0]
	v_pk_mul_f32 v[166:167], v[134:135], v[98:99] op_sel_hi:[1,0]
	v_pk_mul_f32 v[168:169], v[136:137], v[98:99] op_sel_hi:[1,0]
	ds_read_b128 v[130:133], v192 offset:8192
	ds_read_b128 v[134:137], v192 offset:9216
	s_waitcnt lgkmcnt(6)
	v_pk_fma_f32 v[162:163], v[138:139], v[98:99], v[162:163] op_sel:[0,1,0] op_sel_hi:[1,1,1]
	v_pk_fma_f32 v[164:165], v[140:141], v[98:99], v[164:165] op_sel:[0,1,0] op_sel_hi:[1,1,1]
	v_pk_fma_f32 v[166:167], v[142:143], v[98:99], v[166:167] op_sel:[0,1,0] op_sel_hi:[1,1,1]
	v_pk_fma_f32 v[168:169], v[144:145], v[98:99], v[168:169] op_sel:[0,1,0] op_sel_hi:[1,1,1]
	ds_read_b128 v[138:141], v192 offset:10240
	ds_read_b128 v[142:145], v192 offset:11264
	s_waitcnt lgkmcnt(6)
	v_pk_fma_f32 v[162:163], v[146:147], v[100:101], v[162:163] op_sel_hi:[1,0,1]
	v_pk_fma_f32 v[164:165], v[148:149], v[100:101], v[164:165] op_sel_hi:[1,0,1]
	v_pk_fma_f32 v[166:167], v[150:151], v[100:101], v[166:167] op_sel_hi:[1,0,1]
	v_pk_fma_f32 v[168:169], v[152:153], v[100:101], v[168:169] op_sel_hi:[1,0,1]
	ds_read_b128 v[146:149], v192 offset:12288
	ds_read_b128 v[150:153], v192 offset:13312
	s_waitcnt lgkmcnt(6)
	v_pk_fma_f32 v[162:163], v[154:155], v[100:101], v[162:163] op_sel:[0,1,0] op_sel_hi:[1,1,1]
	v_pk_fma_f32 v[164:165], v[156:157], v[100:101], v[164:165] op_sel:[0,1,0] op_sel_hi:[1,1,1]
	v_pk_fma_f32 v[166:167], v[158:159], v[100:101], v[166:167] op_sel:[0,1,0] op_sel_hi:[1,1,1]
	v_pk_fma_f32 v[168:169], v[160:161], v[100:101], v[168:169] op_sel:[0,1,0] op_sel_hi:[1,1,1]
	ds_read_b128 v[154:157], v192 offset:14336
	ds_read_b128 v[158:161], v192 offset:15360
	s_waitcnt lgkmcnt(6)
	v_pk_fma_f32 v[162:163], v[130:131], v[102:103], v[162:163] op_sel_hi:[1,0,1]
	v_pk_fma_f32 v[164:165], v[132:133], v[102:103], v[164:165] op_sel_hi:[1,0,1]
	v_pk_fma_f32 v[166:167], v[134:135], v[102:103], v[166:167] op_sel_hi:[1,0,1]
	v_pk_fma_f32 v[168:169], v[136:137], v[102:103], v[168:169] op_sel_hi:[1,0,1]
	ds_read_b128 v[130:133], v192 offset:16384
	ds_read_b128 v[134:137], v192 offset:17408
	s_waitcnt lgkmcnt(6)
	v_pk_fma_f32 v[162:163], v[138:139], v[102:103], v[162:163] op_sel:[0,1,0] op_sel_hi:[1,1,1]
	v_pk_fma_f32 v[164:165], v[140:141], v[102:103], v[164:165] op_sel:[0,1,0] op_sel_hi:[1,1,1]
	v_pk_fma_f32 v[166:167], v[142:143], v[102:103], v[166:167] op_sel:[0,1,0] op_sel_hi:[1,1,1]
	v_pk_fma_f32 v[168:169], v[144:145], v[102:103], v[168:169] op_sel:[0,1,0] op_sel_hi:[1,1,1]
	ds_read_b128 v[138:141], v192 offset:18432
	ds_read_b128 v[142:145], v192 offset:19456
	s_waitcnt lgkmcnt(6)
	v_pk_fma_f32 v[162:163], v[146:147], v[104:105], v[162:163] op_sel_hi:[1,0,1]
	v_pk_fma_f32 v[164:165], v[148:149], v[104:105], v[164:165] op_sel_hi:[1,0,1]
	v_pk_fma_f32 v[166:167], v[150:151], v[104:105], v[166:167] op_sel_hi:[1,0,1]
	v_pk_fma_f32 v[168:169], v[152:153], v[104:105], v[168:169] op_sel_hi:[1,0,1]
	ds_read_b128 v[146:149], v192 offset:20480
	ds_read_b128 v[150:153], v192 offset:21504
	s_waitcnt lgkmcnt(6)
	v_pk_fma_f32 v[162:163], v[154:155], v[104:105], v[162:163] op_sel:[0,1,0] op_sel_hi:[1,1,1]
	v_pk_fma_f32 v[164:165], v[156:157], v[104:105], v[164:165] op_sel:[0,1,0] op_sel_hi:[1,1,1]
	v_pk_fma_f32 v[166:167], v[158:159], v[104:105], v[166:167] op_sel:[0,1,0] op_sel_hi:[1,1,1]
	v_pk_fma_f32 v[168:169], v[160:161], v[104:105], v[168:169] op_sel:[0,1,0] op_sel_hi:[1,1,1]
	ds_read_b128 v[154:157], v192 offset:22528
	ds_read_b128 v[158:161], v192 offset:23552
	s_waitcnt lgkmcnt(6)
	v_pk_fma_f32 v[162:163], v[130:131], v[106:107], v[162:163] op_sel_hi:[1,0,1]
	v_pk_fma_f32 v[164:165], v[132:133], v[106:107], v[164:165] op_sel_hi:[1,0,1]
	v_pk_fma_f32 v[166:167], v[134:135], v[106:107], v[166:167] op_sel_hi:[1,0,1]
	v_pk_fma_f32 v[168:169], v[136:137], v[106:107], v[168:169] op_sel_hi:[1,0,1]
	ds_read_b128 v[130:133], v192 offset:24576
	ds_read_b128 v[134:137], v192 offset:25600
	s_waitcnt lgkmcnt(6)
	v_pk_fma_f32 v[162:163], v[138:139], v[106:107], v[162:163] op_sel:[0,1,0] op_sel_hi:[1,1,1]
	v_pk_fma_f32 v[164:165], v[140:141], v[106:107], v[164:165] op_sel:[0,1,0] op_sel_hi:[1,1,1]
	v_pk_fma_f32 v[166:167], v[142:143], v[106:107], v[166:167] op_sel:[0,1,0] op_sel_hi:[1,1,1]
	v_pk_fma_f32 v[168:169], v[144:145], v[106:107], v[168:169] op_sel:[0,1,0] op_sel_hi:[1,1,1]
	ds_read_b128 v[138:141], v192 offset:26624
	ds_read_b128 v[142:145], v192 offset:27648
	s_waitcnt lgkmcnt(6)
	v_pk_fma_f32 v[162:163], v[146:147], v[108:109], v[162:163] op_sel_hi:[1,0,1]
	v_pk_fma_f32 v[164:165], v[148:149], v[108:109], v[164:165] op_sel_hi:[1,0,1]
	v_pk_fma_f32 v[166:167], v[150:151], v[108:109], v[166:167] op_sel_hi:[1,0,1]
	v_pk_fma_f32 v[168:169], v[152:153], v[108:109], v[168:169] op_sel_hi:[1,0,1]
	ds_read_b128 v[146:149], v192 offset:28672
	ds_read_b128 v[150:153], v192 offset:29696
	s_waitcnt lgkmcnt(6)
	v_pk_fma_f32 v[162:163], v[154:155], v[108:109], v[162:163] op_sel:[0,1,0] op_sel_hi:[1,1,1]
	v_pk_fma_f32 v[164:165], v[156:157], v[108:109], v[164:165] op_sel:[0,1,0] op_sel_hi:[1,1,1]
	v_pk_fma_f32 v[166:167], v[158:159], v[108:109], v[166:167] op_sel:[0,1,0] op_sel_hi:[1,1,1]
	v_pk_fma_f32 v[168:169], v[160:161], v[108:109], v[168:169] op_sel:[0,1,0] op_sel_hi:[1,1,1]
	ds_read_b128 v[154:157], v192 offset:30720
	ds_read_b128 v[158:161], v192 offset:31744
	s_waitcnt lgkmcnt(6)
	v_pk_fma_f32 v[162:163], v[130:131], v[110:111], v[162:163] op_sel_hi:[1,0,1]
	v_pk_fma_f32 v[164:165], v[132:133], v[110:111], v[164:165] op_sel_hi:[1,0,1]
	v_pk_fma_f32 v[166:167], v[134:135], v[110:111], v[166:167] op_sel_hi:[1,0,1]
	v_pk_fma_f32 v[168:169], v[136:137], v[110:111], v[168:169] op_sel_hi:[1,0,1]
	ds_read_b128 v[130:133], v192 offset:32768
	ds_read_b128 v[134:137], v192 offset:33792
	s_waitcnt lgkmcnt(6)
	v_pk_fma_f32 v[162:163], v[138:139], v[110:111], v[162:163] op_sel:[0,1,0] op_sel_hi:[1,1,1]
	v_pk_fma_f32 v[164:165], v[140:141], v[110:111], v[164:165] op_sel:[0,1,0] op_sel_hi:[1,1,1]
	v_pk_fma_f32 v[166:167], v[142:143], v[110:111], v[166:167] op_sel:[0,1,0] op_sel_hi:[1,1,1]
	v_pk_fma_f32 v[168:169], v[144:145], v[110:111], v[168:169] op_sel:[0,1,0] op_sel_hi:[1,1,1]
	ds_read_b128 v[138:141], v192 offset:34816
	ds_read_b128 v[142:145], v192 offset:35840
	s_waitcnt lgkmcnt(6)
	v_pk_fma_f32 v[162:163], v[146:147], v[112:113], v[162:163] op_sel_hi:[1,0,1]
	v_pk_fma_f32 v[164:165], v[148:149], v[112:113], v[164:165] op_sel_hi:[1,0,1]
	v_pk_fma_f32 v[166:167], v[150:151], v[112:113], v[166:167] op_sel_hi:[1,0,1]
	v_pk_fma_f32 v[168:169], v[152:153], v[112:113], v[168:169] op_sel_hi:[1,0,1]
	ds_read_b128 v[146:149], v192 offset:36864
	ds_read_b128 v[150:153], v192 offset:37888
	s_waitcnt lgkmcnt(6)
	v_pk_fma_f32 v[162:163], v[154:155], v[112:113], v[162:163] op_sel:[0,1,0] op_sel_hi:[1,1,1]
	v_pk_fma_f32 v[164:165], v[156:157], v[112:113], v[164:165] op_sel:[0,1,0] op_sel_hi:[1,1,1]
	v_pk_fma_f32 v[166:167], v[158:159], v[112:113], v[166:167] op_sel:[0,1,0] op_sel_hi:[1,1,1]
	v_pk_fma_f32 v[168:169], v[160:161], v[112:113], v[168:169] op_sel:[0,1,0] op_sel_hi:[1,1,1]
	ds_read_b128 v[154:157], v192 offset:38912
	ds_read_b128 v[158:161], v192 offset:39936
	s_waitcnt lgkmcnt(6)
	v_pk_fma_f32 v[162:163], v[130:131], v[114:115], v[162:163] op_sel_hi:[1,0,1]
	v_pk_fma_f32 v[164:165], v[132:133], v[114:115], v[164:165] op_sel_hi:[1,0,1]
	v_pk_fma_f32 v[166:167], v[134:135], v[114:115], v[166:167] op_sel_hi:[1,0,1]
	v_pk_fma_f32 v[168:169], v[136:137], v[114:115], v[168:169] op_sel_hi:[1,0,1]
	ds_read_b128 v[130:133], v192 offset:40960
	ds_read_b128 v[134:137], v192 offset:41984
	s_waitcnt lgkmcnt(6)
	v_pk_fma_f32 v[162:163], v[138:139], v[114:115], v[162:163] op_sel:[0,1,0] op_sel_hi:[1,1,1]
	v_pk_fma_f32 v[164:165], v[140:141], v[114:115], v[164:165] op_sel:[0,1,0] op_sel_hi:[1,1,1]
	v_pk_fma_f32 v[166:167], v[142:143], v[114:115], v[166:167] op_sel:[0,1,0] op_sel_hi:[1,1,1]
	v_pk_fma_f32 v[168:169], v[144:145], v[114:115], v[168:169] op_sel:[0,1,0] op_sel_hi:[1,1,1]
	ds_read_b128 v[138:141], v192 offset:43008
	ds_read_b128 v[142:145], v192 offset:44032
	s_waitcnt lgkmcnt(6)
	v_pk_fma_f32 v[162:163], v[146:147], v[116:117], v[162:163] op_sel_hi:[1,0,1]
	v_pk_fma_f32 v[164:165], v[148:149], v[116:117], v[164:165] op_sel_hi:[1,0,1]
	v_pk_fma_f32 v[166:167], v[150:151], v[116:117], v[166:167] op_sel_hi:[1,0,1]
	v_pk_fma_f32 v[168:169], v[152:153], v[116:117], v[168:169] op_sel_hi:[1,0,1]
	ds_read_b128 v[146:149], v192 offset:45056
	ds_read_b128 v[150:153], v192 offset:46080
	s_waitcnt lgkmcnt(6)
	v_pk_fma_f32 v[162:163], v[154:155], v[116:117], v[162:163] op_sel:[0,1,0] op_sel_hi:[1,1,1]
	v_pk_fma_f32 v[164:165], v[156:157], v[116:117], v[164:165] op_sel:[0,1,0] op_sel_hi:[1,1,1]
	v_pk_fma_f32 v[166:167], v[158:159], v[116:117], v[166:167] op_sel:[0,1,0] op_sel_hi:[1,1,1]
	v_pk_fma_f32 v[168:169], v[160:161], v[116:117], v[168:169] op_sel:[0,1,0] op_sel_hi:[1,1,1]
	ds_read_b128 v[154:157], v192 offset:47104
	ds_read_b128 v[158:161], v192 offset:48128
	s_waitcnt lgkmcnt(6)
	v_pk_fma_f32 v[162:163], v[130:131], v[118:119], v[162:163] op_sel_hi:[1,0,1]
	v_pk_fma_f32 v[164:165], v[132:133], v[118:119], v[164:165] op_sel_hi:[1,0,1]
	v_pk_fma_f32 v[166:167], v[134:135], v[118:119], v[166:167] op_sel_hi:[1,0,1]
	v_pk_fma_f32 v[168:169], v[136:137], v[118:119], v[168:169] op_sel_hi:[1,0,1]
	ds_read_b128 v[130:133], v192 offset:49152
	ds_read_b128 v[134:137], v192 offset:50176
	s_waitcnt lgkmcnt(6)
	v_pk_fma_f32 v[162:163], v[138:139], v[118:119], v[162:163] op_sel:[0,1,0] op_sel_hi:[1,1,1]
	v_pk_fma_f32 v[164:165], v[140:141], v[118:119], v[164:165] op_sel:[0,1,0] op_sel_hi:[1,1,1]
	v_pk_fma_f32 v[166:167], v[142:143], v[118:119], v[166:167] op_sel:[0,1,0] op_sel_hi:[1,1,1]
	v_pk_fma_f32 v[168:169], v[144:145], v[118:119], v[168:169] op_sel:[0,1,0] op_sel_hi:[1,1,1]
	ds_read_b128 v[138:141], v192 offset:51200
	ds_read_b128 v[142:145], v192 offset:52224
	s_waitcnt lgkmcnt(6)
	v_pk_fma_f32 v[162:163], v[146:147], v[120:121], v[162:163] op_sel_hi:[1,0,1]
	v_pk_fma_f32 v[164:165], v[148:149], v[120:121], v[164:165] op_sel_hi:[1,0,1]
	v_pk_fma_f32 v[166:167], v[150:151], v[120:121], v[166:167] op_sel_hi:[1,0,1]
	v_pk_fma_f32 v[168:169], v[152:153], v[120:121], v[168:169] op_sel_hi:[1,0,1]
	ds_read_b128 v[146:149], v192 offset:53248
	ds_read_b128 v[150:153], v192 offset:54272
	s_waitcnt lgkmcnt(6)
	v_pk_fma_f32 v[162:163], v[154:155], v[120:121], v[162:163] op_sel:[0,1,0] op_sel_hi:[1,1,1]
	v_pk_fma_f32 v[164:165], v[156:157], v[120:121], v[164:165] op_sel:[0,1,0] op_sel_hi:[1,1,1]
	v_pk_fma_f32 v[166:167], v[158:159], v[120:121], v[166:167] op_sel:[0,1,0] op_sel_hi:[1,1,1]
	v_pk_fma_f32 v[168:169], v[160:161], v[120:121], v[168:169] op_sel:[0,1,0] op_sel_hi:[1,1,1]
	ds_read_b128 v[154:157], v192 offset:55296
	ds_read_b128 v[158:161], v192 offset:56320
	s_waitcnt lgkmcnt(6)
	v_pk_fma_f32 v[162:163], v[130:131], v[122:123], v[162:163] op_sel_hi:[1,0,1]
	v_pk_fma_f32 v[164:165], v[132:133], v[122:123], v[164:165] op_sel_hi:[1,0,1]
	v_pk_fma_f32 v[166:167], v[134:135], v[122:123], v[166:167] op_sel_hi:[1,0,1]
	v_pk_fma_f32 v[168:169], v[136:137], v[122:123], v[168:169] op_sel_hi:[1,0,1]
	ds_read_b128 v[130:133], v192 offset:57344
	ds_read_b128 v[134:137], v192 offset:58368
	s_waitcnt lgkmcnt(6)
	v_pk_fma_f32 v[162:163], v[138:139], v[122:123], v[162:163] op_sel:[0,1,0] op_sel_hi:[1,1,1]
	v_pk_fma_f32 v[164:165], v[140:141], v[122:123], v[164:165] op_sel:[0,1,0] op_sel_hi:[1,1,1]
	v_pk_fma_f32 v[166:167], v[142:143], v[122:123], v[166:167] op_sel:[0,1,0] op_sel_hi:[1,1,1]
	v_pk_fma_f32 v[168:169], v[144:145], v[122:123], v[168:169] op_sel:[0,1,0] op_sel_hi:[1,1,1]
	ds_read_b128 v[138:141], v192 offset:59392
	ds_read_b128 v[142:145], v192 offset:60416
	s_waitcnt lgkmcnt(6)
	v_pk_fma_f32 v[162:163], v[146:147], v[124:125], v[162:163] op_sel_hi:[1,0,1]
	v_pk_fma_f32 v[164:165], v[148:149], v[124:125], v[164:165] op_sel_hi:[1,0,1]
	v_pk_fma_f32 v[166:167], v[150:151], v[124:125], v[166:167] op_sel_hi:[1,0,1]
	v_pk_fma_f32 v[168:169], v[152:153], v[124:125], v[168:169] op_sel_hi:[1,0,1]
	ds_read_b128 v[146:149], v192 offset:61440
	ds_read_b128 v[150:153], v192 offset:62464
	s_waitcnt lgkmcnt(6)
	v_pk_fma_f32 v[162:163], v[154:155], v[124:125], v[162:163] op_sel:[0,1,0] op_sel_hi:[1,1,1]
	v_pk_fma_f32 v[164:165], v[156:157], v[124:125], v[164:165] op_sel:[0,1,0] op_sel_hi:[1,1,1]
	v_pk_fma_f32 v[166:167], v[158:159], v[124:125], v[166:167] op_sel:[0,1,0] op_sel_hi:[1,1,1]
	v_pk_fma_f32 v[168:169], v[160:161], v[124:125], v[168:169] op_sel:[0,1,0] op_sel_hi:[1,1,1]
	ds_read_b128 v[154:157], v192 offset:63488
	ds_read_b128 v[158:161], v192 offset:64512
	s_waitcnt lgkmcnt(6)
	v_pk_fma_f32 v[162:163], v[130:131], v[126:127], v[162:163] op_sel_hi:[1,0,1]
	v_pk_fma_f32 v[164:165], v[132:133], v[126:127], v[164:165] op_sel_hi:[1,0,1]
	v_pk_fma_f32 v[166:167], v[134:135], v[126:127], v[166:167] op_sel_hi:[1,0,1]
	v_pk_fma_f32 v[168:169], v[136:137], v[126:127], v[168:169] op_sel_hi:[1,0,1]
	s_waitcnt lgkmcnt(4)
	v_pk_fma_f32 v[162:163], v[138:139], v[126:127], v[162:163] op_sel:[0,1,0] op_sel_hi:[1,1,1]
	v_pk_fma_f32 v[164:165], v[140:141], v[126:127], v[164:165] op_sel:[0,1,0] op_sel_hi:[1,1,1]
	v_pk_fma_f32 v[166:167], v[142:143], v[126:127], v[166:167] op_sel:[0,1,0] op_sel_hi:[1,1,1]
	v_pk_fma_f32 v[168:169], v[144:145], v[126:127], v[168:169] op_sel:[0,1,0] op_sel_hi:[1,1,1]
	s_waitcnt lgkmcnt(2)
	v_pk_fma_f32 v[162:163], v[146:147], v[128:129], v[162:163] op_sel_hi:[1,0,1]
	v_pk_fma_f32 v[164:165], v[148:149], v[128:129], v[164:165] op_sel_hi:[1,0,1]
	v_pk_fma_f32 v[166:167], v[150:151], v[128:129], v[166:167] op_sel_hi:[1,0,1]
	v_pk_fma_f32 v[168:169], v[152:153], v[128:129], v[168:169] op_sel_hi:[1,0,1]
	s_waitcnt lgkmcnt(0)
	v_pk_fma_f32 v[162:163], v[154:155], v[128:129], v[162:163] op_sel:[0,1,0] op_sel_hi:[1,1,1]
	v_pk_fma_f32 v[164:165], v[156:157], v[128:129], v[164:165] op_sel:[0,1,0] op_sel_hi:[1,1,1]
	v_pk_fma_f32 v[166:167], v[158:159], v[128:129], v[166:167] op_sel:[0,1,0] op_sel_hi:[1,1,1]
	v_pk_fma_f32 v[168:169], v[160:161], v[128:129], v[168:169] op_sel:[0,1,0] op_sel_hi:[1,1,1]
	s_nop 1
	v_add_f32_dpp v162, v162, v162 quad_perm:[1,0,3,2] row_mask:0xf bank_mask:0xf
	v_add_f32_dpp v163, v163, v163 quad_perm:[1,0,3,2] row_mask:0xf bank_mask:0xf
	v_add_f32_dpp v164, v164, v164 quad_perm:[1,0,3,2] row_mask:0xf bank_mask:0xf
	v_add_f32_dpp v165, v165, v165 quad_perm:[1,0,3,2] row_mask:0xf bank_mask:0xf
	v_add_f32_dpp v166, v166, v166 quad_perm:[1,0,3,2] row_mask:0xf bank_mask:0xf
	v_add_f32_dpp v167, v167, v167 quad_perm:[1,0,3,2] row_mask:0xf bank_mask:0xf
	v_add_f32_dpp v168, v168, v168 quad_perm:[1,0,3,2] row_mask:0xf bank_mask:0xf
	v_add_f32_dpp v169, v169, v169 quad_perm:[1,0,3,2] row_mask:0xf bank_mask:0xf
	v_add_f32_dpp v162, v162, v162 quad_perm:[2,3,0,1] row_mask:0xf bank_mask:0xf
	v_add_f32_dpp v163, v163, v163 quad_perm:[2,3,0,1] row_mask:0xf bank_mask:0xf
	v_add_f32_dpp v164, v164, v164 quad_perm:[2,3,0,1] row_mask:0xf bank_mask:0xf
	v_add_f32_dpp v165, v165, v165 quad_perm:[2,3,0,1] row_mask:0xf bank_mask:0xf
	v_add_f32_dpp v166, v166, v166 quad_perm:[2,3,0,1] row_mask:0xf bank_mask:0xf
	v_add_f32_dpp v167, v167, v167 quad_perm:[2,3,0,1] row_mask:0xf bank_mask:0xf
	v_add_f32_dpp v168, v168, v168 quad_perm:[2,3,0,1] row_mask:0xf bank_mask:0xf
	v_add_f32_dpp v169, v169, v169 quad_perm:[2,3,0,1] row_mask:0xf bank_mask:0xf
	v_add_f32_dpp v162, v162, v162 row_half_mirror row_mask:0xf bank_mask:0xf
	v_add_f32_dpp v163, v163, v163 row_half_mirror row_mask:0xf bank_mask:0xf
	v_add_f32_dpp v164, v164, v164 row_half_mirror row_mask:0xf bank_mask:0xf
	v_add_f32_dpp v165, v165, v165 row_half_mirror row_mask:0xf bank_mask:0xf
	v_add_f32_dpp v166, v166, v166 row_half_mirror row_mask:0xf bank_mask:0xf
	v_add_f32_dpp v167, v167, v167 row_half_mirror row_mask:0xf bank_mask:0xf
	v_add_f32_dpp v168, v168, v168 row_half_mirror row_mask:0xf bank_mask:0xf
	v_add_f32_dpp v169, v169, v169 row_half_mirror row_mask:0xf bank_mask:0xf
	v_add_f32_dpp v162, v162, v162 row_mirror row_mask:0xf bank_mask:0xf
	v_add_f32_dpp v163, v163, v163 row_mirror row_mask:0xf bank_mask:0xf
	v_add_f32_dpp v164, v164, v164 row_mirror row_mask:0xf bank_mask:0xf
	v_add_f32_dpp v165, v165, v165 row_mirror row_mask:0xf bank_mask:0xf
	v_add_f32_dpp v166, v166, v166 row_mirror row_mask:0xf bank_mask:0xf
	v_add_f32_dpp v167, v167, v167 row_mirror row_mask:0xf bank_mask:0xf
	v_add_f32_dpp v168, v168, v168 row_mirror row_mask:0xf bank_mask:0xf
	v_add_f32_dpp v169, v169, v169 row_mirror row_mask:0xf bank_mask:0xf
	v_mov_b32_e32 v170, v162
	v_mov_b32_e32 v171, v163
	v_mov_b32_e32 v172, v164
	v_mov_b32_e32 v173, v165
	v_mov_b32_e32 v174, v166
	v_mov_b32_e32 v175, v167
	v_mov_b32_e32 v176, v168
	v_mov_b32_e32 v177, v169
	v_permlane16_swap_b32 v170, v162
	v_permlane16_swap_b32 v171, v163
	v_permlane16_swap_b32 v172, v164
	v_permlane16_swap_b32 v173, v165
	v_permlane16_swap_b32 v174, v166
	v_permlane16_swap_b32 v175, v167
	v_permlane16_swap_b32 v176, v168
	v_permlane16_swap_b32 v177, v169
	v_add_f32_e32 v162, v162, v170
	v_add_f32_e32 v163, v163, v171
	v_add_f32_e32 v164, v164, v172
	v_add_f32_e32 v165, v165, v173
	v_add_f32_e32 v166, v166, v174
	v_add_f32_e32 v167, v167, v175
	v_add_f32_e32 v168, v168, v176
	v_add_f32_e32 v169, v169, v177
	v_mov_b32_e32 v170, v162
	v_mov_b32_e32 v171, v163
	v_mov_b32_e32 v172, v164
	v_mov_b32_e32 v173, v165
	v_mov_b32_e32 v174, v166
	v_mov_b32_e32 v175, v167
	v_mov_b32_e32 v176, v168
	v_mov_b32_e32 v177, v169
	v_permlane32_swap_b32 v170, v162
	v_permlane32_swap_b32 v171, v163
	v_permlane32_swap_b32 v172, v164
	v_permlane32_swap_b32 v173, v165
	v_permlane32_swap_b32 v174, v166
	v_permlane32_swap_b32 v175, v167
	v_permlane32_swap_b32 v176, v168
	v_permlane32_swap_b32 v177, v169
	v_add_f32_e32 v162, v162, v170
	v_add_f32_e32 v163, v163, v171
	v_add_f32_e32 v164, v164, v172
	v_add_f32_e32 v165, v165, v173
	v_add_f32_e32 v166, v166, v174
	v_add_f32_e32 v167, v167, v175
	v_add_f32_e32 v168, v168, v176
	v_add_f32_e32 v169, v169, v177
	s_mov_b64 exec, 1
	v_mov_b32_e32 v222, v162
	s_mov_b64 exec, 2
	v_mov_b32_e32 v222, v163
	s_mov_b64 exec, 4
	v_mov_b32_e32 v222, v164
	s_mov_b64 exec, 8
	v_mov_b32_e32 v222, v165
	s_mov_b64 exec, 16
	v_mov_b32_e32 v222, v166
	s_mov_b64 exec, 32
	v_mov_b32_e32 v222, v167
	s_mov_b64 exec, 64
	v_mov_b32_e32 v222, v168
	s_mov_b64 exec, 0x80
	v_mov_b32_e32 v222, v169
	s_mov_b64 exec, 0xff
	v_add_f32_e32 v223, v222, v196
	v_mul_f32_e64 v225, |v223|, s24
	v_exp_f32_e32 v210, v225
	v_min_f32_e32 v225, 0, v223
	s_nop 0
	v_add_f32_e32 v211, 1.0, v210
	v_add_f32_e32 v212, -1.0, v211
	v_frexp_mant_f32_e32 v213, v211
	v_cvt_f64_f32_e32 v[208:209], v211
	v_sub_f32_e32 v214, v212, v211
	v_frexp_exp_i32_f64_e32 v208, v[208:209]
	v_cmp_gt_f32_e32 vcc, s25, v213
	v_sub_f32_e32 v212, v210, v212
	v_add_f32_e32 v209, 1.0, v214
	v_subbrev_co_u32_e32 v208, vcc, 0, v208, vcc
	v_add_f32_e32 v209, v212, v209
	v_sub_u32_e32 v212, 0, v208
	v_cvt_f32_i32_e32 v208, v208
	v_ldexp_f32 v211, v211, v212
	v_ldexp_f32 v209, v209, v212
	v_add_f32_e32 v212, -1.0, v211
	v_add_f32_e32 v213, 1.0, v211
	v_add_f32_e32 v214, 1.0, v212
	v_add_f32_e32 v215, -1.0, v213
	v_sub_f32_e32 v214, v211, v214
	v_sub_f32_e32 v211, v211, v215
	v_mul_f32_e32 v215, 0x3f317218, v208
	v_add_f32_e32 v214, v209, v214
	v_add_f32_e32 v209, v209, v211
	v_fma_f32 v211, v208, s28, -v215
	v_add_f32_e32 v216, v212, v214
	v_add_f32_e32 v217, v213, v209
	v_fmac_f32_e32 v211, 0xb102e308, v208
	v_sub_f32_e32 v208, v216, v212
	v_sub_f32_e32 v212, v217, v213
	v_rcp_f32_e32 v213, v217
	v_add_f32_e32 v218, v215, v211
	v_sub_f32_e32 v209, v209, v212
	v_sub_f32_e32 v212, v218, v215
	v_sub_f32_e32 v211, v211, v212
	v_mul_f32_e32 v212, v216, v213
	v_sub_f32_e32 v208, v214, v208
	v_mul_f32_e32 v214, v217, v212
	v_fma_f32 v215, v212, v217, -v214
	v_fmac_f32_e32 v215, v212, v209
	v_add_f32_e32 v219, v214, v215
	v_sub_f32_e32 v220, v216, v219
	v_sub_f32_e32 v214, v219, v214
	v_sub_f32_e32 v216, v216, v220
	v_sub_f32_e32 v214, v214, v215
	v_sub_f32_e32 v215, v216, v219
	v_add_f32_e32 v208, v208, v215
	v_add_f32_e32 v208, v214, v208
	v_add_f32_e32 v214, v220, v208
	v_mul_f32_e32 v215, v213, v214
	v_sub_f32_e32 v216, v220, v214
	v_mul_f32_e32 v219, v217, v215
	v_add_f32_e32 v208, v208, v216
	v_add_f32_e32 v216, v212, v215
	v_fma_f32 v217, v215, v217, -v219
	v_sub_f32_e32 v212, v216, v212
	v_fmac_f32_e32 v217, v215, v209
	v_sub_f32_e32 v209, v215, v212
	v_add_f32_e32 v212, v219, v217
	v_sub_f32_e32 v215, v212, v219
	v_sub_f32_e32 v219, v214, v212
	v_sub_f32_e32 v214, v214, v219
	v_sub_f32_e32 v212, v214, v212
	v_sub_f32_e32 v215, v215, v217
	v_add_f32_e32 v208, v208, v212
	v_add_f32_e32 v208, v215, v208
	v_add_f32_e32 v208, v219, v208
	v_mul_f32_e32 v208, v213, v208
	v_add_f32_e32 v208, v209, v208
	v_add_f32_e32 v209, v216, v208
	v_mul_f32_e32 v212, v209, v209
	v_fmamk_f32 v215, v212, 0x3e9b6dac, v242
	v_sub_f32_e32 v213, v209, v216
	v_ldexp_f32 v214, v209, 1
	v_mul_f32_e32 v209, v209, v212
	v_fmaak_f32 v212, v212, v215, 0x3f2aaada
	v_mul_f32_e32 v209, v209, v212
	v_add_f32_e32 v212, v214, v209
	v_sub_f32_e32 v208, v208, v213
	v_sub_f32_e32 v213, v212, v214
	v_ldexp_f32 v208, v208, 1
	v_sub_f32_e32 v209, v209, v213
	v_add_f32_e32 v208, v208, v209
	v_add_f32_e32 v209, v212, v208
	v_sub_f32_e32 v212, v209, v212
	v_add_f32_e32 v213, v218, v209
	v_sub_f32_e32 v208, v208, v212
	v_sub_f32_e32 v212, v213, v218
	v_sub_f32_e32 v214, v213, v212
	v_sub_f32_e32 v209, v209, v212
	v_add_f32_e32 v212, v211, v208
	v_sub_f32_e32 v214, v218, v214
	v_sub_f32_e32 v215, v212, v211
	v_add_f32_e32 v209, v209, v214
	v_sub_f32_e32 v214, v212, v215
	v_sub_f32_e32 v208, v208, v215
	v_sub_f32_e32 v211, v211, v214
	v_add_f32_e32 v209, v212, v209
	v_add_f32_e32 v208, v208, v211
	v_add_f32_e32 v211, v213, v209
	v_sub_f32_e32 v212, v211, v213
	v_sub_f32_e32 v209, v209, v212
	v_add_f32_e32 v208, v208, v209
	v_add_f32_e32 v208, v211, v208
	v_cmp_neq_f32_e32 vcc, s29, v210
	s_nop 0
	s_nop 0
	v_cndmask_b32_e32 v208, v243, v208, vcc
	v_cmp_ngt_f32_e32 vcc, -1.0, v210
	s_nop 1
	v_cndmask_b32_e32 v208, v244, v208, vcc
	v_cmp_neq_f32_e32 vcc, -1.0, v210
	s_nop 1
	v_cndmask_b32_e32 v208, v245, v208, vcc
	v_cmp_lt_f32_e64 vcc, |v210|, s30
	s_nop 1
	v_cndmask_b32_e32 v208, v208, v210, vcc
	v_sub_f32_e32 v225, v225, v208
	global_store_dword v195, v225, s[74:75]
	s_mov_b64 exec, -1
	v_add_u32_e32 v195, 0x2000, v195
	s_waitcnt vmcnt(10)
	v_pk_mul_f32 v[198:199], v[66:67], v[66:67]
	v_pk_mul_f32 v[200:201], v[68:69], v[68:69]
	v_pk_fma_f32 v[198:199], v[70:71], v[70:71], v[198:199]
	v_pk_fma_f32 v[200:201], v[72:73], v[72:73], v[200:201]
	v_pk_fma_f32 v[198:199], v[74:75], v[74:75], v[198:199]
	v_pk_fma_f32 v[200:201], v[76:77], v[76:77], v[200:201]
	v_pk_fma_f32 v[198:199], v[78:79], v[78:79], v[198:199]
	v_pk_fma_f32 v[200:201], v[80:81], v[80:81], v[200:201]
	v_pk_fma_f32 v[198:199], v[82:83], v[82:83], v[198:199]
	v_pk_fma_f32 v[200:201], v[84:85], v[84:85], v[200:201]
	v_pk_fma_f32 v[198:199], v[86:87], v[86:87], v[198:199]
	v_pk_fma_f32 v[200:201], v[88:89], v[88:89], v[200:201]
	v_pk_fma_f32 v[198:199], v[90:91], v[90:91], v[198:199]
	v_pk_fma_f32 v[200:201], v[92:93], v[92:93], v[200:201]
	v_pk_fma_f32 v[198:199], v[94:95], v[94:95], v[198:199]
	v_pk_fma_f32 v[200:201], v[96:97], v[96:97], v[200:201]
	v_pk_add_f32 v[198:199], v[198:199], v[200:201]
	v_add_f32_e32 v198, v198, v199
	s_nop 1
	v_add_f32_dpp v198, v198, v198 quad_perm:[1,0,3,2] row_mask:0xf bank_mask:0xf
	s_nop 1
	v_add_f32_dpp v198, v198, v198 quad_perm:[2,3,0,1] row_mask:0xf bank_mask:0xf
	s_nop 1
	v_add_f32_dpp v198, v198, v198 row_half_mirror row_mask:0xf bank_mask:0xf
	s_nop 1
	v_add_f32_dpp v198, v198, v198 row_mirror row_mask:0xf bank_mask:0xf
	v_mov_b32_e32 v199, v198
	s_nop 1
	v_permlane16_swap_b32 v199, v198
	v_add_f32_e32 v198, v198, v199
	v_mov_b32_e32 v199, v198
	s_nop 1
	v_permlane32_swap_b32 v199, v198
	v_add_f32_e32 v198, v198, v199
	ds_read_b128 v[130:133], v192
	ds_read_b128 v[134:137], v192 offset:1024
	ds_read_b128 v[138:141], v192 offset:2048
	ds_read_b128 v[142:145], v192 offset:3072
	ds_read_b128 v[146:149], v192 offset:4096
	ds_read_b128 v[150:153], v192 offset:5120
	ds_read_b128 v[154:157], v192 offset:6144
	ds_read_b128 v[158:161], v192 offset:7168
	v_fmamk_f32 v198, v198, 0x3a000000, v241
	v_mul_f32_e32 v199, 0x4b800000, v198
	v_cmp_gt_f32_e32 vcc, s17, v198
	s_nop 1
	v_cndmask_b32_e32 v198, v198, v199, vcc
	v_rsq_f32_e32 v198, v198
	s_nop 0
	v_mul_f32_e32 v199, 0x45800000, v198
	v_cndmask_b32_e32 v202, v198, v199, vcc
	v_pk_mul_f32 v[98:99], v[66:67], v[202:203] op_sel_hi:[1,0]
	v_pk_mul_f32 v[98:99], v[2:3], v[98:99]
	v_pk_mul_f32 v[100:101], v[68:69], v[202:203] op_sel_hi:[1,0]
	v_pk_mul_f32 v[100:101], v[4:5], v[100:101]
	v_cvt_pk_bf16_f32 v206, v98, v99
	v_cvt_pk_bf16_f32 v207, v100, v101
	global_store_dwordx2 v194, v[206:207], s[52:53]
	v_pk_mul_f32 v[102:103], v[70:71], v[202:203] op_sel_hi:[1,0]
	v_pk_mul_f32 v[102:103], v[6:7], v[102:103]
	v_pk_mul_f32 v[104:105], v[72:73], v[202:203] op_sel_hi:[1,0]
	v_pk_mul_f32 v[104:105], v[8:9], v[104:105]
	v_cvt_pk_bf16_f32 v206, v102, v103
	v_cvt_pk_bf16_f32 v207, v104, v105
	global_store_dwordx2 v194, v[206:207], s[52:53] offset:512
	v_pk_mul_f32 v[106:107], v[74:75], v[202:203] op_sel_hi:[1,0]
	v_pk_mul_f32 v[106:107], v[10:11], v[106:107]
	v_pk_mul_f32 v[108:109], v[76:77], v[202:203] op_sel_hi:[1,0]
	v_pk_mul_f32 v[108:109], v[12:13], v[108:109]
	v_cvt_pk_bf16_f32 v206, v106, v107
	v_cvt_pk_bf16_f32 v207, v108, v109
	global_store_dwordx2 v194, v[206:207], s[52:53] offset:1024
	v_pk_mul_f32 v[110:111], v[78:79], v[202:203] op_sel_hi:[1,0]
	v_pk_mul_f32 v[110:111], v[14:15], v[110:111]
	v_pk_mul_f32 v[112:113], v[80:81], v[202:203] op_sel_hi:[1,0]
	v_pk_mul_f32 v[112:113], v[16:17], v[112:113]
	v_cvt_pk_bf16_f32 v206, v110, v111
	v_cvt_pk_bf16_f32 v207, v112, v113
	global_store_dwordx2 v194, v[206:207], s[52:53] offset:1536
	v_pk_mul_f32 v[114:115], v[82:83], v[202:203] op_sel_hi:[1,0]
	v_pk_mul_f32 v[114:115], v[18:19], v[114:115]
	v_pk_mul_f32 v[116:117], v[84:85], v[202:203] op_sel_hi:[1,0]
	v_pk_mul_f32 v[116:117], v[20:21], v[116:117]
	v_cvt_pk_bf16_f32 v206, v114, v115
	v_cvt_pk_bf16_f32 v207, v116, v117
	global_store_dwordx2 v194, v[206:207], s[52:53] offset:2048
	v_pk_mul_f32 v[118:119], v[86:87], v[202:203] op_sel_hi:[1,0]
	v_pk_mul_f32 v[118:119], v[22:23], v[118:119]
	v_pk_mul_f32 v[120:121], v[88:89], v[202:203] op_sel_hi:[1,0]
	v_pk_mul_f32 v[120:121], v[24:25], v[120:121]
	v_cvt_pk_bf16_f32 v206, v118, v119
	v_cvt_pk_bf16_f32 v207, v120, v121
	global_store_dwordx2 v194, v[206:207], s[52:53] offset:2560
	v_pk_mul_f32 v[122:123], v[90:91], v[202:203] op_sel_hi:[1,0]
	v_pk_mul_f32 v[122:123], v[26:27], v[122:123]
	v_pk_mul_f32 v[124:125], v[92:93], v[202:203] op_sel_hi:[1,0]
	v_pk_mul_f32 v[124:125], v[28:29], v[124:125]
	v_cvt_pk_bf16_f32 v206, v122, v123
	v_cvt_pk_bf16_f32 v207, v124, v125
	global_store_dwordx2 v194, v[206:207], s[52:53] offset:3072
	v_pk_mul_f32 v[126:127], v[94:95], v[202:203] op_sel_hi:[1,0]
	v_pk_mul_f32 v[126:127], v[30:31], v[126:127]
	v_pk_mul_f32 v[128:129], v[96:97], v[202:203] op_sel_hi:[1,0]
	v_pk_mul_f32 v[128:129], v[32:33], v[128:129]
	v_cvt_pk_bf16_f32 v206, v126, v127
	v_cvt_pk_bf16_f32 v207, v128, v129
	global_store_dwordx2 v194, v[206:207], s[52:53] offset:3584
	v_add_u32_e32 v194, 0x800000, v194
	s_waitcnt lgkmcnt(6)
	v_pk_mul_f32 v[162:163], v[130:131], v[98:99] op_sel_hi:[1,0]
	v_pk_mul_f32 v[164:165], v[132:133], v[98:99] op_sel_hi:[1,0]
	v_pk_mul_f32 v[166:167], v[134:135], v[98:99] op_sel_hi:[1,0]
	v_pk_mul_f32 v[168:169], v[136:137], v[98:99] op_sel_hi:[1,0]
	ds_read_b128 v[130:133], v192 offset:8192
	ds_read_b128 v[134:137], v192 offset:9216
	s_waitcnt lgkmcnt(6)
	v_pk_fma_f32 v[162:163], v[138:139], v[98:99], v[162:163] op_sel:[0,1,0] op_sel_hi:[1,1,1]
	v_pk_fma_f32 v[164:165], v[140:141], v[98:99], v[164:165] op_sel:[0,1,0] op_sel_hi:[1,1,1]
	v_pk_fma_f32 v[166:167], v[142:143], v[98:99], v[166:167] op_sel:[0,1,0] op_sel_hi:[1,1,1]
	v_pk_fma_f32 v[168:169], v[144:145], v[98:99], v[168:169] op_sel:[0,1,0] op_sel_hi:[1,1,1]
	ds_read_b128 v[138:141], v192 offset:10240
	ds_read_b128 v[142:145], v192 offset:11264
	s_waitcnt lgkmcnt(6)
	v_pk_fma_f32 v[162:163], v[146:147], v[100:101], v[162:163] op_sel_hi:[1,0,1]
	v_pk_fma_f32 v[164:165], v[148:149], v[100:101], v[164:165] op_sel_hi:[1,0,1]
	v_pk_fma_f32 v[166:167], v[150:151], v[100:101], v[166:167] op_sel_hi:[1,0,1]
	v_pk_fma_f32 v[168:169], v[152:153], v[100:101], v[168:169] op_sel_hi:[1,0,1]
	ds_read_b128 v[146:149], v192 offset:12288
	ds_read_b128 v[150:153], v192 offset:13312
	s_waitcnt lgkmcnt(6)
	v_pk_fma_f32 v[162:163], v[154:155], v[100:101], v[162:163] op_sel:[0,1,0] op_sel_hi:[1,1,1]
	v_pk_fma_f32 v[164:165], v[156:157], v[100:101], v[164:165] op_sel:[0,1,0] op_sel_hi:[1,1,1]
	v_pk_fma_f32 v[166:167], v[158:159], v[100:101], v[166:167] op_sel:[0,1,0] op_sel_hi:[1,1,1]
	v_pk_fma_f32 v[168:169], v[160:161], v[100:101], v[168:169] op_sel:[0,1,0] op_sel_hi:[1,1,1]
	ds_read_b128 v[154:157], v192 offset:14336
	ds_read_b128 v[158:161], v192 offset:15360
	s_waitcnt lgkmcnt(6)
	v_pk_fma_f32 v[162:163], v[130:131], v[102:103], v[162:163] op_sel_hi:[1,0,1]
	v_pk_fma_f32 v[164:165], v[132:133], v[102:103], v[164:165] op_sel_hi:[1,0,1]
	v_pk_fma_f32 v[166:167], v[134:135], v[102:103], v[166:167] op_sel_hi:[1,0,1]
	v_pk_fma_f32 v[168:169], v[136:137], v[102:103], v[168:169] op_sel_hi:[1,0,1]
	ds_read_b128 v[130:133], v192 offset:16384
	ds_read_b128 v[134:137], v192 offset:17408
	s_waitcnt lgkmcnt(6)
	v_pk_fma_f32 v[162:163], v[138:139], v[102:103], v[162:163] op_sel:[0,1,0] op_sel_hi:[1,1,1]
	v_pk_fma_f32 v[164:165], v[140:141], v[102:103], v[164:165] op_sel:[0,1,0] op_sel_hi:[1,1,1]
	v_pk_fma_f32 v[166:167], v[142:143], v[102:103], v[166:167] op_sel:[0,1,0] op_sel_hi:[1,1,1]
	v_pk_fma_f32 v[168:169], v[144:145], v[102:103], v[168:169] op_sel:[0,1,0] op_sel_hi:[1,1,1]
	ds_read_b128 v[138:141], v192 offset:18432
	ds_read_b128 v[142:145], v192 offset:19456
	s_waitcnt lgkmcnt(6)
	v_pk_fma_f32 v[162:163], v[146:147], v[104:105], v[162:163] op_sel_hi:[1,0,1]
	v_pk_fma_f32 v[164:165], v[148:149], v[104:105], v[164:165] op_sel_hi:[1,0,1]
	v_pk_fma_f32 v[166:167], v[150:151], v[104:105], v[166:167] op_sel_hi:[1,0,1]
	v_pk_fma_f32 v[168:169], v[152:153], v[104:105], v[168:169] op_sel_hi:[1,0,1]
	ds_read_b128 v[146:149], v192 offset:20480
	ds_read_b128 v[150:153], v192 offset:21504
	s_waitcnt lgkmcnt(6)
	v_pk_fma_f32 v[162:163], v[154:155], v[104:105], v[162:163] op_sel:[0,1,0] op_sel_hi:[1,1,1]
	v_pk_fma_f32 v[164:165], v[156:157], v[104:105], v[164:165] op_sel:[0,1,0] op_sel_hi:[1,1,1]
	v_pk_fma_f32 v[166:167], v[158:159], v[104:105], v[166:167] op_sel:[0,1,0] op_sel_hi:[1,1,1]
	v_pk_fma_f32 v[168:169], v[160:161], v[104:105], v[168:169] op_sel:[0,1,0] op_sel_hi:[1,1,1]
	ds_read_b128 v[154:157], v192 offset:22528
	ds_read_b128 v[158:161], v192 offset:23552
	s_waitcnt lgkmcnt(6)
	v_pk_fma_f32 v[162:163], v[130:131], v[106:107], v[162:163] op_sel_hi:[1,0,1]
	v_pk_fma_f32 v[164:165], v[132:133], v[106:107], v[164:165] op_sel_hi:[1,0,1]
	v_pk_fma_f32 v[166:167], v[134:135], v[106:107], v[166:167] op_sel_hi:[1,0,1]
	v_pk_fma_f32 v[168:169], v[136:137], v[106:107], v[168:169] op_sel_hi:[1,0,1]
	ds_read_b128 v[130:133], v192 offset:24576
	ds_read_b128 v[134:137], v192 offset:25600
	s_waitcnt lgkmcnt(6)
	v_pk_fma_f32 v[162:163], v[138:139], v[106:107], v[162:163] op_sel:[0,1,0] op_sel_hi:[1,1,1]
	v_pk_fma_f32 v[164:165], v[140:141], v[106:107], v[164:165] op_sel:[0,1,0] op_sel_hi:[1,1,1]
	v_pk_fma_f32 v[166:167], v[142:143], v[106:107], v[166:167] op_sel:[0,1,0] op_sel_hi:[1,1,1]
	v_pk_fma_f32 v[168:169], v[144:145], v[106:107], v[168:169] op_sel:[0,1,0] op_sel_hi:[1,1,1]
	ds_read_b128 v[138:141], v192 offset:26624
	ds_read_b128 v[142:145], v192 offset:27648
	s_waitcnt lgkmcnt(6)
	v_pk_fma_f32 v[162:163], v[146:147], v[108:109], v[162:163] op_sel_hi:[1,0,1]
	v_pk_fma_f32 v[164:165], v[148:149], v[108:109], v[164:165] op_sel_hi:[1,0,1]
	v_pk_fma_f32 v[166:167], v[150:151], v[108:109], v[166:167] op_sel_hi:[1,0,1]
	v_pk_fma_f32 v[168:169], v[152:153], v[108:109], v[168:169] op_sel_hi:[1,0,1]
	ds_read_b128 v[146:149], v192 offset:28672
	ds_read_b128 v[150:153], v192 offset:29696
	s_waitcnt lgkmcnt(6)
	v_pk_fma_f32 v[162:163], v[154:155], v[108:109], v[162:163] op_sel:[0,1,0] op_sel_hi:[1,1,1]
	v_pk_fma_f32 v[164:165], v[156:157], v[108:109], v[164:165] op_sel:[0,1,0] op_sel_hi:[1,1,1]
	v_pk_fma_f32 v[166:167], v[158:159], v[108:109], v[166:167] op_sel:[0,1,0] op_sel_hi:[1,1,1]
	v_pk_fma_f32 v[168:169], v[160:161], v[108:109], v[168:169] op_sel:[0,1,0] op_sel_hi:[1,1,1]
	ds_read_b128 v[154:157], v192 offset:30720
	ds_read_b128 v[158:161], v192 offset:31744
	s_waitcnt lgkmcnt(6)
	v_pk_fma_f32 v[162:163], v[130:131], v[110:111], v[162:163] op_sel_hi:[1,0,1]
	v_pk_fma_f32 v[164:165], v[132:133], v[110:111], v[164:165] op_sel_hi:[1,0,1]
	v_pk_fma_f32 v[166:167], v[134:135], v[110:111], v[166:167] op_sel_hi:[1,0,1]
	v_pk_fma_f32 v[168:169], v[136:137], v[110:111], v[168:169] op_sel_hi:[1,0,1]
	ds_read_b128 v[130:133], v192 offset:32768
	ds_read_b128 v[134:137], v192 offset:33792
	s_waitcnt lgkmcnt(6)
	v_pk_fma_f32 v[162:163], v[138:139], v[110:111], v[162:163] op_sel:[0,1,0] op_sel_hi:[1,1,1]
	v_pk_fma_f32 v[164:165], v[140:141], v[110:111], v[164:165] op_sel:[0,1,0] op_sel_hi:[1,1,1]
	v_pk_fma_f32 v[166:167], v[142:143], v[110:111], v[166:167] op_sel:[0,1,0] op_sel_hi:[1,1,1]
	v_pk_fma_f32 v[168:169], v[144:145], v[110:111], v[168:169] op_sel:[0,1,0] op_sel_hi:[1,1,1]
	ds_read_b128 v[138:141], v192 offset:34816
	ds_read_b128 v[142:145], v192 offset:35840
	s_waitcnt lgkmcnt(6)
	v_pk_fma_f32 v[162:163], v[146:147], v[112:113], v[162:163] op_sel_hi:[1,0,1]
	v_pk_fma_f32 v[164:165], v[148:149], v[112:113], v[164:165] op_sel_hi:[1,0,1]
	v_pk_fma_f32 v[166:167], v[150:151], v[112:113], v[166:167] op_sel_hi:[1,0,1]
	v_pk_fma_f32 v[168:169], v[152:153], v[112:113], v[168:169] op_sel_hi:[1,0,1]
	ds_read_b128 v[146:149], v192 offset:36864
	ds_read_b128 v[150:153], v192 offset:37888
	s_waitcnt lgkmcnt(6)
	v_pk_fma_f32 v[162:163], v[154:155], v[112:113], v[162:163] op_sel:[0,1,0] op_sel_hi:[1,1,1]
	v_pk_fma_f32 v[164:165], v[156:157], v[112:113], v[164:165] op_sel:[0,1,0] op_sel_hi:[1,1,1]
	v_pk_fma_f32 v[166:167], v[158:159], v[112:113], v[166:167] op_sel:[0,1,0] op_sel_hi:[1,1,1]
	v_pk_fma_f32 v[168:169], v[160:161], v[112:113], v[168:169] op_sel:[0,1,0] op_sel_hi:[1,1,1]
	ds_read_b128 v[154:157], v192 offset:38912
	ds_read_b128 v[158:161], v192 offset:39936
	s_waitcnt lgkmcnt(6)
	v_pk_fma_f32 v[162:163], v[130:131], v[114:115], v[162:163] op_sel_hi:[1,0,1]
	v_pk_fma_f32 v[164:165], v[132:133], v[114:115], v[164:165] op_sel_hi:[1,0,1]
	v_pk_fma_f32 v[166:167], v[134:135], v[114:115], v[166:167] op_sel_hi:[1,0,1]
	v_pk_fma_f32 v[168:169], v[136:137], v[114:115], v[168:169] op_sel_hi:[1,0,1]
	ds_read_b128 v[130:133], v192 offset:40960
	ds_read_b128 v[134:137], v192 offset:41984
	s_waitcnt lgkmcnt(6)
	v_pk_fma_f32 v[162:163], v[138:139], v[114:115], v[162:163] op_sel:[0,1,0] op_sel_hi:[1,1,1]
	v_pk_fma_f32 v[164:165], v[140:141], v[114:115], v[164:165] op_sel:[0,1,0] op_sel_hi:[1,1,1]
	v_pk_fma_f32 v[166:167], v[142:143], v[114:115], v[166:167] op_sel:[0,1,0] op_sel_hi:[1,1,1]
	v_pk_fma_f32 v[168:169], v[144:145], v[114:115], v[168:169] op_sel:[0,1,0] op_sel_hi:[1,1,1]
	ds_read_b128 v[138:141], v192 offset:43008
	ds_read_b128 v[142:145], v192 offset:44032
	s_waitcnt lgkmcnt(6)
	v_pk_fma_f32 v[162:163], v[146:147], v[116:117], v[162:163] op_sel_hi:[1,0,1]
	v_pk_fma_f32 v[164:165], v[148:149], v[116:117], v[164:165] op_sel_hi:[1,0,1]
	v_pk_fma_f32 v[166:167], v[150:151], v[116:117], v[166:167] op_sel_hi:[1,0,1]
	v_pk_fma_f32 v[168:169], v[152:153], v[116:117], v[168:169] op_sel_hi:[1,0,1]
	ds_read_b128 v[146:149], v192 offset:45056
	ds_read_b128 v[150:153], v192 offset:46080
	s_waitcnt lgkmcnt(6)
	v_pk_fma_f32 v[162:163], v[154:155], v[116:117], v[162:163] op_sel:[0,1,0] op_sel_hi:[1,1,1]
	v_pk_fma_f32 v[164:165], v[156:157], v[116:117], v[164:165] op_sel:[0,1,0] op_sel_hi:[1,1,1]
	v_pk_fma_f32 v[166:167], v[158:159], v[116:117], v[166:167] op_sel:[0,1,0] op_sel_hi:[1,1,1]
	v_pk_fma_f32 v[168:169], v[160:161], v[116:117], v[168:169] op_sel:[0,1,0] op_sel_hi:[1,1,1]
	ds_read_b128 v[154:157], v192 offset:47104
	ds_read_b128 v[158:161], v192 offset:48128
	s_waitcnt lgkmcnt(6)
	v_pk_fma_f32 v[162:163], v[130:131], v[118:119], v[162:163] op_sel_hi:[1,0,1]
	v_pk_fma_f32 v[164:165], v[132:133], v[118:119], v[164:165] op_sel_hi:[1,0,1]
	v_pk_fma_f32 v[166:167], v[134:135], v[118:119], v[166:167] op_sel_hi:[1,0,1]
	v_pk_fma_f32 v[168:169], v[136:137], v[118:119], v[168:169] op_sel_hi:[1,0,1]
	ds_read_b128 v[130:133], v192 offset:49152
	ds_read_b128 v[134:137], v192 offset:50176
	s_waitcnt lgkmcnt(6)
	v_pk_fma_f32 v[162:163], v[138:139], v[118:119], v[162:163] op_sel:[0,1,0] op_sel_hi:[1,1,1]
	v_pk_fma_f32 v[164:165], v[140:141], v[118:119], v[164:165] op_sel:[0,1,0] op_sel_hi:[1,1,1]
	v_pk_fma_f32 v[166:167], v[142:143], v[118:119], v[166:167] op_sel:[0,1,0] op_sel_hi:[1,1,1]
	v_pk_fma_f32 v[168:169], v[144:145], v[118:119], v[168:169] op_sel:[0,1,0] op_sel_hi:[1,1,1]
	ds_read_b128 v[138:141], v192 offset:51200
	ds_read_b128 v[142:145], v192 offset:52224
	s_waitcnt lgkmcnt(6)
	v_pk_fma_f32 v[162:163], v[146:147], v[120:121], v[162:163] op_sel_hi:[1,0,1]
	v_pk_fma_f32 v[164:165], v[148:149], v[120:121], v[164:165] op_sel_hi:[1,0,1]
	v_pk_fma_f32 v[166:167], v[150:151], v[120:121], v[166:167] op_sel_hi:[1,0,1]
	v_pk_fma_f32 v[168:169], v[152:153], v[120:121], v[168:169] op_sel_hi:[1,0,1]
	ds_read_b128 v[146:149], v192 offset:53248
	ds_read_b128 v[150:153], v192 offset:54272
	s_waitcnt lgkmcnt(6)
	v_pk_fma_f32 v[162:163], v[154:155], v[120:121], v[162:163] op_sel:[0,1,0] op_sel_hi:[1,1,1]
	v_pk_fma_f32 v[164:165], v[156:157], v[120:121], v[164:165] op_sel:[0,1,0] op_sel_hi:[1,1,1]
	v_pk_fma_f32 v[166:167], v[158:159], v[120:121], v[166:167] op_sel:[0,1,0] op_sel_hi:[1,1,1]
	v_pk_fma_f32 v[168:169], v[160:161], v[120:121], v[168:169] op_sel:[0,1,0] op_sel_hi:[1,1,1]
	ds_read_b128 v[154:157], v192 offset:55296
	ds_read_b128 v[158:161], v192 offset:56320
	s_waitcnt lgkmcnt(6)
	v_pk_fma_f32 v[162:163], v[130:131], v[122:123], v[162:163] op_sel_hi:[1,0,1]
	v_pk_fma_f32 v[164:165], v[132:133], v[122:123], v[164:165] op_sel_hi:[1,0,1]
	v_pk_fma_f32 v[166:167], v[134:135], v[122:123], v[166:167] op_sel_hi:[1,0,1]
	v_pk_fma_f32 v[168:169], v[136:137], v[122:123], v[168:169] op_sel_hi:[1,0,1]
	ds_read_b128 v[130:133], v192 offset:57344
	ds_read_b128 v[134:137], v192 offset:58368
	s_waitcnt lgkmcnt(6)
	v_pk_fma_f32 v[162:163], v[138:139], v[122:123], v[162:163] op_sel:[0,1,0] op_sel_hi:[1,1,1]
	v_pk_fma_f32 v[164:165], v[140:141], v[122:123], v[164:165] op_sel:[0,1,0] op_sel_hi:[1,1,1]
	v_pk_fma_f32 v[166:167], v[142:143], v[122:123], v[166:167] op_sel:[0,1,0] op_sel_hi:[1,1,1]
	v_pk_fma_f32 v[168:169], v[144:145], v[122:123], v[168:169] op_sel:[0,1,0] op_sel_hi:[1,1,1]
	ds_read_b128 v[138:141], v192 offset:59392
	ds_read_b128 v[142:145], v192 offset:60416
	s_waitcnt lgkmcnt(6)
	v_pk_fma_f32 v[162:163], v[146:147], v[124:125], v[162:163] op_sel_hi:[1,0,1]
	v_pk_fma_f32 v[164:165], v[148:149], v[124:125], v[164:165] op_sel_hi:[1,0,1]
	v_pk_fma_f32 v[166:167], v[150:151], v[124:125], v[166:167] op_sel_hi:[1,0,1]
	v_pk_fma_f32 v[168:169], v[152:153], v[124:125], v[168:169] op_sel_hi:[1,0,1]
	ds_read_b128 v[146:149], v192 offset:61440
	ds_read_b128 v[150:153], v192 offset:62464
	s_waitcnt lgkmcnt(6)
	v_pk_fma_f32 v[162:163], v[154:155], v[124:125], v[162:163] op_sel:[0,1,0] op_sel_hi:[1,1,1]
	v_pk_fma_f32 v[164:165], v[156:157], v[124:125], v[164:165] op_sel:[0,1,0] op_sel_hi:[1,1,1]
	v_pk_fma_f32 v[166:167], v[158:159], v[124:125], v[166:167] op_sel:[0,1,0] op_sel_hi:[1,1,1]
	v_pk_fma_f32 v[168:169], v[160:161], v[124:125], v[168:169] op_sel:[0,1,0] op_sel_hi:[1,1,1]
	ds_read_b128 v[154:157], v192 offset:63488
	ds_read_b128 v[158:161], v192 offset:64512
	s_waitcnt lgkmcnt(6)
	v_pk_fma_f32 v[162:163], v[130:131], v[126:127], v[162:163] op_sel_hi:[1,0,1]
	v_pk_fma_f32 v[164:165], v[132:133], v[126:127], v[164:165] op_sel_hi:[1,0,1]
	v_pk_fma_f32 v[166:167], v[134:135], v[126:127], v[166:167] op_sel_hi:[1,0,1]
	v_pk_fma_f32 v[168:169], v[136:137], v[126:127], v[168:169] op_sel_hi:[1,0,1]
	s_waitcnt lgkmcnt(4)
	v_pk_fma_f32 v[162:163], v[138:139], v[126:127], v[162:163] op_sel:[0,1,0] op_sel_hi:[1,1,1]
	v_pk_fma_f32 v[164:165], v[140:141], v[126:127], v[164:165] op_sel:[0,1,0] op_sel_hi:[1,1,1]
	v_pk_fma_f32 v[166:167], v[142:143], v[126:127], v[166:167] op_sel:[0,1,0] op_sel_hi:[1,1,1]
	v_pk_fma_f32 v[168:169], v[144:145], v[126:127], v[168:169] op_sel:[0,1,0] op_sel_hi:[1,1,1]
	s_waitcnt lgkmcnt(2)
	v_pk_fma_f32 v[162:163], v[146:147], v[128:129], v[162:163] op_sel_hi:[1,0,1]
	v_pk_fma_f32 v[164:165], v[148:149], v[128:129], v[164:165] op_sel_hi:[1,0,1]
	v_pk_fma_f32 v[166:167], v[150:151], v[128:129], v[166:167] op_sel_hi:[1,0,1]
	v_pk_fma_f32 v[168:169], v[152:153], v[128:129], v[168:169] op_sel_hi:[1,0,1]
	s_waitcnt lgkmcnt(0)
	v_pk_fma_f32 v[162:163], v[154:155], v[128:129], v[162:163] op_sel:[0,1,0] op_sel_hi:[1,1,1]
	v_pk_fma_f32 v[164:165], v[156:157], v[128:129], v[164:165] op_sel:[0,1,0] op_sel_hi:[1,1,1]
	v_pk_fma_f32 v[166:167], v[158:159], v[128:129], v[166:167] op_sel:[0,1,0] op_sel_hi:[1,1,1]
	v_pk_fma_f32 v[168:169], v[160:161], v[128:129], v[168:169] op_sel:[0,1,0] op_sel_hi:[1,1,1]
	s_nop 1
	v_add_f32_dpp v162, v162, v162 quad_perm:[1,0,3,2] row_mask:0xf bank_mask:0xf
	v_add_f32_dpp v163, v163, v163 quad_perm:[1,0,3,2] row_mask:0xf bank_mask:0xf
	v_add_f32_dpp v164, v164, v164 quad_perm:[1,0,3,2] row_mask:0xf bank_mask:0xf
	v_add_f32_dpp v165, v165, v165 quad_perm:[1,0,3,2] row_mask:0xf bank_mask:0xf
	v_add_f32_dpp v166, v166, v166 quad_perm:[1,0,3,2] row_mask:0xf bank_mask:0xf
	v_add_f32_dpp v167, v167, v167 quad_perm:[1,0,3,2] row_mask:0xf bank_mask:0xf
	v_add_f32_dpp v168, v168, v168 quad_perm:[1,0,3,2] row_mask:0xf bank_mask:0xf
	v_add_f32_dpp v169, v169, v169 quad_perm:[1,0,3,2] row_mask:0xf bank_mask:0xf
	v_add_f32_dpp v162, v162, v162 quad_perm:[2,3,0,1] row_mask:0xf bank_mask:0xf
	v_add_f32_dpp v163, v163, v163 quad_perm:[2,3,0,1] row_mask:0xf bank_mask:0xf
	v_add_f32_dpp v164, v164, v164 quad_perm:[2,3,0,1] row_mask:0xf bank_mask:0xf
	v_add_f32_dpp v165, v165, v165 quad_perm:[2,3,0,1] row_mask:0xf bank_mask:0xf
	v_add_f32_dpp v166, v166, v166 quad_perm:[2,3,0,1] row_mask:0xf bank_mask:0xf
	v_add_f32_dpp v167, v167, v167 quad_perm:[2,3,0,1] row_mask:0xf bank_mask:0xf
	v_add_f32_dpp v168, v168, v168 quad_perm:[2,3,0,1] row_mask:0xf bank_mask:0xf
	v_add_f32_dpp v169, v169, v169 quad_perm:[2,3,0,1] row_mask:0xf bank_mask:0xf
	v_add_f32_dpp v162, v162, v162 row_half_mirror row_mask:0xf bank_mask:0xf
	v_add_f32_dpp v163, v163, v163 row_half_mirror row_mask:0xf bank_mask:0xf
	v_add_f32_dpp v164, v164, v164 row_half_mirror row_mask:0xf bank_mask:0xf
	v_add_f32_dpp v165, v165, v165 row_half_mirror row_mask:0xf bank_mask:0xf
	v_add_f32_dpp v166, v166, v166 row_half_mirror row_mask:0xf bank_mask:0xf
	v_add_f32_dpp v167, v167, v167 row_half_mirror row_mask:0xf bank_mask:0xf
	v_add_f32_dpp v168, v168, v168 row_half_mirror row_mask:0xf bank_mask:0xf
	v_add_f32_dpp v169, v169, v169 row_half_mirror row_mask:0xf bank_mask:0xf
	v_add_f32_dpp v162, v162, v162 row_mirror row_mask:0xf bank_mask:0xf
	v_add_f32_dpp v163, v163, v163 row_mirror row_mask:0xf bank_mask:0xf
	v_add_f32_dpp v164, v164, v164 row_mirror row_mask:0xf bank_mask:0xf
	v_add_f32_dpp v165, v165, v165 row_mirror row_mask:0xf bank_mask:0xf
	v_add_f32_dpp v166, v166, v166 row_mirror row_mask:0xf bank_mask:0xf
	v_add_f32_dpp v167, v167, v167 row_mirror row_mask:0xf bank_mask:0xf
	v_add_f32_dpp v168, v168, v168 row_mirror row_mask:0xf bank_mask:0xf
	v_add_f32_dpp v169, v169, v169 row_mirror row_mask:0xf bank_mask:0xf
	v_mov_b32_e32 v170, v162
	v_mov_b32_e32 v171, v163
	v_mov_b32_e32 v172, v164
	v_mov_b32_e32 v173, v165
	v_mov_b32_e32 v174, v166
	v_mov_b32_e32 v175, v167
	v_mov_b32_e32 v176, v168
	v_mov_b32_e32 v177, v169
	v_permlane16_swap_b32 v170, v162
	v_permlane16_swap_b32 v171, v163
	v_permlane16_swap_b32 v172, v164
	v_permlane16_swap_b32 v173, v165
	v_permlane16_swap_b32 v174, v166
	v_permlane16_swap_b32 v175, v167
	v_permlane16_swap_b32 v176, v168
	v_permlane16_swap_b32 v177, v169
	v_add_f32_e32 v162, v162, v170
	v_add_f32_e32 v163, v163, v171
	v_add_f32_e32 v164, v164, v172
	v_add_f32_e32 v165, v165, v173
	v_add_f32_e32 v166, v166, v174
	v_add_f32_e32 v167, v167, v175
	v_add_f32_e32 v168, v168, v176
	v_add_f32_e32 v169, v169, v177
	v_mov_b32_e32 v170, v162
	v_mov_b32_e32 v171, v163
	v_mov_b32_e32 v172, v164
	v_mov_b32_e32 v173, v165
	v_mov_b32_e32 v174, v166
	v_mov_b32_e32 v175, v167
	v_mov_b32_e32 v176, v168
	v_mov_b32_e32 v177, v169
	v_permlane32_swap_b32 v170, v162
	v_permlane32_swap_b32 v171, v163
	v_permlane32_swap_b32 v172, v164
	v_permlane32_swap_b32 v173, v165
	v_permlane32_swap_b32 v174, v166
	v_permlane32_swap_b32 v175, v167
	v_permlane32_swap_b32 v176, v168
	v_permlane32_swap_b32 v177, v169
	v_add_f32_e32 v162, v162, v170
	v_add_f32_e32 v163, v163, v171
	v_add_f32_e32 v164, v164, v172
	v_add_f32_e32 v165, v165, v173
	v_add_f32_e32 v166, v166, v174
	v_add_f32_e32 v167, v167, v175
	v_add_f32_e32 v168, v168, v176
	v_add_f32_e32 v169, v169, v177
	s_mov_b64 exec, 1
	v_mov_b32_e32 v222, v162
	s_mov_b64 exec, 2
	v_mov_b32_e32 v222, v163
	s_mov_b64 exec, 4
	v_mov_b32_e32 v222, v164
	s_mov_b64 exec, 8
	v_mov_b32_e32 v222, v165
	s_mov_b64 exec, 16
	v_mov_b32_e32 v222, v166
	s_mov_b64 exec, 32
	v_mov_b32_e32 v222, v167
	s_mov_b64 exec, 64
	v_mov_b32_e32 v222, v168
	s_mov_b64 exec, 0x80
	v_mov_b32_e32 v222, v169
	s_mov_b64 exec, 0xff
	v_add_f32_e32 v223, v222, v196
	v_mul_f32_e64 v225, |v223|, s24
	v_exp_f32_e32 v210, v225
	v_min_f32_e32 v225, 0, v223
	s_nop 0
	v_add_f32_e32 v211, 1.0, v210
	v_add_f32_e32 v212, -1.0, v211
	v_frexp_mant_f32_e32 v213, v211
	v_cvt_f64_f32_e32 v[208:209], v211
	v_sub_f32_e32 v214, v212, v211
	v_frexp_exp_i32_f64_e32 v208, v[208:209]
	v_cmp_gt_f32_e32 vcc, s25, v213
	v_sub_f32_e32 v212, v210, v212
	v_add_f32_e32 v209, 1.0, v214
	v_subbrev_co_u32_e32 v208, vcc, 0, v208, vcc
	v_add_f32_e32 v209, v212, v209
	v_sub_u32_e32 v212, 0, v208
	v_cvt_f32_i32_e32 v208, v208
	v_ldexp_f32 v211, v211, v212
	v_ldexp_f32 v209, v209, v212
	v_add_f32_e32 v212, -1.0, v211
	v_add_f32_e32 v213, 1.0, v211
	v_add_f32_e32 v214, 1.0, v212
	v_add_f32_e32 v215, -1.0, v213
	v_sub_f32_e32 v214, v211, v214
	v_sub_f32_e32 v211, v211, v215
	v_mul_f32_e32 v215, 0x3f317218, v208
	v_add_f32_e32 v214, v209, v214
	v_add_f32_e32 v209, v209, v211
	v_fma_f32 v211, v208, s28, -v215
	v_add_f32_e32 v216, v212, v214
	v_add_f32_e32 v217, v213, v209
	v_fmac_f32_e32 v211, 0xb102e308, v208
	v_sub_f32_e32 v208, v216, v212
	v_sub_f32_e32 v212, v217, v213
	v_rcp_f32_e32 v213, v217
	v_add_f32_e32 v218, v215, v211
	v_sub_f32_e32 v209, v209, v212
	v_sub_f32_e32 v212, v218, v215
	v_sub_f32_e32 v211, v211, v212
	v_mul_f32_e32 v212, v216, v213
	v_sub_f32_e32 v208, v214, v208
	v_mul_f32_e32 v214, v217, v212
	v_fma_f32 v215, v212, v217, -v214
	v_fmac_f32_e32 v215, v212, v209
	v_add_f32_e32 v219, v214, v215
	v_sub_f32_e32 v220, v216, v219
	v_sub_f32_e32 v214, v219, v214
	v_sub_f32_e32 v216, v216, v220
	v_sub_f32_e32 v214, v214, v215
	v_sub_f32_e32 v215, v216, v219
	v_add_f32_e32 v208, v208, v215
	v_add_f32_e32 v208, v214, v208
	v_add_f32_e32 v214, v220, v208
	v_mul_f32_e32 v215, v213, v214
	v_sub_f32_e32 v216, v220, v214
	v_mul_f32_e32 v219, v217, v215
	v_add_f32_e32 v208, v208, v216
	v_add_f32_e32 v216, v212, v215
	v_fma_f32 v217, v215, v217, -v219
	v_sub_f32_e32 v212, v216, v212
	v_fmac_f32_e32 v217, v215, v209
	v_sub_f32_e32 v209, v215, v212
	v_add_f32_e32 v212, v219, v217
	v_sub_f32_e32 v215, v212, v219
	v_sub_f32_e32 v219, v214, v212
	v_sub_f32_e32 v214, v214, v219
	v_sub_f32_e32 v212, v214, v212
	v_sub_f32_e32 v215, v215, v217
	v_add_f32_e32 v208, v208, v212
	v_add_f32_e32 v208, v215, v208
	v_add_f32_e32 v208, v219, v208
	v_mul_f32_e32 v208, v213, v208
	v_add_f32_e32 v208, v209, v208
	v_add_f32_e32 v209, v216, v208
	v_mul_f32_e32 v212, v209, v209
	v_fmamk_f32 v215, v212, 0x3e9b6dac, v242
	v_sub_f32_e32 v213, v209, v216
	v_ldexp_f32 v214, v209, 1
	v_mul_f32_e32 v209, v209, v212
	v_fmaak_f32 v212, v212, v215, 0x3f2aaada
	v_mul_f32_e32 v209, v209, v212
	v_add_f32_e32 v212, v214, v209
	v_sub_f32_e32 v208, v208, v213
	v_sub_f32_e32 v213, v212, v214
	v_ldexp_f32 v208, v208, 1
	v_sub_f32_e32 v209, v209, v213
	v_add_f32_e32 v208, v208, v209
	v_add_f32_e32 v209, v212, v208
	v_sub_f32_e32 v212, v209, v212
	v_add_f32_e32 v213, v218, v209
	v_sub_f32_e32 v208, v208, v212
	v_sub_f32_e32 v212, v213, v218
	v_sub_f32_e32 v214, v213, v212
	v_sub_f32_e32 v209, v209, v212
	v_add_f32_e32 v212, v211, v208
	v_sub_f32_e32 v214, v218, v214
	v_sub_f32_e32 v215, v212, v211
	v_add_f32_e32 v209, v209, v214
	v_sub_f32_e32 v214, v212, v215
	v_sub_f32_e32 v208, v208, v215
	v_sub_f32_e32 v211, v211, v214
	v_add_f32_e32 v209, v212, v209
	v_add_f32_e32 v208, v208, v211
	v_add_f32_e32 v211, v213, v209
	v_sub_f32_e32 v212, v211, v213
	v_sub_f32_e32 v209, v209, v212
	v_add_f32_e32 v208, v208, v209
	v_add_f32_e32 v208, v211, v208
	v_cmp_neq_f32_e32 vcc, s29, v210
	s_nop 0
	s_nop 0
	v_cndmask_b32_e32 v208, v243, v208, vcc
	v_cmp_ngt_f32_e32 vcc, -1.0, v210
	s_nop 1
	v_cndmask_b32_e32 v208, v244, v208, vcc
	v_cmp_neq_f32_e32 vcc, -1.0, v210
	s_nop 1
	v_cndmask_b32_e32 v208, v245, v208, vcc
	v_cmp_lt_f32_e64 vcc, |v210|, s30
	s_nop 1
	v_cndmask_b32_e32 v208, v208, v210, vcc
	v_sub_f32_e32 v225, v225, v208
	global_store_dword v195, v225, s[74:75]
	s_mov_b64 exec, -1
